# EpiRes bf16 copy also stored as 16 B per lane (permlane16_swap pairing), on top of the EpiQKV0 wide-store epilogue
# speedup vs baseline: 1.0216x; 1.0020x over previous
.LBB0_368:
	ds_read_b128 v[144:147], v149
	ds_read_b128 v[152:155], v149 offset:1024
	ds_read_b128 v[156:159], v149 offset:2048
	ds_read_b128 v[160:163], v149 offset:3072
	s_add_u32 s70, s68, 0x100
	s_addc_u32 s71, s69, 0
	s_cmp_eq_u32 s77, 12
	s_cselect_b32 s75, s19, s71
	s_cselect_b32 s74, s55, s70
	s_cselect_b32 s73, s17, s76
	s_cselect_b32 s72, s57, s67
	v_lshl_add_u64 v[196:197], s[68:69], 0, v[134:135]
	s_add_i32 m0, s26, 0xc000
	ds_read_b128 v[164:167], v150
	ds_read_b128 v[168:171], v150 offset:1024
	ds_read_b128 v[172:175], v150 offset:2048
	ds_read_b128 v[176:179], v150 offset:3072
	ds_read_b128 v[180:183], v150 offset:4096
	ds_read_b128 v[184:187], v150 offset:5120
	ds_read_b128 v[188:191], v150 offset:6144
	ds_read_b128 v[192:195], v150 offset:7168
	global_load_lds_dwordx4 v[196:197], off
	v_lshl_add_u64 v[196:197], s[68:69], 0, v[138:139]
	s_add_i32 m0, s26, 0xe000
	s_nop 0
	global_load_lds_dwordx4 v[196:197], off
	s_waitcnt lgkmcnt(8)
	s_barrier
	s_waitcnt lgkmcnt(0)
	s_setprio 1
	s_waitcnt lgkmcnt(0)
	v_mfma_f32_16x16x32_bf16 v[124:127], v[144:147], v[164:167], v[124:127]
	v_mfma_f32_16x16x32_bf16 v[120:123], v[156:159], v[164:167], v[120:123]
	v_mfma_f32_16x16x32_bf16 v[108:111], v[144:147], v[172:175], v[108:111]
	v_mfma_f32_16x16x32_bf16 v[104:107], v[156:159], v[172:175], v[104:107]
	v_mfma_f32_16x16x32_bf16 v[92:95], v[144:147], v[180:183], v[92:95]
	v_mfma_f32_16x16x32_bf16 v[88:91], v[156:159], v[180:183], v[88:91]
	v_mfma_f32_16x16x32_bf16 v[76:79], v[144:147], v[188:191], v[76:79]
	v_mfma_f32_16x16x32_bf16 v[72:75], v[156:159], v[188:191], v[72:75]
	v_mfma_f32_16x16x32_bf16 v[124:127], v[152:155], v[168:171], v[124:127]
	v_mfma_f32_16x16x32_bf16 v[120:123], v[160:163], v[168:171], v[120:123]
	v_mfma_f32_16x16x32_bf16 v[108:111], v[152:155], v[176:179], v[108:111]
	v_mfma_f32_16x16x32_bf16 v[104:107], v[160:163], v[176:179], v[104:107]
	v_mfma_f32_16x16x32_bf16 v[92:95], v[152:155], v[184:187], v[92:95]
	v_mfma_f32_16x16x32_bf16 v[88:91], v[160:163], v[184:187], v[88:91]
	v_mfma_f32_16x16x32_bf16 v[76:79], v[152:155], v[192:195], v[76:79]
	v_mfma_f32_16x16x32_bf16 v[72:75], v[160:163], v[192:195], v[72:75]
	s_setprio 0
	s_barrier
	s_add_i32 s68, s49, s7
	v_lshl_add_u64 v[212:213], s[72:73], 0, v[128:129]
	s_mov_b32 m0, s68
	ds_read_b128 v[196:199], v151
	ds_read_b128 v[200:203], v151 offset:1024
	ds_read_b128 v[204:207], v151 offset:2048
	ds_read_b128 v[208:211], v151 offset:3072
	global_load_lds_dwordx4 v[212:213], off
	v_lshl_add_u64 v[214:215], s[72:73], 0, v[130:131]
	s_add_i32 m0, s68, 0x2000
	s_nop 0
	global_load_lds_dwordx4 v[214:215], off
	s_barrier
	s_waitcnt lgkmcnt(0)
	s_setprio 1
	s_waitcnt lgkmcnt(0)
	v_mfma_f32_16x16x32_bf16 v[116:119], v[196:199], v[164:167], v[116:119]
	v_mfma_f32_16x16x32_bf16 v[112:115], v[204:207], v[164:167], v[112:115]
	v_mfma_f32_16x16x32_bf16 v[100:103], v[196:199], v[172:175], v[100:103]
	v_mfma_f32_16x16x32_bf16 v[96:99], v[204:207], v[172:175], v[96:99]
	v_mfma_f32_16x16x32_bf16 v[84:87], v[196:199], v[180:183], v[84:87]
	v_mfma_f32_16x16x32_bf16 v[80:83], v[204:207], v[180:183], v[80:83]
	v_mfma_f32_16x16x32_bf16 v[68:71], v[196:199], v[188:191], v[68:71]
	v_mfma_f32_16x16x32_bf16 v[64:67], v[204:207], v[188:191], v[64:67]
	v_mfma_f32_16x16x32_bf16 v[116:119], v[200:203], v[168:171], v[116:119]
	v_mfma_f32_16x16x32_bf16 v[112:115], v[208:211], v[168:171], v[112:115]
	v_mfma_f32_16x16x32_bf16 v[100:103], v[200:203], v[176:179], v[100:103]
	v_mfma_f32_16x16x32_bf16 v[96:99], v[208:211], v[176:179], v[96:99]
	v_mfma_f32_16x16x32_bf16 v[84:87], v[200:203], v[184:187], v[84:87]
	v_mfma_f32_16x16x32_bf16 v[80:83], v[208:211], v[184:187], v[80:83]
	v_mfma_f32_16x16x32_bf16 v[68:71], v[200:203], v[192:195], v[68:71]
	v_mfma_f32_16x16x32_bf16 v[64:67], v[208:211], v[192:195], v[64:67]
	s_setprio 0
	s_mov_b32 m0, s26
	v_lshl_add_u64 v[216:217], s[74:75], 0, v[128:129]
	s_barrier
	ds_read_b128 v[164:167], v150 offset:16384
	ds_read_b128 v[168:171], v150 offset:17408
	ds_read_b128 v[172:175], v150 offset:18432
	ds_read_b128 v[176:179], v150 offset:19456
	ds_read_b128 v[180:183], v150 offset:20480
	ds_read_b128 v[184:187], v150 offset:21504
	ds_read_b128 v[188:191], v150 offset:22528
	ds_read_b128 v[192:195], v150 offset:23552
	global_load_lds_dwordx4 v[216:217], off
	v_lshl_add_u64 v[218:219], s[74:75], 0, v[130:131]
	s_mov_b32 m0, s27
	s_nop 0
	global_load_lds_dwordx4 v[218:219], off
	s_barrier
	s_waitcnt lgkmcnt(0)
	s_setprio 1
	s_waitcnt lgkmcnt(0)
	v_mfma_f32_16x16x32_bf16 v[60:63], v[144:147], v[164:167], v[60:63]
	v_mfma_f32_16x16x32_bf16 v[56:59], v[156:159], v[164:167], v[56:59]
	v_mfma_f32_16x16x32_bf16 v[44:47], v[144:147], v[172:175], v[44:47]
	v_mfma_f32_16x16x32_bf16 v[40:43], v[156:159], v[172:175], v[40:43]
	v_mfma_f32_16x16x32_bf16 v[28:31], v[144:147], v[180:183], v[28:31]
	v_mfma_f32_16x16x32_bf16 v[24:27], v[156:159], v[180:183], v[24:27]
	v_mfma_f32_16x16x32_bf16 v[12:15], v[144:147], v[188:191], v[12:15]
	v_mfma_f32_16x16x32_bf16 v[8:11], v[156:159], v[188:191], v[8:11]
	v_mfma_f32_16x16x32_bf16 v[60:63], v[152:155], v[168:171], v[60:63]
	v_mfma_f32_16x16x32_bf16 v[56:59], v[160:163], v[168:171], v[56:59]
	v_mfma_f32_16x16x32_bf16 v[44:47], v[152:155], v[176:179], v[44:47]
	v_mfma_f32_16x16x32_bf16 v[40:43], v[160:163], v[176:179], v[40:43]
	v_mfma_f32_16x16x32_bf16 v[28:31], v[152:155], v[184:187], v[28:31]
	v_mfma_f32_16x16x32_bf16 v[24:27], v[160:163], v[184:187], v[24:27]
	v_mfma_f32_16x16x32_bf16 v[12:15], v[152:155], v[192:195], v[12:15]
	v_mfma_f32_16x16x32_bf16 v[8:11], v[160:163], v[192:195], v[8:11]
	s_setprio 0
	s_barrier
	s_add_u32 s68, s72, 0x40000
	s_addc_u32 s69, s73, 0
	s_add_i32 s78, s56, s7
	v_lshl_add_u64 v[144:145], s[68:69], 0, v[128:129]
	s_mov_b32 m0, s78
	s_nop 0
	global_load_lds_dwordx4 v[144:145], off
	v_lshl_add_u64 v[144:145], s[68:69], 0, v[130:131]
	s_add_i32 m0, s78, 0x2000
	s_nop 0
	global_load_lds_dwordx4 v[144:145], off
	s_waitcnt vmcnt(6)
	s_barrier
	s_setprio 1
	v_mfma_f32_16x16x32_bf16 v[52:55], v[196:199], v[164:167], v[52:55]
	v_mfma_f32_16x16x32_bf16 v[48:51], v[204:207], v[164:167], v[48:51]
	v_mfma_f32_16x16x32_bf16 v[36:39], v[196:199], v[172:175], v[36:39]
	v_mfma_f32_16x16x32_bf16 v[32:35], v[204:207], v[172:175], v[32:35]
	v_mfma_f32_16x16x32_bf16 v[20:23], v[196:199], v[180:183], v[20:23]
	v_mfma_f32_16x16x32_bf16 v[16:19], v[204:207], v[180:183], v[16:19]
	v_mfma_f32_16x16x32_bf16 v[4:7], v[196:199], v[188:191], v[4:7]
	v_mfma_f32_16x16x32_bf16 v[0:3], v[204:207], v[188:191], v[0:3]
	v_mfma_f32_16x16x32_bf16 v[52:55], v[200:203], v[168:171], v[52:55]
	v_mfma_f32_16x16x32_bf16 v[48:51], v[208:211], v[168:171], v[48:51]
	v_mfma_f32_16x16x32_bf16 v[36:39], v[200:203], v[176:179], v[36:39]
	v_mfma_f32_16x16x32_bf16 v[32:35], v[208:211], v[176:179], v[32:35]
	v_mfma_f32_16x16x32_bf16 v[20:23], v[200:203], v[184:187], v[20:23]
	v_mfma_f32_16x16x32_bf16 v[16:19], v[208:211], v[184:187], v[16:19]
	v_mfma_f32_16x16x32_bf16 v[4:7], v[200:203], v[192:195], v[4:7]
	v_mfma_f32_16x16x32_bf16 v[0:3], v[208:211], v[192:195], v[0:3]
	s_setprio 0
	s_add_i32 s78, 16, 0x18000
	v_add_u32_e32 v160, s78, v148
	s_barrier
	ds_read_b128 v[144:147], v160
	ds_read_b128 v[152:155], v160 offset:1024
	ds_read_b128 v[156:159], v160 offset:2048
	ds_read_b128 v[160:163], v160 offset:3072
	s_add_u32 s68, s74, 0x40000
	s_addc_u32 s69, s75, 0
	s_mov_b32 m0, s39
	v_lshl_add_u64 v[196:197], s[68:69], 0, v[128:129]
	ds_read_b128 v[164:167], v150 offset:32768
	ds_read_b128 v[168:171], v150 offset:33792
	ds_read_b128 v[172:175], v150 offset:34816
	ds_read_b128 v[176:179], v150 offset:35840
	ds_read_b128 v[180:183], v150 offset:36864
	ds_read_b128 v[184:187], v150 offset:37888
	ds_read_b128 v[188:191], v150 offset:38912
	ds_read_b128 v[192:195], v150 offset:39936
	global_load_lds_dwordx4 v[196:197], off
	v_lshl_add_u64 v[196:197], s[68:69], 0, v[130:131]
	s_mov_b32 m0, s44
	s_nop 0
	global_load_lds_dwordx4 v[196:197], off
	s_waitcnt lgkmcnt(8)
	s_barrier
	s_waitcnt lgkmcnt(0)
	s_setprio 1
	s_waitcnt lgkmcnt(0)
	v_mfma_f32_16x16x32_bf16 v[124:127], v[144:147], v[164:167], v[124:127]
	v_mfma_f32_16x16x32_bf16 v[120:123], v[156:159], v[164:167], v[120:123]
	v_mfma_f32_16x16x32_bf16 v[108:111], v[144:147], v[172:175], v[108:111]
	v_mfma_f32_16x16x32_bf16 v[104:107], v[156:159], v[172:175], v[104:107]
	v_mfma_f32_16x16x32_bf16 v[92:95], v[144:147], v[180:183], v[92:95]
	v_mfma_f32_16x16x32_bf16 v[88:91], v[156:159], v[180:183], v[88:91]
	v_mfma_f32_16x16x32_bf16 v[76:79], v[144:147], v[188:191], v[76:79]
	v_mfma_f32_16x16x32_bf16 v[72:75], v[156:159], v[188:191], v[72:75]
	v_mfma_f32_16x16x32_bf16 v[124:127], v[152:155], v[168:171], v[124:127]
	v_mfma_f32_16x16x32_bf16 v[120:123], v[160:163], v[168:171], v[120:123]
	v_mfma_f32_16x16x32_bf16 v[108:111], v[152:155], v[176:179], v[108:111]
	v_mfma_f32_16x16x32_bf16 v[104:107], v[160:163], v[176:179], v[104:107]
	v_mfma_f32_16x16x32_bf16 v[92:95], v[152:155], v[184:187], v[92:95]
	v_mfma_f32_16x16x32_bf16 v[88:91], v[160:163], v[184:187], v[88:91]
	v_mfma_f32_16x16x32_bf16 v[76:79], v[152:155], v[192:195], v[76:79]
	v_mfma_f32_16x16x32_bf16 v[72:75], v[160:163], v[192:195], v[72:75]
	s_setprio 0
	s_barrier
	s_add_i32 s74, 16, 0x1c000
	s_add_i32 s68, s78, s7
	v_add_u32_e32 v208, s74, v148
	v_lshl_add_u64 v[212:213], v[212:213], 0, s[14:15]
	s_mov_b32 m0, s68
	ds_read_b128 v[196:199], v208
	ds_read_b128 v[200:203], v208 offset:1024
	ds_read_b128 v[204:207], v208 offset:2048
	ds_read_b128 v[208:211], v208 offset:3072
	global_load_lds_dwordx4 v[212:213], off
	v_lshl_add_u64 v[212:213], v[214:215], 0, s[14:15]
	s_add_i32 m0, s68, 0x2000
	s_nop 0
	global_load_lds_dwordx4 v[212:213], off
	s_barrier
	s_waitcnt lgkmcnt(0)
	s_setprio 1
	s_waitcnt lgkmcnt(0)
	v_mfma_f32_16x16x32_bf16 v[116:119], v[196:199], v[164:167], v[116:119]
	v_mfma_f32_16x16x32_bf16 v[112:115], v[204:207], v[164:167], v[112:115]
	v_mfma_f32_16x16x32_bf16 v[100:103], v[196:199], v[172:175], v[100:103]
	v_mfma_f32_16x16x32_bf16 v[96:99], v[204:207], v[172:175], v[96:99]
	v_mfma_f32_16x16x32_bf16 v[84:87], v[196:199], v[180:183], v[84:87]
	v_mfma_f32_16x16x32_bf16 v[80:83], v[204:207], v[180:183], v[80:83]
	v_mfma_f32_16x16x32_bf16 v[68:71], v[196:199], v[188:191], v[68:71]
	v_mfma_f32_16x16x32_bf16 v[64:67], v[204:207], v[188:191], v[64:67]
	v_mfma_f32_16x16x32_bf16 v[116:119], v[200:203], v[168:171], v[116:119]
	v_mfma_f32_16x16x32_bf16 v[112:115], v[208:211], v[168:171], v[112:115]
	v_mfma_f32_16x16x32_bf16 v[100:103], v[200:203], v[176:179], v[100:103]
	v_mfma_f32_16x16x32_bf16 v[96:99], v[208:211], v[176:179], v[96:99]
	v_mfma_f32_16x16x32_bf16 v[84:87], v[200:203], v[184:187], v[84:87]
	v_mfma_f32_16x16x32_bf16 v[80:83], v[208:211], v[184:187], v[80:83]
	v_mfma_f32_16x16x32_bf16 v[68:71], v[200:203], v[192:195], v[68:71]
	v_mfma_f32_16x16x32_bf16 v[64:67], v[208:211], v[192:195], v[64:67]
	s_setprio 0
	s_mov_b32 m0, s45
	v_lshl_add_u64 v[212:213], v[216:217], 0, s[14:15]
	s_barrier
	ds_read_b128 v[164:167], v150 offset:49152
	ds_read_b128 v[168:171], v150 offset:50176
	ds_read_b128 v[172:175], v150 offset:51200
	ds_read_b128 v[176:179], v150 offset:52224
	ds_read_b128 v[180:183], v150 offset:53248
	ds_read_b128 v[184:187], v150 offset:54272
	ds_read_b128 v[188:191], v150 offset:55296
	ds_read_b128 v[192:195], v150 offset:56320
	global_load_lds_dwordx4 v[212:213], off
	v_lshl_add_u64 v[212:213], v[218:219], 0, s[14:15]
	s_mov_b32 m0, s46
	s_nop 0
	global_load_lds_dwordx4 v[212:213], off
	s_barrier
	s_waitcnt lgkmcnt(0)
	s_setprio 1
	s_waitcnt lgkmcnt(0)
	v_mfma_f32_16x16x32_bf16 v[60:63], v[144:147], v[164:167], v[60:63]
	v_mfma_f32_16x16x32_bf16 v[56:59], v[156:159], v[164:167], v[56:59]
	v_mfma_f32_16x16x32_bf16 v[44:47], v[144:147], v[172:175], v[44:47]
	v_mfma_f32_16x16x32_bf16 v[40:43], v[156:159], v[172:175], v[40:43]
	v_mfma_f32_16x16x32_bf16 v[28:31], v[144:147], v[180:183], v[28:31]
	v_mfma_f32_16x16x32_bf16 v[24:27], v[156:159], v[180:183], v[24:27]
	v_mfma_f32_16x16x32_bf16 v[12:15], v[144:147], v[188:191], v[12:15]
	v_mfma_f32_16x16x32_bf16 v[8:11], v[156:159], v[188:191], v[8:11]
	v_mfma_f32_16x16x32_bf16 v[60:63], v[152:155], v[168:171], v[60:63]
	v_mfma_f32_16x16x32_bf16 v[56:59], v[160:163], v[168:171], v[56:59]
	v_mfma_f32_16x16x32_bf16 v[44:47], v[152:155], v[176:179], v[44:47]
	v_mfma_f32_16x16x32_bf16 v[40:43], v[160:163], v[176:179], v[40:43]
	v_mfma_f32_16x16x32_bf16 v[28:31], v[152:155], v[184:187], v[28:31]
	v_mfma_f32_16x16x32_bf16 v[24:27], v[160:163], v[184:187], v[24:27]
	v_mfma_f32_16x16x32_bf16 v[12:15], v[152:155], v[192:195], v[12:15]
	v_mfma_f32_16x16x32_bf16 v[8:11], v[160:163], v[192:195], v[8:11]
	s_setprio 0
	s_barrier
	s_add_u32 s68, s72, 0x40080
	s_addc_u32 s69, s73, 0
	s_add_i32 s72, s74, s7
	v_lshl_add_u64 v[144:145], s[68:69], 0, v[128:129]
	s_mov_b32 m0, s72
	s_nop 0
	global_load_lds_dwordx4 v[144:145], off
	v_lshl_add_u64 v[144:145], s[68:69], 0, v[130:131]
	s_add_i32 m0, s72, 0x2000
	s_nop 0
	global_load_lds_dwordx4 v[144:145], off
	s_waitcnt vmcnt(6)
	s_barrier
	s_setprio 1
	v_mfma_f32_16x16x32_bf16 v[52:55], v[196:199], v[164:167], v[52:55]
	v_mfma_f32_16x16x32_bf16 v[48:51], v[204:207], v[164:167], v[48:51]
	v_mfma_f32_16x16x32_bf16 v[36:39], v[196:199], v[172:175], v[36:39]
	v_mfma_f32_16x16x32_bf16 v[32:35], v[204:207], v[172:175], v[32:35]
	v_mfma_f32_16x16x32_bf16 v[20:23], v[196:199], v[180:183], v[20:23]
	v_mfma_f32_16x16x32_bf16 v[16:19], v[204:207], v[180:183], v[16:19]
	v_mfma_f32_16x16x32_bf16 v[4:7], v[196:199], v[188:191], v[4:7]
	v_mfma_f32_16x16x32_bf16 v[0:3], v[204:207], v[188:191], v[0:3]
	v_mfma_f32_16x16x32_bf16 v[52:55], v[200:203], v[168:171], v[52:55]
	v_mfma_f32_16x16x32_bf16 v[48:51], v[208:211], v[168:171], v[48:51]
	v_mfma_f32_16x16x32_bf16 v[36:39], v[200:203], v[176:179], v[36:39]
	v_mfma_f32_16x16x32_bf16 v[32:35], v[208:211], v[176:179], v[32:35]
	v_mfma_f32_16x16x32_bf16 v[20:23], v[200:203], v[184:187], v[20:23]
	v_mfma_f32_16x16x32_bf16 v[16:19], v[208:211], v[184:187], v[16:19]
	v_mfma_f32_16x16x32_bf16 v[4:7], v[200:203], v[192:195], v[4:7]
	v_mfma_f32_16x16x32_bf16 v[0:3], v[208:211], v[192:195], v[0:3]
	s_setprio 0
	s_add_i32 s77, s77, 2
	s_add_u32 s67, s67, 0x100
	s_addc_u32 s76, s76, 0
	s_cmp_gt_u32 s77, 13
	s_mov_b64 s[68:69], s[70:71]
	s_barrier
	s_cbranch_scc0 .LBB0_368
	v_lshl_add_u32 v146, s54, 8, v133
	s_lshl_b32 s17, s66, 8
	s_ashr_i32 s19, s17, 31
	v_ashrrev_i32_e32 v147, 31, v146
	v_mov_b32_e32 v145, s19
	v_or_b32_e32 v144, s17, v132
	v_bfe_u32 v224, v136, 4, 1
	v_mul_u32_u24_e32 v224, 24, v224
	v_mov_b32_e32 v225, 0
	v_mov_b32_e32 v212, v146
	v_mov_b32_e32 v213, v147
	v_lshlrev_b64 v[214:215], 11, v[212:213]
	v_lshl_add_u64 v[214:215], v[214:215], 0, v[144:145]
	v_lshl_add_u64 v[152:153], v[214:215], 2, s[20:21]
	global_load_dwordx4 v[164:167], v[152:153], off
	global_load_dwordx4 v[168:171], v[152:153], off offset:64
	global_load_dwordx4 v[172:175], v[152:153], off offset:512
	global_load_dwordx4 v[176:179], v[152:153], off offset:576
	v_add_u32_e32 v212, 0x10, v146
	v_mov_b32_e32 v213, v147
	v_lshlrev_b64 v[214:215], 11, v[212:213]
	v_lshl_add_u64 v[214:215], v[214:215], 0, v[144:145]
	v_lshl_add_u64 v[152:153], v[214:215], 2, s[20:21]
	global_load_dwordx4 v[180:183], v[152:153], off
	global_load_dwordx4 v[184:187], v[152:153], off offset:64
	global_load_dwordx4 v[188:191], v[152:153], off offset:512
	global_load_dwordx4 v[192:195], v[152:153], off offset:576
	v_add_u32_e32 v212, 0x20, v146
	v_mov_b32_e32 v213, v147
	v_lshlrev_b64 v[214:215], 11, v[212:213]
	v_lshl_add_u64 v[214:215], v[214:215], 0, v[144:145]
	v_lshl_add_u64 v[152:153], v[214:215], 2, s[20:21]
	global_load_dwordx4 v[196:199], v[152:153], off
	global_load_dwordx4 v[200:203], v[152:153], off offset:64
	global_load_dwordx4 v[204:207], v[152:153], off offset:512
	global_load_dwordx4 v[208:211], v[152:153], off offset:576
	s_waitcnt vmcnt(8)
	v_mov_b32_e32 v212, v146
	v_mov_b32_e32 v213, v147
	v_lshlrev_b64 v[214:215], 11, v[212:213]
	v_lshl_add_u64 v[214:215], v[214:215], 0, v[144:145]
	v_lshl_add_u64 v[154:155], v[214:215], 2, s[28:29]
	v_lshl_add_u64 v[156:157], v[214:215], 1, s[40:41]
	v_lshl_add_u64 v[156:157], v[156:157], 0, v[224:225]
	v_pk_add_f32 v[126:127], v[126:127], v[166:167]
	v_pk_add_f32 v[124:125], v[124:125], v[164:165]
	v_cvt_pk_bf16_f32 v221, v126, v127
	v_cvt_pk_bf16_f32 v220, v124, v125
	global_store_dwordx4 v[154:155], v[124:127], off
	s_nop 1
	v_mul_f32_e32 v125, v125, v125
	v_mul_f32_e32 v127, v127, v127
	v_fmac_f32_e32 v125, v124, v124
	v_fmac_f32_e32 v127, v126, v126
	v_add_f32_e32 v160, v125, v127
	v_pk_add_f32 v[122:123], v[122:123], v[170:171]
	v_pk_add_f32 v[120:121], v[120:121], v[168:169]
	v_cvt_pk_bf16_f32 v223, v122, v123
	v_cvt_pk_bf16_f32 v222, v120, v121
	global_store_dwordx4 v[154:155], v[120:123], off offset:64
	s_nop 1
	v_mul_f32_e32 v121, v121, v121
	v_mul_f32_e32 v123, v123, v123
	v_fmac_f32_e32 v121, v120, v120
	v_fmac_f32_e32 v123, v122, v122
	v_add_f32_e32 v120, v121, v123
	v_add_f32_e32 v160, v160, v120
	v_permlane16_swap_b32_e32 v220, v222
	v_permlane16_swap_b32_e32 v221, v223
	global_store_dwordx4 v[156:157], v[220:223], off
	s_nop 0
	v_pk_add_f32 v[118:119], v[118:119], v[174:175]
	v_pk_add_f32 v[116:117], v[116:117], v[172:173]
	v_cvt_pk_bf16_f32 v221, v118, v119
	v_cvt_pk_bf16_f32 v220, v116, v117
	global_store_dwordx4 v[154:155], v[116:119], off offset:512
	s_nop 1
	v_mul_f32_e32 v117, v117, v117
	v_mul_f32_e32 v119, v119, v119
	v_fmac_f32_e32 v117, v116, v116
	v_fmac_f32_e32 v119, v118, v118
	v_add_f32_e32 v116, v117, v119
	v_add_f32_e32 v160, v160, v116
	v_pk_add_f32 v[114:115], v[114:115], v[178:179]
	v_pk_add_f32 v[112:113], v[112:113], v[176:177]
	v_cvt_pk_bf16_f32 v223, v114, v115
	v_cvt_pk_bf16_f32 v222, v112, v113
	global_store_dwordx4 v[154:155], v[112:115], off offset:576
	s_nop 1
	v_mul_f32_e32 v113, v113, v113
	v_mul_f32_e32 v115, v115, v115
	v_fmac_f32_e32 v113, v112, v112
	v_fmac_f32_e32 v115, v114, v114
	v_add_f32_e32 v112, v113, v115
	v_add_f32_e32 v160, v160, v112
	v_permlane16_swap_b32_e32 v220, v222
	v_permlane16_swap_b32_e32 v221, v223
	global_store_dwordx4 v[156:157], v[220:223], off offset:256
	s_nop 0
	v_mov_b32_e32 v161, v160
	s_nop 1
	v_permlane16_swap_b32_e32 v160, v161
	v_add_f32_e32 v160, v160, v161
	v_mov_b32_e32 v161, v160
	s_nop 1
	v_permlane32_swap_b32_e32 v160, v161
	s_and_saveexec_b64 s[54:55], s[8:9]
	v_lshl_add_u64 v[162:163], v[212:213], 2, s[64:65]
	v_add_f32_e32 v160, v160, v161
	global_atomic_add_f32 v[162:163], v160, off
	s_or_b64 exec, exec, s[54:55]
	v_add_u32_e32 v212, 0x30, v146
	v_mov_b32_e32 v213, v147
	v_lshlrev_b64 v[214:215], 11, v[212:213]
	v_lshl_add_u64 v[214:215], v[214:215], 0, v[144:145]
	v_lshl_add_u64 v[152:153], v[214:215], 2, s[20:21]
	global_load_dwordx4 v[164:167], v[152:153], off
	global_load_dwordx4 v[168:171], v[152:153], off offset:64
	global_load_dwordx4 v[172:175], v[152:153], off offset:512
	global_load_dwordx4 v[176:179], v[152:153], off offset:576
	s_waitcnt vmcnt(15)
	v_add_u32_e32 v212, 0x10, v146
	v_mov_b32_e32 v213, v147
	v_lshlrev_b64 v[214:215], 11, v[212:213]
	v_lshl_add_u64 v[214:215], v[214:215], 0, v[144:145]
	v_lshl_add_u64 v[154:155], v[214:215], 2, s[28:29]
	v_lshl_add_u64 v[156:157], v[214:215], 1, s[40:41]
	v_lshl_add_u64 v[156:157], v[156:157], 0, v[224:225]
	v_pk_add_f32 v[110:111], v[110:111], v[182:183]
	v_pk_add_f32 v[108:109], v[108:109], v[180:181]
	v_cvt_pk_bf16_f32 v221, v110, v111
	v_cvt_pk_bf16_f32 v220, v108, v109
	global_store_dwordx4 v[154:155], v[108:111], off
	s_nop 1
	v_mul_f32_e32 v109, v109, v109
	v_mul_f32_e32 v111, v111, v111
	v_fmac_f32_e32 v109, v108, v108
	v_fmac_f32_e32 v111, v110, v110
	v_add_f32_e32 v160, v109, v111
	v_pk_add_f32 v[106:107], v[106:107], v[186:187]
	v_pk_add_f32 v[104:105], v[104:105], v[184:185]
	v_cvt_pk_bf16_f32 v223, v106, v107
	v_cvt_pk_bf16_f32 v222, v104, v105
	global_store_dwordx4 v[154:155], v[104:107], off offset:64
	s_nop 1
	v_mul_f32_e32 v105, v105, v105
	v_mul_f32_e32 v107, v107, v107
	v_fmac_f32_e32 v105, v104, v104
	v_fmac_f32_e32 v107, v106, v106
	v_add_f32_e32 v104, v105, v107
	v_add_f32_e32 v160, v160, v104
	v_permlane16_swap_b32_e32 v220, v222
	v_permlane16_swap_b32_e32 v221, v223
	global_store_dwordx4 v[156:157], v[220:223], off
	s_nop 0
	v_pk_add_f32 v[102:103], v[102:103], v[190:191]
	v_pk_add_f32 v[100:101], v[100:101], v[188:189]
	v_cvt_pk_bf16_f32 v221, v102, v103
	v_cvt_pk_bf16_f32 v220, v100, v101
	global_store_dwordx4 v[154:155], v[100:103], off offset:512
	s_nop 1
	v_mul_f32_e32 v101, v101, v101
	v_mul_f32_e32 v103, v103, v103
	v_fmac_f32_e32 v101, v100, v100
	v_fmac_f32_e32 v103, v102, v102
	v_add_f32_e32 v100, v101, v103
	v_add_f32_e32 v160, v160, v100
	v_pk_add_f32 v[98:99], v[98:99], v[194:195]
	v_pk_add_f32 v[96:97], v[96:97], v[192:193]
	v_cvt_pk_bf16_f32 v223, v98, v99
	v_cvt_pk_bf16_f32 v222, v96, v97
	global_store_dwordx4 v[154:155], v[96:99], off offset:576
	s_nop 1
	v_mul_f32_e32 v97, v97, v97
	v_mul_f32_e32 v99, v99, v99
	v_fmac_f32_e32 v97, v96, v96
	v_fmac_f32_e32 v99, v98, v98
	v_add_f32_e32 v96, v97, v99
	v_add_f32_e32 v160, v160, v96
	v_permlane16_swap_b32_e32 v220, v222
	v_permlane16_swap_b32_e32 v221, v223
	global_store_dwordx4 v[156:157], v[220:223], off offset:256
	s_nop 0
	v_mov_b32_e32 v161, v160
	s_nop 1
	v_permlane16_swap_b32_e32 v160, v161
	v_add_f32_e32 v160, v160, v161
	v_mov_b32_e32 v161, v160
	s_nop 1
	v_permlane32_swap_b32_e32 v160, v161
	s_and_saveexec_b64 s[54:55], s[8:9]
	v_lshl_add_u64 v[162:163], v[212:213], 2, s[64:65]
	v_add_f32_e32 v160, v160, v161
	global_atomic_add_f32 v[162:163], v160, off
	s_or_b64 exec, exec, s[54:55]
	v_add_u32_e32 v212, 0x80, v146
	v_mov_b32_e32 v213, v147
	v_lshlrev_b64 v[214:215], 11, v[212:213]
	v_lshl_add_u64 v[214:215], v[214:215], 0, v[144:145]
	v_lshl_add_u64 v[152:153], v[214:215], 2, s[20:21]
	global_load_dwordx4 v[180:183], v[152:153], off
	global_load_dwordx4 v[184:187], v[152:153], off offset:64
	global_load_dwordx4 v[188:191], v[152:153], off offset:512
	global_load_dwordx4 v[192:195], v[152:153], off offset:576
	s_waitcnt vmcnt(22)
	v_add_u32_e32 v212, 0x20, v146
	v_mov_b32_e32 v213, v147
	v_lshlrev_b64 v[214:215], 11, v[212:213]
	v_lshl_add_u64 v[214:215], v[214:215], 0, v[144:145]
	v_lshl_add_u64 v[154:155], v[214:215], 2, s[28:29]
	v_lshl_add_u64 v[156:157], v[214:215], 1, s[40:41]
	v_lshl_add_u64 v[156:157], v[156:157], 0, v[224:225]
	v_pk_add_f32 v[94:95], v[94:95], v[198:199]
	v_pk_add_f32 v[92:93], v[92:93], v[196:197]
	v_cvt_pk_bf16_f32 v221, v94, v95
	v_cvt_pk_bf16_f32 v220, v92, v93
	global_store_dwordx4 v[154:155], v[92:95], off
	s_nop 1
	v_mul_f32_e32 v93, v93, v93
	v_mul_f32_e32 v95, v95, v95
	v_fmac_f32_e32 v93, v92, v92
	v_fmac_f32_e32 v95, v94, v94
	v_add_f32_e32 v160, v93, v95
	v_pk_add_f32 v[90:91], v[90:91], v[202:203]
	v_pk_add_f32 v[88:89], v[88:89], v[200:201]
	v_cvt_pk_bf16_f32 v223, v90, v91
	v_cvt_pk_bf16_f32 v222, v88, v89
	global_store_dwordx4 v[154:155], v[88:91], off offset:64
	s_nop 1
	v_mul_f32_e32 v89, v89, v89
	v_mul_f32_e32 v91, v91, v91
	v_fmac_f32_e32 v89, v88, v88
	v_fmac_f32_e32 v91, v90, v90
	v_add_f32_e32 v88, v89, v91
	v_add_f32_e32 v160, v160, v88
	v_permlane16_swap_b32_e32 v220, v222
	v_permlane16_swap_b32_e32 v221, v223
	global_store_dwordx4 v[156:157], v[220:223], off
	s_nop 0
	v_pk_add_f32 v[86:87], v[86:87], v[206:207]
	v_pk_add_f32 v[84:85], v[84:85], v[204:205]
	v_cvt_pk_bf16_f32 v221, v86, v87
	v_cvt_pk_bf16_f32 v220, v84, v85
	global_store_dwordx4 v[154:155], v[84:87], off offset:512
	s_nop 1
	v_mul_f32_e32 v85, v85, v85
	v_mul_f32_e32 v87, v87, v87
	v_fmac_f32_e32 v85, v84, v84
	v_fmac_f32_e32 v87, v86, v86
	v_add_f32_e32 v84, v85, v87
	v_add_f32_e32 v160, v160, v84
	v_pk_add_f32 v[82:83], v[82:83], v[210:211]
	v_pk_add_f32 v[80:81], v[80:81], v[208:209]
	v_cvt_pk_bf16_f32 v223, v82, v83
	v_cvt_pk_bf16_f32 v222, v80, v81
	global_store_dwordx4 v[154:155], v[80:83], off offset:576
	s_nop 1
	v_mul_f32_e32 v81, v81, v81
	v_mul_f32_e32 v83, v83, v83
	v_fmac_f32_e32 v81, v80, v80
	v_fmac_f32_e32 v83, v82, v82
	v_add_f32_e32 v80, v81, v83
	v_add_f32_e32 v160, v160, v80
	v_permlane16_swap_b32_e32 v220, v222
	v_permlane16_swap_b32_e32 v221, v223
	global_store_dwordx4 v[156:157], v[220:223], off offset:256
	s_nop 0
	v_mov_b32_e32 v161, v160
	s_nop 1
	v_permlane16_swap_b32_e32 v160, v161
	v_add_f32_e32 v160, v160, v161
	v_mov_b32_e32 v161, v160
	s_nop 1
	v_permlane32_swap_b32_e32 v160, v161
	s_and_saveexec_b64 s[54:55], s[8:9]
	v_lshl_add_u64 v[162:163], v[212:213], 2, s[64:65]
	v_add_f32_e32 v160, v160, v161
	global_atomic_add_f32 v[162:163], v160, off
	s_or_b64 exec, exec, s[54:55]
	v_add_u32_e32 v212, 0x90, v146
	v_mov_b32_e32 v213, v147
	v_lshlrev_b64 v[214:215], 11, v[212:213]
	v_lshl_add_u64 v[214:215], v[214:215], 0, v[144:145]
	v_lshl_add_u64 v[152:153], v[214:215], 2, s[20:21]
	global_load_dwordx4 v[196:199], v[152:153], off
	global_load_dwordx4 v[200:203], v[152:153], off offset:64
	global_load_dwordx4 v[204:207], v[152:153], off offset:512
	global_load_dwordx4 v[208:211], v[152:153], off offset:576
	s_waitcnt vmcnt(22)
	v_add_u32_e32 v212, 0x30, v146
	v_mov_b32_e32 v213, v147
	v_lshlrev_b64 v[214:215], 11, v[212:213]
	v_lshl_add_u64 v[214:215], v[214:215], 0, v[144:145]
	v_lshl_add_u64 v[154:155], v[214:215], 2, s[28:29]
	v_lshl_add_u64 v[156:157], v[214:215], 1, s[40:41]
	v_lshl_add_u64 v[156:157], v[156:157], 0, v[224:225]
	v_pk_add_f32 v[78:79], v[78:79], v[166:167]
	v_pk_add_f32 v[76:77], v[76:77], v[164:165]
	v_cvt_pk_bf16_f32 v221, v78, v79
	v_cvt_pk_bf16_f32 v220, v76, v77
	global_store_dwordx4 v[154:155], v[76:79], off
	s_nop 1
	v_mul_f32_e32 v77, v77, v77
	v_mul_f32_e32 v79, v79, v79
	v_fmac_f32_e32 v77, v76, v76
	v_fmac_f32_e32 v79, v78, v78
	v_add_f32_e32 v160, v77, v79
	v_pk_add_f32 v[74:75], v[74:75], v[170:171]
	v_pk_add_f32 v[72:73], v[72:73], v[168:169]
	v_cvt_pk_bf16_f32 v223, v74, v75
	v_cvt_pk_bf16_f32 v222, v72, v73
	global_store_dwordx4 v[154:155], v[72:75], off offset:64
	s_nop 1
	v_mul_f32_e32 v73, v73, v73
	v_mul_f32_e32 v75, v75, v75
	v_fmac_f32_e32 v73, v72, v72
	v_fmac_f32_e32 v75, v74, v74
	v_add_f32_e32 v72, v73, v75
	v_add_f32_e32 v160, v160, v72
	v_permlane16_swap_b32_e32 v220, v222
	v_permlane16_swap_b32_e32 v221, v223
	global_store_dwordx4 v[156:157], v[220:223], off
	s_nop 0
	v_pk_add_f32 v[70:71], v[70:71], v[174:175]
	v_pk_add_f32 v[68:69], v[68:69], v[172:173]
	v_cvt_pk_bf16_f32 v221, v70, v71
	v_cvt_pk_bf16_f32 v220, v68, v69
	global_store_dwordx4 v[154:155], v[68:71], off offset:512
	s_nop 1
	v_mul_f32_e32 v69, v69, v69
	v_mul_f32_e32 v71, v71, v71
	v_fmac_f32_e32 v69, v68, v68
	v_fmac_f32_e32 v71, v70, v70
	v_add_f32_e32 v68, v69, v71
	v_add_f32_e32 v160, v160, v68
	v_pk_add_f32 v[66:67], v[66:67], v[178:179]
	v_pk_add_f32 v[64:65], v[64:65], v[176:177]
	v_cvt_pk_bf16_f32 v223, v66, v67
	v_cvt_pk_bf16_f32 v222, v64, v65
	global_store_dwordx4 v[154:155], v[64:67], off offset:576
	s_nop 1
	v_mul_f32_e32 v65, v65, v65
	v_mul_f32_e32 v67, v67, v67
	v_fmac_f32_e32 v65, v64, v64
	v_fmac_f32_e32 v67, v66, v66
	v_add_f32_e32 v64, v65, v67
	v_add_f32_e32 v160, v160, v64
	v_permlane16_swap_b32_e32 v220, v222
	v_permlane16_swap_b32_e32 v221, v223
	global_store_dwordx4 v[156:157], v[220:223], off offset:256
	s_nop 0
	v_mov_b32_e32 v161, v160
	s_nop 1
	v_permlane16_swap_b32_e32 v160, v161
	v_add_f32_e32 v160, v160, v161
	v_mov_b32_e32 v161, v160
	s_nop 1
	v_permlane32_swap_b32_e32 v160, v161
	s_and_saveexec_b64 s[54:55], s[8:9]
	v_lshl_add_u64 v[162:163], v[212:213], 2, s[64:65]
	v_add_f32_e32 v160, v160, v161
	global_atomic_add_f32 v[162:163], v160, off
	s_or_b64 exec, exec, s[54:55]
	v_add_u32_e32 v212, 0xa0, v146
	v_mov_b32_e32 v213, v147
	v_lshlrev_b64 v[214:215], 11, v[212:213]
	v_lshl_add_u64 v[214:215], v[214:215], 0, v[144:145]
	v_lshl_add_u64 v[152:153], v[214:215], 2, s[20:21]
	global_load_dwordx4 v[164:167], v[152:153], off
	global_load_dwordx4 v[168:171], v[152:153], off offset:64
	global_load_dwordx4 v[172:175], v[152:153], off offset:512
	global_load_dwordx4 v[176:179], v[152:153], off offset:576
	s_waitcnt vmcnt(22)
	v_add_u32_e32 v212, 0x80, v146
	v_mov_b32_e32 v213, v147
	v_lshlrev_b64 v[214:215], 11, v[212:213]
	v_lshl_add_u64 v[214:215], v[214:215], 0, v[144:145]
	v_lshl_add_u64 v[154:155], v[214:215], 2, s[28:29]
	v_lshl_add_u64 v[156:157], v[214:215], 1, s[40:41]
	v_lshl_add_u64 v[156:157], v[156:157], 0, v[224:225]
	v_pk_add_f32 v[62:63], v[62:63], v[182:183]
	v_pk_add_f32 v[60:61], v[60:61], v[180:181]
	v_cvt_pk_bf16_f32 v221, v62, v63
	v_cvt_pk_bf16_f32 v220, v60, v61
	global_store_dwordx4 v[154:155], v[60:63], off
	s_nop 1
	v_mul_f32_e32 v61, v61, v61
	v_mul_f32_e32 v63, v63, v63
	v_fmac_f32_e32 v61, v60, v60
	v_fmac_f32_e32 v63, v62, v62
	v_add_f32_e32 v160, v61, v63
	v_pk_add_f32 v[58:59], v[58:59], v[186:187]
	v_pk_add_f32 v[56:57], v[56:57], v[184:185]
	v_cvt_pk_bf16_f32 v223, v58, v59
	v_cvt_pk_bf16_f32 v222, v56, v57
	global_store_dwordx4 v[154:155], v[56:59], off offset:64
	s_nop 1
	v_mul_f32_e32 v57, v57, v57
	v_mul_f32_e32 v59, v59, v59
	v_fmac_f32_e32 v57, v56, v56
	v_fmac_f32_e32 v59, v58, v58
	v_add_f32_e32 v56, v57, v59
	v_add_f32_e32 v160, v160, v56
	v_permlane16_swap_b32_e32 v220, v222
	v_permlane16_swap_b32_e32 v221, v223
	global_store_dwordx4 v[156:157], v[220:223], off
	s_nop 0
	v_pk_add_f32 v[54:55], v[54:55], v[190:191]
	v_pk_add_f32 v[52:53], v[52:53], v[188:189]
	v_cvt_pk_bf16_f32 v221, v54, v55
	v_cvt_pk_bf16_f32 v220, v52, v53
	global_store_dwordx4 v[154:155], v[52:55], off offset:512
	s_nop 1
	v_mul_f32_e32 v53, v53, v53
	v_mul_f32_e32 v55, v55, v55
	v_fmac_f32_e32 v53, v52, v52
	v_fmac_f32_e32 v55, v54, v54
	v_add_f32_e32 v52, v53, v55
	v_add_f32_e32 v160, v160, v52
	v_pk_add_f32 v[50:51], v[50:51], v[194:195]
	v_pk_add_f32 v[48:49], v[48:49], v[192:193]
	v_cvt_pk_bf16_f32 v223, v50, v51
	v_cvt_pk_bf16_f32 v222, v48, v49
	global_store_dwordx4 v[154:155], v[48:51], off offset:576
	s_nop 1
	v_mul_f32_e32 v49, v49, v49
	v_mul_f32_e32 v51, v51, v51
	v_fmac_f32_e32 v49, v48, v48
	v_fmac_f32_e32 v51, v50, v50
	v_add_f32_e32 v48, v49, v51
	v_add_f32_e32 v160, v160, v48
	v_permlane16_swap_b32_e32 v220, v222
	v_permlane16_swap_b32_e32 v221, v223
	global_store_dwordx4 v[156:157], v[220:223], off offset:256
	s_nop 0
	v_mov_b32_e32 v161, v160
	s_nop 1
	v_permlane16_swap_b32_e32 v160, v161
	v_add_f32_e32 v160, v160, v161
	v_mov_b32_e32 v161, v160
	s_nop 1
	v_permlane32_swap_b32_e32 v160, v161
	s_and_saveexec_b64 s[54:55], s[8:9]
	v_lshl_add_u64 v[162:163], v[212:213], 2, s[64:65]
	v_add_f32_e32 v160, v160, v161
	global_atomic_add_f32 v[162:163], v160, off
	s_or_b64 exec, exec, s[54:55]
	v_add_u32_e32 v212, 0xb0, v146
	v_mov_b32_e32 v213, v147
	v_lshlrev_b64 v[214:215], 11, v[212:213]
	v_lshl_add_u64 v[214:215], v[214:215], 0, v[144:145]
	v_lshl_add_u64 v[152:153], v[214:215], 2, s[20:21]
	global_load_dwordx4 v[180:183], v[152:153], off
	global_load_dwordx4 v[184:187], v[152:153], off offset:64
	global_load_dwordx4 v[188:191], v[152:153], off offset:512
	global_load_dwordx4 v[192:195], v[152:153], off offset:576
	s_waitcnt vmcnt(22)
	v_add_u32_e32 v212, 0x90, v146
	v_mov_b32_e32 v213, v147
	v_lshlrev_b64 v[214:215], 11, v[212:213]
	v_lshl_add_u64 v[214:215], v[214:215], 0, v[144:145]
	v_lshl_add_u64 v[154:155], v[214:215], 2, s[28:29]
	v_lshl_add_u64 v[156:157], v[214:215], 1, s[40:41]
	v_lshl_add_u64 v[156:157], v[156:157], 0, v[224:225]
	v_pk_add_f32 v[46:47], v[46:47], v[198:199]
	v_pk_add_f32 v[44:45], v[44:45], v[196:197]
	v_cvt_pk_bf16_f32 v221, v46, v47
	v_cvt_pk_bf16_f32 v220, v44, v45
	global_store_dwordx4 v[154:155], v[44:47], off
	s_nop 1
	v_mul_f32_e32 v45, v45, v45
	v_mul_f32_e32 v47, v47, v47
	v_fmac_f32_e32 v45, v44, v44
	v_fmac_f32_e32 v47, v46, v46
	v_add_f32_e32 v160, v45, v47
	v_pk_add_f32 v[42:43], v[42:43], v[202:203]
	v_pk_add_f32 v[40:41], v[40:41], v[200:201]
	v_cvt_pk_bf16_f32 v223, v42, v43
	v_cvt_pk_bf16_f32 v222, v40, v41
	global_store_dwordx4 v[154:155], v[40:43], off offset:64
	s_nop 1
	v_mul_f32_e32 v41, v41, v41
	v_mul_f32_e32 v43, v43, v43
	v_fmac_f32_e32 v41, v40, v40
	v_fmac_f32_e32 v43, v42, v42
	v_add_f32_e32 v40, v41, v43
	v_add_f32_e32 v160, v160, v40
	v_permlane16_swap_b32_e32 v220, v222
	v_permlane16_swap_b32_e32 v221, v223
	global_store_dwordx4 v[156:157], v[220:223], off
	s_nop 0
	v_pk_add_f32 v[38:39], v[38:39], v[206:207]
	v_pk_add_f32 v[36:37], v[36:37], v[204:205]
	v_cvt_pk_bf16_f32 v221, v38, v39
	v_cvt_pk_bf16_f32 v220, v36, v37
	global_store_dwordx4 v[154:155], v[36:39], off offset:512
	s_nop 1
	v_mul_f32_e32 v37, v37, v37
	v_mul_f32_e32 v39, v39, v39
	v_fmac_f32_e32 v37, v36, v36
	v_fmac_f32_e32 v39, v38, v38
	v_add_f32_e32 v36, v37, v39
	v_add_f32_e32 v160, v160, v36
	v_pk_add_f32 v[34:35], v[34:35], v[210:211]
	v_pk_add_f32 v[32:33], v[32:33], v[208:209]
	v_cvt_pk_bf16_f32 v223, v34, v35
	v_cvt_pk_bf16_f32 v222, v32, v33
	global_store_dwordx4 v[154:155], v[32:35], off offset:576
	s_nop 1
	v_mul_f32_e32 v33, v33, v33
	v_mul_f32_e32 v35, v35, v35
	v_fmac_f32_e32 v33, v32, v32
	v_fmac_f32_e32 v35, v34, v34
	v_add_f32_e32 v32, v33, v35
	v_add_f32_e32 v160, v160, v32
	v_permlane16_swap_b32_e32 v220, v222
	v_permlane16_swap_b32_e32 v221, v223
	global_store_dwordx4 v[156:157], v[220:223], off offset:256
	s_nop 0
	v_mov_b32_e32 v161, v160
	s_nop 1
	v_permlane16_swap_b32_e32 v160, v161
	v_add_f32_e32 v160, v160, v161
	v_mov_b32_e32 v161, v160
	s_nop 1
	v_permlane32_swap_b32_e32 v160, v161
	s_and_saveexec_b64 s[54:55], s[8:9]
	v_lshl_add_u64 v[162:163], v[212:213], 2, s[64:65]
	v_add_f32_e32 v160, v160, v161
	global_atomic_add_f32 v[162:163], v160, off
	s_or_b64 exec, exec, s[54:55]
	s_waitcnt vmcnt(18)
	v_add_u32_e32 v212, 0xa0, v146
	v_mov_b32_e32 v213, v147
	v_lshlrev_b64 v[214:215], 11, v[212:213]
	v_lshl_add_u64 v[214:215], v[214:215], 0, v[144:145]
	v_lshl_add_u64 v[154:155], v[214:215], 2, s[28:29]
	v_lshl_add_u64 v[156:157], v[214:215], 1, s[40:41]
	v_lshl_add_u64 v[156:157], v[156:157], 0, v[224:225]
	v_pk_add_f32 v[30:31], v[30:31], v[166:167]
	v_pk_add_f32 v[28:29], v[28:29], v[164:165]
	v_cvt_pk_bf16_f32 v221, v30, v31
	v_cvt_pk_bf16_f32 v220, v28, v29
	global_store_dwordx4 v[154:155], v[28:31], off
	s_nop 1
	v_mul_f32_e32 v29, v29, v29
	v_mul_f32_e32 v31, v31, v31
	v_fmac_f32_e32 v29, v28, v28
	v_fmac_f32_e32 v31, v30, v30
	v_add_f32_e32 v160, v29, v31
	v_pk_add_f32 v[26:27], v[26:27], v[170:171]
	v_pk_add_f32 v[24:25], v[24:25], v[168:169]
	v_cvt_pk_bf16_f32 v223, v26, v27
	v_cvt_pk_bf16_f32 v222, v24, v25
	global_store_dwordx4 v[154:155], v[24:27], off offset:64
	s_nop 1
	v_mul_f32_e32 v25, v25, v25
	v_mul_f32_e32 v27, v27, v27
	v_fmac_f32_e32 v25, v24, v24
	v_fmac_f32_e32 v27, v26, v26
	v_add_f32_e32 v24, v25, v27
	v_add_f32_e32 v160, v160, v24
	v_permlane16_swap_b32_e32 v220, v222
	v_permlane16_swap_b32_e32 v221, v223
	global_store_dwordx4 v[156:157], v[220:223], off
	s_nop 0
	v_pk_add_f32 v[22:23], v[22:23], v[174:175]
	v_pk_add_f32 v[20:21], v[20:21], v[172:173]
	v_cvt_pk_bf16_f32 v221, v22, v23
	v_cvt_pk_bf16_f32 v220, v20, v21
	global_store_dwordx4 v[154:155], v[20:23], off offset:512
	s_nop 1
	v_mul_f32_e32 v21, v21, v21
	v_mul_f32_e32 v23, v23, v23
	v_fmac_f32_e32 v21, v20, v20
	v_fmac_f32_e32 v23, v22, v22
	v_add_f32_e32 v20, v21, v23
	v_add_f32_e32 v160, v160, v20
	v_pk_add_f32 v[18:19], v[18:19], v[178:179]
	v_pk_add_f32 v[16:17], v[16:17], v[176:177]
	v_cvt_pk_bf16_f32 v223, v18, v19
	v_cvt_pk_bf16_f32 v222, v16, v17
	global_store_dwordx4 v[154:155], v[16:19], off offset:576
	s_nop 1
	v_mul_f32_e32 v17, v17, v17
	v_mul_f32_e32 v19, v19, v19
	v_fmac_f32_e32 v17, v16, v16
	v_fmac_f32_e32 v19, v18, v18
	v_add_f32_e32 v16, v17, v19
	v_add_f32_e32 v160, v160, v16
	v_permlane16_swap_b32_e32 v220, v222
	v_permlane16_swap_b32_e32 v221, v223
	global_store_dwordx4 v[156:157], v[220:223], off offset:256
	s_nop 0
	v_mov_b32_e32 v161, v160
	s_nop 1
	v_permlane16_swap_b32_e32 v160, v161
	v_add_f32_e32 v160, v160, v161
	v_mov_b32_e32 v161, v160
	s_nop 1
	v_permlane32_swap_b32_e32 v160, v161
	s_and_saveexec_b64 s[54:55], s[8:9]
	v_lshl_add_u64 v[162:163], v[212:213], 2, s[64:65]
	v_add_f32_e32 v160, v160, v161
	global_atomic_add_f32 v[162:163], v160, off
	s_or_b64 exec, exec, s[54:55]
	s_waitcnt vmcnt(14)
	v_add_u32_e32 v212, 0xb0, v146
	v_mov_b32_e32 v213, v147
	v_lshlrev_b64 v[214:215], 11, v[212:213]
	v_lshl_add_u64 v[214:215], v[214:215], 0, v[144:145]
	v_lshl_add_u64 v[154:155], v[214:215], 2, s[28:29]
	v_lshl_add_u64 v[156:157], v[214:215], 1, s[40:41]
	v_lshl_add_u64 v[156:157], v[156:157], 0, v[224:225]
	v_pk_add_f32 v[14:15], v[14:15], v[182:183]
	v_pk_add_f32 v[12:13], v[12:13], v[180:181]
	v_cvt_pk_bf16_f32 v221, v14, v15
	v_cvt_pk_bf16_f32 v220, v12, v13
	global_store_dwordx4 v[154:155], v[12:15], off
	s_nop 1
	v_mul_f32_e32 v13, v13, v13
	v_mul_f32_e32 v15, v15, v15
	v_fmac_f32_e32 v13, v12, v12
	v_fmac_f32_e32 v15, v14, v14
	v_add_f32_e32 v160, v13, v15
	v_pk_add_f32 v[10:11], v[10:11], v[186:187]
	v_pk_add_f32 v[8:9], v[8:9], v[184:185]
	v_cvt_pk_bf16_f32 v223, v10, v11
	v_cvt_pk_bf16_f32 v222, v8, v9
	global_store_dwordx4 v[154:155], v[8:11], off offset:64
	s_nop 1
	v_mul_f32_e32 v9, v9, v9
	v_mul_f32_e32 v11, v11, v11
	v_fmac_f32_e32 v9, v8, v8
	v_fmac_f32_e32 v11, v10, v10
	v_add_f32_e32 v8, v9, v11
	v_add_f32_e32 v160, v160, v8
	v_permlane16_swap_b32_e32 v220, v222
	v_permlane16_swap_b32_e32 v221, v223
	global_store_dwordx4 v[156:157], v[220:223], off
	s_nop 0
	v_pk_add_f32 v[6:7], v[6:7], v[190:191]
	v_pk_add_f32 v[4:5], v[4:5], v[188:189]
	v_cvt_pk_bf16_f32 v221, v6, v7
	v_cvt_pk_bf16_f32 v220, v4, v5
	global_store_dwordx4 v[154:155], v[4:7], off offset:512
	s_nop 1
	v_mul_f32_e32 v5, v5, v5
	v_mul_f32_e32 v7, v7, v7
	v_fmac_f32_e32 v5, v4, v4
	v_fmac_f32_e32 v7, v6, v6
	v_add_f32_e32 v4, v5, v7
	v_add_f32_e32 v160, v160, v4
	v_pk_add_f32 v[2:3], v[2:3], v[194:195]
	v_pk_add_f32 v[0:1], v[0:1], v[192:193]
	v_cvt_pk_bf16_f32 v223, v2, v3
	v_cvt_pk_bf16_f32 v222, v0, v1
	global_store_dwordx4 v[154:155], v[0:3], off offset:576
	s_nop 1
	v_mul_f32_e32 v1, v1, v1
	v_mul_f32_e32 v3, v3, v3
	v_fmac_f32_e32 v1, v0, v0
	v_fmac_f32_e32 v3, v2, v2
	v_add_f32_e32 v0, v1, v3
	v_add_f32_e32 v160, v160, v0
	v_permlane16_swap_b32_e32 v220, v222
	v_permlane16_swap_b32_e32 v221, v223
	global_store_dwordx4 v[156:157], v[220:223], off offset:256
	s_nop 0
	v_mov_b32_e32 v161, v160
	s_nop 1
	v_permlane16_swap_b32_e32 v160, v161
	v_add_f32_e32 v160, v160, v161
	v_mov_b32_e32 v161, v160
	s_nop 1
	v_permlane32_swap_b32_e32 v160, v161
	s_and_saveexec_b64 s[54:55], s[8:9]
	v_lshl_add_u64 v[162:163], v[212:213], 2, s[64:65]
	v_add_f32_e32 v160, v160, v161
	global_atomic_add_f32 v[162:163], v160, off
	s_or_b64 exec, exec, s[54:55]
	s_branch .LBB0_360

.LBB0_530:
	ds_read_b128 v[144:147], v149
	ds_read_b128 v[152:155], v149 offset:1024
	ds_read_b128 v[156:159], v149 offset:2048
	ds_read_b128 v[160:163], v149 offset:3072
	s_add_u32 s70, s68, 0x100
	s_addc_u32 s71, s69, 0
	s_cmpk_eq_i32 s56, 0x7c
	s_cselect_b32 s75, s19, s71
	s_cselect_b32 s74, s25, s70
	s_cselect_b32 s73, s17, s55
	s_cselect_b32 s72, s49, s54
	v_lshl_add_u64 v[196:197], s[68:69], 0, v[134:135]
	s_add_i32 m0, s6, 0xc000
	ds_read_b128 v[164:167], v150
	ds_read_b128 v[168:171], v150 offset:1024
	ds_read_b128 v[172:175], v150 offset:2048
	ds_read_b128 v[176:179], v150 offset:3072
	ds_read_b128 v[180:183], v150 offset:4096
	ds_read_b128 v[184:187], v150 offset:5120
	ds_read_b128 v[188:191], v150 offset:6144
	ds_read_b128 v[192:195], v150 offset:7168
	global_load_lds_dwordx4 v[196:197], off
	v_lshl_add_u64 v[196:197], s[68:69], 0, v[138:139]
	s_add_i32 m0, s6, 0xe000
	s_nop 0
	global_load_lds_dwordx4 v[196:197], off
	s_waitcnt lgkmcnt(8)
	s_barrier
	s_waitcnt lgkmcnt(0)
	s_setprio 1
	s_waitcnt lgkmcnt(0)
	v_mfma_f32_16x16x32_bf16 v[124:127], v[144:147], v[164:167], v[124:127]
	v_mfma_f32_16x16x32_bf16 v[120:123], v[156:159], v[164:167], v[120:123]
	v_mfma_f32_16x16x32_bf16 v[108:111], v[144:147], v[172:175], v[108:111]
	v_mfma_f32_16x16x32_bf16 v[104:107], v[156:159], v[172:175], v[104:107]
	v_mfma_f32_16x16x32_bf16 v[92:95], v[144:147], v[180:183], v[92:95]
	v_mfma_f32_16x16x32_bf16 v[88:91], v[156:159], v[180:183], v[88:91]
	v_mfma_f32_16x16x32_bf16 v[76:79], v[144:147], v[188:191], v[76:79]
	v_mfma_f32_16x16x32_bf16 v[72:75], v[156:159], v[188:191], v[72:75]
	v_mfma_f32_16x16x32_bf16 v[124:127], v[152:155], v[168:171], v[124:127]
	v_mfma_f32_16x16x32_bf16 v[120:123], v[160:163], v[168:171], v[120:123]
	v_mfma_f32_16x16x32_bf16 v[108:111], v[152:155], v[176:179], v[108:111]
	v_mfma_f32_16x16x32_bf16 v[104:107], v[160:163], v[176:179], v[104:107]
	v_mfma_f32_16x16x32_bf16 v[92:95], v[152:155], v[184:187], v[92:95]
	v_mfma_f32_16x16x32_bf16 v[88:91], v[160:163], v[184:187], v[88:91]
	v_mfma_f32_16x16x32_bf16 v[76:79], v[152:155], v[192:195], v[76:79]
	v_mfma_f32_16x16x32_bf16 v[72:75], v[160:163], v[192:195], v[72:75]
	s_setprio 0
	s_barrier
	s_add_i32 s57, s47, s5
	v_lshl_add_u64 v[212:213], s[72:73], 0, v[128:129]
	s_mov_b32 m0, s57
	ds_read_b128 v[196:199], v151
	ds_read_b128 v[200:203], v151 offset:1024
	ds_read_b128 v[204:207], v151 offset:2048
	ds_read_b128 v[208:211], v151 offset:3072
	global_load_lds_dwordx4 v[212:213], off
	v_lshl_add_u64 v[214:215], s[72:73], 0, v[130:131]
	s_add_i32 m0, s57, 0x2000
	s_nop 0
	global_load_lds_dwordx4 v[214:215], off
	s_barrier
	s_waitcnt lgkmcnt(0)
	s_setprio 1
	s_waitcnt lgkmcnt(0)
	v_mfma_f32_16x16x32_bf16 v[116:119], v[196:199], v[164:167], v[116:119]
	v_mfma_f32_16x16x32_bf16 v[112:115], v[204:207], v[164:167], v[112:115]
	v_mfma_f32_16x16x32_bf16 v[100:103], v[196:199], v[172:175], v[100:103]
	v_mfma_f32_16x16x32_bf16 v[96:99], v[204:207], v[172:175], v[96:99]
	v_mfma_f32_16x16x32_bf16 v[84:87], v[196:199], v[180:183], v[84:87]
	v_mfma_f32_16x16x32_bf16 v[80:83], v[204:207], v[180:183], v[80:83]
	v_mfma_f32_16x16x32_bf16 v[68:71], v[196:199], v[188:191], v[68:71]
	v_mfma_f32_16x16x32_bf16 v[64:67], v[204:207], v[188:191], v[64:67]
	v_mfma_f32_16x16x32_bf16 v[116:119], v[200:203], v[168:171], v[116:119]
	v_mfma_f32_16x16x32_bf16 v[112:115], v[208:211], v[168:171], v[112:115]
	v_mfma_f32_16x16x32_bf16 v[100:103], v[200:203], v[176:179], v[100:103]
	v_mfma_f32_16x16x32_bf16 v[96:99], v[208:211], v[176:179], v[96:99]
	v_mfma_f32_16x16x32_bf16 v[84:87], v[200:203], v[184:187], v[84:87]
	v_mfma_f32_16x16x32_bf16 v[80:83], v[208:211], v[184:187], v[80:83]
	v_mfma_f32_16x16x32_bf16 v[68:71], v[200:203], v[192:195], v[68:71]
	v_mfma_f32_16x16x32_bf16 v[64:67], v[208:211], v[192:195], v[64:67]
	s_setprio 0
	s_mov_b32 m0, s6
	v_lshl_add_u64 v[216:217], s[74:75], 0, v[128:129]
	s_barrier
	ds_read_b128 v[164:167], v150 offset:16384
	ds_read_b128 v[168:171], v150 offset:17408
	ds_read_b128 v[172:175], v150 offset:18432
	ds_read_b128 v[176:179], v150 offset:19456
	ds_read_b128 v[180:183], v150 offset:20480
	ds_read_b128 v[184:187], v150 offset:21504
	ds_read_b128 v[188:191], v150 offset:22528
	ds_read_b128 v[192:195], v150 offset:23552
	global_load_lds_dwordx4 v[216:217], off
	v_lshl_add_u64 v[218:219], s[74:75], 0, v[130:131]
	s_mov_b32 m0, s7
	s_nop 0
	global_load_lds_dwordx4 v[218:219], off
	s_barrier
	s_waitcnt lgkmcnt(0)
	s_setprio 1
	s_waitcnt lgkmcnt(0)
	v_mfma_f32_16x16x32_bf16 v[60:63], v[144:147], v[164:167], v[60:63]
	v_mfma_f32_16x16x32_bf16 v[56:59], v[156:159], v[164:167], v[56:59]
	v_mfma_f32_16x16x32_bf16 v[44:47], v[144:147], v[172:175], v[44:47]
	v_mfma_f32_16x16x32_bf16 v[40:43], v[156:159], v[172:175], v[40:43]
	v_mfma_f32_16x16x32_bf16 v[28:31], v[144:147], v[180:183], v[28:31]
	v_mfma_f32_16x16x32_bf16 v[24:27], v[156:159], v[180:183], v[24:27]
	v_mfma_f32_16x16x32_bf16 v[12:15], v[144:147], v[188:191], v[12:15]
	v_mfma_f32_16x16x32_bf16 v[8:11], v[156:159], v[188:191], v[8:11]
	v_mfma_f32_16x16x32_bf16 v[60:63], v[152:155], v[168:171], v[60:63]
	v_mfma_f32_16x16x32_bf16 v[56:59], v[160:163], v[168:171], v[56:59]
	v_mfma_f32_16x16x32_bf16 v[44:47], v[152:155], v[176:179], v[44:47]
	v_mfma_f32_16x16x32_bf16 v[40:43], v[160:163], v[176:179], v[40:43]
	v_mfma_f32_16x16x32_bf16 v[28:31], v[152:155], v[184:187], v[28:31]
	v_mfma_f32_16x16x32_bf16 v[24:27], v[160:163], v[184:187], v[24:27]
	v_mfma_f32_16x16x32_bf16 v[12:15], v[152:155], v[192:195], v[12:15]
	v_mfma_f32_16x16x32_bf16 v[8:11], v[160:163], v[192:195], v[8:11]
	s_setprio 0
	s_barrier
	s_add_u32 s68, s72, 0x200000
	s_addc_u32 s69, s73, 0
	s_add_i32 s57, s48, s5
	v_lshl_add_u64 v[144:145], s[68:69], 0, v[128:129]
	s_mov_b32 m0, s57
	s_nop 0
	global_load_lds_dwordx4 v[144:145], off
	v_lshl_add_u64 v[144:145], s[68:69], 0, v[130:131]
	s_add_i32 m0, s57, 0x2000
	s_nop 0
	global_load_lds_dwordx4 v[144:145], off
	s_waitcnt vmcnt(6)
	s_barrier
	s_setprio 1
	v_mfma_f32_16x16x32_bf16 v[52:55], v[196:199], v[164:167], v[52:55]
	v_mfma_f32_16x16x32_bf16 v[48:51], v[204:207], v[164:167], v[48:51]
	v_mfma_f32_16x16x32_bf16 v[36:39], v[196:199], v[172:175], v[36:39]
	v_mfma_f32_16x16x32_bf16 v[32:35], v[204:207], v[172:175], v[32:35]
	v_mfma_f32_16x16x32_bf16 v[20:23], v[196:199], v[180:183], v[20:23]
	v_mfma_f32_16x16x32_bf16 v[16:19], v[204:207], v[180:183], v[16:19]
	v_mfma_f32_16x16x32_bf16 v[4:7], v[196:199], v[188:191], v[4:7]
	v_mfma_f32_16x16x32_bf16 v[0:3], v[204:207], v[188:191], v[0:3]
	v_mfma_f32_16x16x32_bf16 v[52:55], v[200:203], v[168:171], v[52:55]
	v_mfma_f32_16x16x32_bf16 v[48:51], v[208:211], v[168:171], v[48:51]
	v_mfma_f32_16x16x32_bf16 v[36:39], v[200:203], v[176:179], v[36:39]
	v_mfma_f32_16x16x32_bf16 v[32:35], v[208:211], v[176:179], v[32:35]
	v_mfma_f32_16x16x32_bf16 v[20:23], v[200:203], v[184:187], v[20:23]
	v_mfma_f32_16x16x32_bf16 v[16:19], v[208:211], v[184:187], v[16:19]
	v_mfma_f32_16x16x32_bf16 v[4:7], v[200:203], v[192:195], v[4:7]
	v_mfma_f32_16x16x32_bf16 v[0:3], v[208:211], v[192:195], v[0:3]
	s_setprio 0
	s_add_i32 s57, 16, 0x18000
	v_add_u32_e32 v160, s57, v148
	s_barrier
	ds_read_b128 v[144:147], v160
	ds_read_b128 v[152:155], v160 offset:1024
	ds_read_b128 v[156:159], v160 offset:2048
	ds_read_b128 v[160:163], v160 offset:3072
	s_add_u32 s68, s74, 0x200000
	s_addc_u32 s69, s75, 0
	s_mov_b32 m0, s26
	v_lshl_add_u64 v[196:197], s[68:69], 0, v[128:129]
	ds_read_b128 v[164:167], v150 offset:32768
	ds_read_b128 v[168:171], v150 offset:33792
	ds_read_b128 v[172:175], v150 offset:34816
	ds_read_b128 v[176:179], v150 offset:35840
	ds_read_b128 v[180:183], v150 offset:36864
	ds_read_b128 v[184:187], v150 offset:37888
	ds_read_b128 v[188:191], v150 offset:38912
	ds_read_b128 v[192:195], v150 offset:39936
	global_load_lds_dwordx4 v[196:197], off
	v_lshl_add_u64 v[196:197], s[68:69], 0, v[130:131]
	s_mov_b32 m0, s27
	s_nop 0
	global_load_lds_dwordx4 v[196:197], off
	s_waitcnt lgkmcnt(8)
	s_barrier
	s_waitcnt lgkmcnt(0)
	s_setprio 1
	s_waitcnt lgkmcnt(0)
	v_mfma_f32_16x16x32_bf16 v[124:127], v[144:147], v[164:167], v[124:127]
	v_mfma_f32_16x16x32_bf16 v[120:123], v[156:159], v[164:167], v[120:123]
	v_mfma_f32_16x16x32_bf16 v[108:111], v[144:147], v[172:175], v[108:111]
	v_mfma_f32_16x16x32_bf16 v[104:107], v[156:159], v[172:175], v[104:107]
	v_mfma_f32_16x16x32_bf16 v[92:95], v[144:147], v[180:183], v[92:95]
	v_mfma_f32_16x16x32_bf16 v[88:91], v[156:159], v[180:183], v[88:91]
	v_mfma_f32_16x16x32_bf16 v[76:79], v[144:147], v[188:191], v[76:79]
	v_mfma_f32_16x16x32_bf16 v[72:75], v[156:159], v[188:191], v[72:75]
	v_mfma_f32_16x16x32_bf16 v[124:127], v[152:155], v[168:171], v[124:127]
	v_mfma_f32_16x16x32_bf16 v[120:123], v[160:163], v[168:171], v[120:123]
	v_mfma_f32_16x16x32_bf16 v[108:111], v[152:155], v[176:179], v[108:111]
	v_mfma_f32_16x16x32_bf16 v[104:107], v[160:163], v[176:179], v[104:107]
	v_mfma_f32_16x16x32_bf16 v[92:95], v[152:155], v[184:187], v[92:95]
	v_mfma_f32_16x16x32_bf16 v[88:91], v[160:163], v[184:187], v[88:91]
	v_mfma_f32_16x16x32_bf16 v[76:79], v[152:155], v[192:195], v[76:79]
	v_mfma_f32_16x16x32_bf16 v[72:75], v[160:163], v[192:195], v[72:75]
	s_setprio 0
	s_barrier
	s_add_i32 s67, 16, 0x1c000
	s_add_i32 s57, s57, s5
	v_add_u32_e32 v208, s67, v148
	v_lshl_add_u64 v[212:213], v[212:213], 0, s[14:15]
	s_mov_b32 m0, s57
	ds_read_b128 v[196:199], v208
	ds_read_b128 v[200:203], v208 offset:1024
	ds_read_b128 v[204:207], v208 offset:2048
	ds_read_b128 v[208:211], v208 offset:3072
	global_load_lds_dwordx4 v[212:213], off
	v_lshl_add_u64 v[212:213], v[214:215], 0, s[14:15]
	s_add_i32 m0, s57, 0x2000
	s_nop 0
	global_load_lds_dwordx4 v[212:213], off
	s_barrier
	s_waitcnt lgkmcnt(0)
	s_setprio 1
	s_waitcnt lgkmcnt(0)
	v_mfma_f32_16x16x32_bf16 v[116:119], v[196:199], v[164:167], v[116:119]
	v_mfma_f32_16x16x32_bf16 v[112:115], v[204:207], v[164:167], v[112:115]
	v_mfma_f32_16x16x32_bf16 v[100:103], v[196:199], v[172:175], v[100:103]
	v_mfma_f32_16x16x32_bf16 v[96:99], v[204:207], v[172:175], v[96:99]
	v_mfma_f32_16x16x32_bf16 v[84:87], v[196:199], v[180:183], v[84:87]
	v_mfma_f32_16x16x32_bf16 v[80:83], v[204:207], v[180:183], v[80:83]
	v_mfma_f32_16x16x32_bf16 v[68:71], v[196:199], v[188:191], v[68:71]
	v_mfma_f32_16x16x32_bf16 v[64:67], v[204:207], v[188:191], v[64:67]
	v_mfma_f32_16x16x32_bf16 v[116:119], v[200:203], v[168:171], v[116:119]
	v_mfma_f32_16x16x32_bf16 v[112:115], v[208:211], v[168:171], v[112:115]
	v_mfma_f32_16x16x32_bf16 v[100:103], v[200:203], v[176:179], v[100:103]
	v_mfma_f32_16x16x32_bf16 v[96:99], v[208:211], v[176:179], v[96:99]
	v_mfma_f32_16x16x32_bf16 v[84:87], v[200:203], v[184:187], v[84:87]
	v_mfma_f32_16x16x32_bf16 v[80:83], v[208:211], v[184:187], v[80:83]
	v_mfma_f32_16x16x32_bf16 v[68:71], v[200:203], v[192:195], v[68:71]
	v_mfma_f32_16x16x32_bf16 v[64:67], v[208:211], v[192:195], v[64:67]
	s_setprio 0
	s_mov_b32 m0, s39
	v_lshl_add_u64 v[212:213], v[216:217], 0, s[14:15]
	s_barrier
	ds_read_b128 v[164:167], v150 offset:49152
	ds_read_b128 v[168:171], v150 offset:50176
	ds_read_b128 v[172:175], v150 offset:51200
	ds_read_b128 v[176:179], v150 offset:52224
	ds_read_b128 v[180:183], v150 offset:53248
	ds_read_b128 v[184:187], v150 offset:54272
	ds_read_b128 v[188:191], v150 offset:55296
	ds_read_b128 v[192:195], v150 offset:56320
	global_load_lds_dwordx4 v[212:213], off
	v_lshl_add_u64 v[212:213], v[218:219], 0, s[14:15]
	s_mov_b32 m0, s44
	s_nop 0
	global_load_lds_dwordx4 v[212:213], off
	s_barrier
	s_waitcnt lgkmcnt(0)
	s_setprio 1
	s_waitcnt lgkmcnt(0)
	v_mfma_f32_16x16x32_bf16 v[60:63], v[144:147], v[164:167], v[60:63]
	v_mfma_f32_16x16x32_bf16 v[56:59], v[156:159], v[164:167], v[56:59]
	v_mfma_f32_16x16x32_bf16 v[44:47], v[144:147], v[172:175], v[44:47]
	v_mfma_f32_16x16x32_bf16 v[40:43], v[156:159], v[172:175], v[40:43]
	v_mfma_f32_16x16x32_bf16 v[28:31], v[144:147], v[180:183], v[28:31]
	v_mfma_f32_16x16x32_bf16 v[24:27], v[156:159], v[180:183], v[24:27]
	v_mfma_f32_16x16x32_bf16 v[12:15], v[144:147], v[188:191], v[12:15]
	v_mfma_f32_16x16x32_bf16 v[8:11], v[156:159], v[188:191], v[8:11]
	v_mfma_f32_16x16x32_bf16 v[60:63], v[152:155], v[168:171], v[60:63]
	v_mfma_f32_16x16x32_bf16 v[56:59], v[160:163], v[168:171], v[56:59]
	v_mfma_f32_16x16x32_bf16 v[44:47], v[152:155], v[176:179], v[44:47]
	v_mfma_f32_16x16x32_bf16 v[40:43], v[160:163], v[176:179], v[40:43]
	v_mfma_f32_16x16x32_bf16 v[28:31], v[152:155], v[184:187], v[28:31]
	v_mfma_f32_16x16x32_bf16 v[24:27], v[160:163], v[184:187], v[24:27]
	v_mfma_f32_16x16x32_bf16 v[12:15], v[152:155], v[192:195], v[12:15]
	v_mfma_f32_16x16x32_bf16 v[8:11], v[160:163], v[192:195], v[8:11]
	s_setprio 0
	s_barrier
	s_add_u32 s68, s72, 0x200080
	s_addc_u32 s69, s73, 0
	s_add_i32 s57, s67, s5
	v_lshl_add_u64 v[144:145], s[68:69], 0, v[128:129]
	s_mov_b32 m0, s57
	s_nop 0
	global_load_lds_dwordx4 v[144:145], off
	v_lshl_add_u64 v[144:145], s[68:69], 0, v[130:131]
	s_add_i32 m0, s57, 0x2000
	s_nop 0
	global_load_lds_dwordx4 v[144:145], off
	s_waitcnt vmcnt(6)
	s_barrier
	s_setprio 1
	v_mfma_f32_16x16x32_bf16 v[52:55], v[196:199], v[164:167], v[52:55]
	v_mfma_f32_16x16x32_bf16 v[48:51], v[204:207], v[164:167], v[48:51]
	v_mfma_f32_16x16x32_bf16 v[36:39], v[196:199], v[172:175], v[36:39]
	v_mfma_f32_16x16x32_bf16 v[32:35], v[204:207], v[172:175], v[32:35]
	v_mfma_f32_16x16x32_bf16 v[20:23], v[196:199], v[180:183], v[20:23]
	v_mfma_f32_16x16x32_bf16 v[16:19], v[204:207], v[180:183], v[16:19]
	v_mfma_f32_16x16x32_bf16 v[4:7], v[196:199], v[188:191], v[4:7]
	v_mfma_f32_16x16x32_bf16 v[0:3], v[204:207], v[188:191], v[0:3]
	v_mfma_f32_16x16x32_bf16 v[52:55], v[200:203], v[168:171], v[52:55]
	v_mfma_f32_16x16x32_bf16 v[48:51], v[208:211], v[168:171], v[48:51]
	v_mfma_f32_16x16x32_bf16 v[36:39], v[200:203], v[176:179], v[36:39]
	v_mfma_f32_16x16x32_bf16 v[32:35], v[208:211], v[176:179], v[32:35]
	v_mfma_f32_16x16x32_bf16 v[20:23], v[200:203], v[184:187], v[20:23]
	v_mfma_f32_16x16x32_bf16 v[16:19], v[208:211], v[184:187], v[16:19]
	v_mfma_f32_16x16x32_bf16 v[4:7], v[200:203], v[192:195], v[4:7]
	v_mfma_f32_16x16x32_bf16 v[0:3], v[208:211], v[192:195], v[0:3]
	s_setprio 0
	s_add_i32 s56, s56, 2
	s_add_u32 s54, s54, 0x100
	s_addc_u32 s55, s55, 0
	s_cmpk_gt_u32 s56, 0x7d
	s_mov_b64 s[68:69], s[70:71]
	s_barrier
	s_cbranch_scc0 .LBB0_530
	v_lshl_add_u32 v146, s24, 8, v133
	s_lshl_b32 s17, s66, 8
	s_ashr_i32 s19, s17, 31
	v_ashrrev_i32_e32 v147, 31, v146
	v_mov_b32_e32 v145, s19
	v_or_b32_e32 v144, s17, v132
	v_bfe_u32 v224, v136, 4, 1
	v_mul_u32_u24_e32 v224, 24, v224
	v_mov_b32_e32 v225, 0
	v_mov_b32_e32 v212, v146
	v_mov_b32_e32 v213, v147
	v_lshlrev_b64 v[214:215], 11, v[212:213]
	v_lshl_add_u64 v[214:215], v[214:215], 0, v[144:145]
	v_lshl_add_u64 v[152:153], v[214:215], 2, s[28:29]
	global_load_dwordx4 v[164:167], v[152:153], off
	global_load_dwordx4 v[168:171], v[152:153], off offset:64
	global_load_dwordx4 v[172:175], v[152:153], off offset:512
	global_load_dwordx4 v[176:179], v[152:153], off offset:576
	v_add_u32_e32 v212, 0x10, v146
	v_mov_b32_e32 v213, v147
	v_lshlrev_b64 v[214:215], 11, v[212:213]
	v_lshl_add_u64 v[214:215], v[214:215], 0, v[144:145]
	v_lshl_add_u64 v[152:153], v[214:215], 2, s[28:29]
	global_load_dwordx4 v[180:183], v[152:153], off
	global_load_dwordx4 v[184:187], v[152:153], off offset:64
	global_load_dwordx4 v[188:191], v[152:153], off offset:512
	global_load_dwordx4 v[192:195], v[152:153], off offset:576
	v_add_u32_e32 v212, 0x20, v146
	v_mov_b32_e32 v213, v147
	v_lshlrev_b64 v[214:215], 11, v[212:213]
	v_lshl_add_u64 v[214:215], v[214:215], 0, v[144:145]
	v_lshl_add_u64 v[152:153], v[214:215], 2, s[28:29]
	global_load_dwordx4 v[196:199], v[152:153], off
	global_load_dwordx4 v[200:203], v[152:153], off offset:64
	global_load_dwordx4 v[204:207], v[152:153], off offset:512
	global_load_dwordx4 v[208:211], v[152:153], off offset:576
	s_waitcnt vmcnt(8)
	v_mov_b32_e32 v212, v146
	v_mov_b32_e32 v213, v147
	v_lshlrev_b64 v[214:215], 11, v[212:213]
	v_lshl_add_u64 v[214:215], v[214:215], 0, v[144:145]
	v_lshl_add_u64 v[154:155], v[214:215], 2, s[28:29]
	v_lshl_add_u64 v[156:157], v[214:215], 1, s[40:41]
	v_lshl_add_u64 v[156:157], v[156:157], 0, v[224:225]
	v_pk_add_f32 v[126:127], v[126:127], v[166:167]
	v_pk_add_f32 v[124:125], v[124:125], v[164:165]
	v_cvt_pk_bf16_f32 v221, v126, v127
	v_cvt_pk_bf16_f32 v220, v124, v125
	global_store_dwordx4 v[154:155], v[124:127], off
	s_nop 1
	v_mul_f32_e32 v125, v125, v125
	v_mul_f32_e32 v127, v127, v127
	v_fmac_f32_e32 v125, v124, v124
	v_fmac_f32_e32 v127, v126, v126
	v_add_f32_e32 v160, v125, v127
	v_pk_add_f32 v[122:123], v[122:123], v[170:171]
	v_pk_add_f32 v[120:121], v[120:121], v[168:169]
	v_cvt_pk_bf16_f32 v223, v122, v123
	v_cvt_pk_bf16_f32 v222, v120, v121
	global_store_dwordx4 v[154:155], v[120:123], off offset:64
	s_nop 1
	v_mul_f32_e32 v121, v121, v121
	v_mul_f32_e32 v123, v123, v123
	v_fmac_f32_e32 v121, v120, v120
	v_fmac_f32_e32 v123, v122, v122
	v_add_f32_e32 v120, v121, v123
	v_add_f32_e32 v160, v160, v120
	v_permlane16_swap_b32_e32 v220, v222
	v_permlane16_swap_b32_e32 v221, v223
	global_store_dwordx4 v[156:157], v[220:223], off
	s_nop 0
	v_pk_add_f32 v[118:119], v[118:119], v[174:175]
	v_pk_add_f32 v[116:117], v[116:117], v[172:173]
	v_cvt_pk_bf16_f32 v221, v118, v119
	v_cvt_pk_bf16_f32 v220, v116, v117
	global_store_dwordx4 v[154:155], v[116:119], off offset:512
	s_nop 1
	v_mul_f32_e32 v117, v117, v117
	v_mul_f32_e32 v119, v119, v119
	v_fmac_f32_e32 v117, v116, v116
	v_fmac_f32_e32 v119, v118, v118
	v_add_f32_e32 v116, v117, v119
	v_add_f32_e32 v160, v160, v116
	v_pk_add_f32 v[114:115], v[114:115], v[178:179]
	v_pk_add_f32 v[112:113], v[112:113], v[176:177]
	v_cvt_pk_bf16_f32 v223, v114, v115
	v_cvt_pk_bf16_f32 v222, v112, v113
	global_store_dwordx4 v[154:155], v[112:115], off offset:576
	s_nop 1
	v_mul_f32_e32 v113, v113, v113
	v_mul_f32_e32 v115, v115, v115
	v_fmac_f32_e32 v113, v112, v112
	v_fmac_f32_e32 v115, v114, v114
	v_add_f32_e32 v112, v113, v115
	v_add_f32_e32 v160, v160, v112
	v_permlane16_swap_b32_e32 v220, v222
	v_permlane16_swap_b32_e32 v221, v223
	global_store_dwordx4 v[156:157], v[220:223], off offset:256
	s_nop 0
	v_mov_b32_e32 v161, v160
	s_nop 1
	v_permlane16_swap_b32_e32 v160, v161
	v_add_f32_e32 v160, v160, v161
	v_mov_b32_e32 v161, v160
	s_nop 1
	v_permlane32_swap_b32_e32 v160, v161
	s_and_saveexec_b64 s[24:25], s[8:9]
	v_lshl_add_u64 v[162:163], v[212:213], 2, s[64:65]
	v_add_f32_e32 v160, v160, v161
	global_atomic_add_f32 v[162:163], v160, off
	s_or_b64 exec, exec, s[24:25]
	v_add_u32_e32 v212, 0x30, v146
	v_mov_b32_e32 v213, v147
	v_lshlrev_b64 v[214:215], 11, v[212:213]
	v_lshl_add_u64 v[214:215], v[214:215], 0, v[144:145]
	v_lshl_add_u64 v[152:153], v[214:215], 2, s[28:29]
	global_load_dwordx4 v[164:167], v[152:153], off
	global_load_dwordx4 v[168:171], v[152:153], off offset:64
	global_load_dwordx4 v[172:175], v[152:153], off offset:512
	global_load_dwordx4 v[176:179], v[152:153], off offset:576
	s_waitcnt vmcnt(15)
	v_add_u32_e32 v212, 0x10, v146
	v_mov_b32_e32 v213, v147
	v_lshlrev_b64 v[214:215], 11, v[212:213]
	v_lshl_add_u64 v[214:215], v[214:215], 0, v[144:145]
	v_lshl_add_u64 v[154:155], v[214:215], 2, s[28:29]
	v_lshl_add_u64 v[156:157], v[214:215], 1, s[40:41]
	v_lshl_add_u64 v[156:157], v[156:157], 0, v[224:225]
	v_pk_add_f32 v[110:111], v[110:111], v[182:183]
	v_pk_add_f32 v[108:109], v[108:109], v[180:181]
	v_cvt_pk_bf16_f32 v221, v110, v111
	v_cvt_pk_bf16_f32 v220, v108, v109
	global_store_dwordx4 v[154:155], v[108:111], off
	s_nop 1
	v_mul_f32_e32 v109, v109, v109
	v_mul_f32_e32 v111, v111, v111
	v_fmac_f32_e32 v109, v108, v108
	v_fmac_f32_e32 v111, v110, v110
	v_add_f32_e32 v160, v109, v111
	v_pk_add_f32 v[106:107], v[106:107], v[186:187]
	v_pk_add_f32 v[104:105], v[104:105], v[184:185]
	v_cvt_pk_bf16_f32 v223, v106, v107
	v_cvt_pk_bf16_f32 v222, v104, v105
	global_store_dwordx4 v[154:155], v[104:107], off offset:64
	s_nop 1
	v_mul_f32_e32 v105, v105, v105
	v_mul_f32_e32 v107, v107, v107
	v_fmac_f32_e32 v105, v104, v104
	v_fmac_f32_e32 v107, v106, v106
	v_add_f32_e32 v104, v105, v107
	v_add_f32_e32 v160, v160, v104
	v_permlane16_swap_b32_e32 v220, v222
	v_permlane16_swap_b32_e32 v221, v223
	global_store_dwordx4 v[156:157], v[220:223], off
	s_nop 0
	v_pk_add_f32 v[102:103], v[102:103], v[190:191]
	v_pk_add_f32 v[100:101], v[100:101], v[188:189]
	v_cvt_pk_bf16_f32 v221, v102, v103
	v_cvt_pk_bf16_f32 v220, v100, v101
	global_store_dwordx4 v[154:155], v[100:103], off offset:512
	s_nop 1
	v_mul_f32_e32 v101, v101, v101
	v_mul_f32_e32 v103, v103, v103
	v_fmac_f32_e32 v101, v100, v100
	v_fmac_f32_e32 v103, v102, v102
	v_add_f32_e32 v100, v101, v103
	v_add_f32_e32 v160, v160, v100
	v_pk_add_f32 v[98:99], v[98:99], v[194:195]
	v_pk_add_f32 v[96:97], v[96:97], v[192:193]
	v_cvt_pk_bf16_f32 v223, v98, v99
	v_cvt_pk_bf16_f32 v222, v96, v97
	global_store_dwordx4 v[154:155], v[96:99], off offset:576
	s_nop 1
	v_mul_f32_e32 v97, v97, v97
	v_mul_f32_e32 v99, v99, v99
	v_fmac_f32_e32 v97, v96, v96
	v_fmac_f32_e32 v99, v98, v98
	v_add_f32_e32 v96, v97, v99
	v_add_f32_e32 v160, v160, v96
	v_permlane16_swap_b32_e32 v220, v222
	v_permlane16_swap_b32_e32 v221, v223
	global_store_dwordx4 v[156:157], v[220:223], off offset:256
	s_nop 0
	v_mov_b32_e32 v161, v160
	s_nop 1
	v_permlane16_swap_b32_e32 v160, v161
	v_add_f32_e32 v160, v160, v161
	v_mov_b32_e32 v161, v160
	s_nop 1
	v_permlane32_swap_b32_e32 v160, v161
	s_and_saveexec_b64 s[24:25], s[8:9]
	v_lshl_add_u64 v[162:163], v[212:213], 2, s[64:65]
	v_add_f32_e32 v160, v160, v161
	global_atomic_add_f32 v[162:163], v160, off
	s_or_b64 exec, exec, s[24:25]
	v_add_u32_e32 v212, 0x80, v146
	v_mov_b32_e32 v213, v147
	v_lshlrev_b64 v[214:215], 11, v[212:213]
	v_lshl_add_u64 v[214:215], v[214:215], 0, v[144:145]
	v_lshl_add_u64 v[152:153], v[214:215], 2, s[28:29]
	global_load_dwordx4 v[180:183], v[152:153], off
	global_load_dwordx4 v[184:187], v[152:153], off offset:64
	global_load_dwordx4 v[188:191], v[152:153], off offset:512
	global_load_dwordx4 v[192:195], v[152:153], off offset:576
	s_waitcnt vmcnt(22)
	v_add_u32_e32 v212, 0x20, v146
	v_mov_b32_e32 v213, v147
	v_lshlrev_b64 v[214:215], 11, v[212:213]
	v_lshl_add_u64 v[214:215], v[214:215], 0, v[144:145]
	v_lshl_add_u64 v[154:155], v[214:215], 2, s[28:29]
	v_lshl_add_u64 v[156:157], v[214:215], 1, s[40:41]
	v_lshl_add_u64 v[156:157], v[156:157], 0, v[224:225]
	v_pk_add_f32 v[94:95], v[94:95], v[198:199]
	v_pk_add_f32 v[92:93], v[92:93], v[196:197]
	v_cvt_pk_bf16_f32 v221, v94, v95
	v_cvt_pk_bf16_f32 v220, v92, v93
	global_store_dwordx4 v[154:155], v[92:95], off
	s_nop 1
	v_mul_f32_e32 v93, v93, v93
	v_mul_f32_e32 v95, v95, v95
	v_fmac_f32_e32 v93, v92, v92
	v_fmac_f32_e32 v95, v94, v94
	v_add_f32_e32 v160, v93, v95
	v_pk_add_f32 v[90:91], v[90:91], v[202:203]
	v_pk_add_f32 v[88:89], v[88:89], v[200:201]
	v_cvt_pk_bf16_f32 v223, v90, v91
	v_cvt_pk_bf16_f32 v222, v88, v89
	global_store_dwordx4 v[154:155], v[88:91], off offset:64
	s_nop 1
	v_mul_f32_e32 v89, v89, v89
	v_mul_f32_e32 v91, v91, v91
	v_fmac_f32_e32 v89, v88, v88
	v_fmac_f32_e32 v91, v90, v90
	v_add_f32_e32 v88, v89, v91
	v_add_f32_e32 v160, v160, v88
	v_permlane16_swap_b32_e32 v220, v222
	v_permlane16_swap_b32_e32 v221, v223
	global_store_dwordx4 v[156:157], v[220:223], off
	s_nop 0
	v_pk_add_f32 v[86:87], v[86:87], v[206:207]
	v_pk_add_f32 v[84:85], v[84:85], v[204:205]
	v_cvt_pk_bf16_f32 v221, v86, v87
	v_cvt_pk_bf16_f32 v220, v84, v85
	global_store_dwordx4 v[154:155], v[84:87], off offset:512
	s_nop 1
	v_mul_f32_e32 v85, v85, v85
	v_mul_f32_e32 v87, v87, v87
	v_fmac_f32_e32 v85, v84, v84
	v_fmac_f32_e32 v87, v86, v86
	v_add_f32_e32 v84, v85, v87
	v_add_f32_e32 v160, v160, v84
	v_pk_add_f32 v[82:83], v[82:83], v[210:211]
	v_pk_add_f32 v[80:81], v[80:81], v[208:209]
	v_cvt_pk_bf16_f32 v223, v82, v83
	v_cvt_pk_bf16_f32 v222, v80, v81
	global_store_dwordx4 v[154:155], v[80:83], off offset:576
	s_nop 1
	v_mul_f32_e32 v81, v81, v81
	v_mul_f32_e32 v83, v83, v83
	v_fmac_f32_e32 v81, v80, v80
	v_fmac_f32_e32 v83, v82, v82
	v_add_f32_e32 v80, v81, v83
	v_add_f32_e32 v160, v160, v80
	v_permlane16_swap_b32_e32 v220, v222
	v_permlane16_swap_b32_e32 v221, v223
	global_store_dwordx4 v[156:157], v[220:223], off offset:256
	s_nop 0
	v_mov_b32_e32 v161, v160
	s_nop 1
	v_permlane16_swap_b32_e32 v160, v161
	v_add_f32_e32 v160, v160, v161
	v_mov_b32_e32 v161, v160
	s_nop 1
	v_permlane32_swap_b32_e32 v160, v161
	s_and_saveexec_b64 s[24:25], s[8:9]
	v_lshl_add_u64 v[162:163], v[212:213], 2, s[64:65]
	v_add_f32_e32 v160, v160, v161
	global_atomic_add_f32 v[162:163], v160, off
	s_or_b64 exec, exec, s[24:25]
	v_add_u32_e32 v212, 0x90, v146
	v_mov_b32_e32 v213, v147
	v_lshlrev_b64 v[214:215], 11, v[212:213]
	v_lshl_add_u64 v[214:215], v[214:215], 0, v[144:145]
	v_lshl_add_u64 v[152:153], v[214:215], 2, s[28:29]
	global_load_dwordx4 v[196:199], v[152:153], off
	global_load_dwordx4 v[200:203], v[152:153], off offset:64
	global_load_dwordx4 v[204:207], v[152:153], off offset:512
	global_load_dwordx4 v[208:211], v[152:153], off offset:576
	s_waitcnt vmcnt(22)
	v_add_u32_e32 v212, 0x30, v146
	v_mov_b32_e32 v213, v147
	v_lshlrev_b64 v[214:215], 11, v[212:213]
	v_lshl_add_u64 v[214:215], v[214:215], 0, v[144:145]
	v_lshl_add_u64 v[154:155], v[214:215], 2, s[28:29]
	v_lshl_add_u64 v[156:157], v[214:215], 1, s[40:41]
	v_lshl_add_u64 v[156:157], v[156:157], 0, v[224:225]
	v_pk_add_f32 v[78:79], v[78:79], v[166:167]
	v_pk_add_f32 v[76:77], v[76:77], v[164:165]
	v_cvt_pk_bf16_f32 v221, v78, v79
	v_cvt_pk_bf16_f32 v220, v76, v77
	global_store_dwordx4 v[154:155], v[76:79], off
	s_nop 1
	v_mul_f32_e32 v77, v77, v77
	v_mul_f32_e32 v79, v79, v79
	v_fmac_f32_e32 v77, v76, v76
	v_fmac_f32_e32 v79, v78, v78
	v_add_f32_e32 v160, v77, v79
	v_pk_add_f32 v[74:75], v[74:75], v[170:171]
	v_pk_add_f32 v[72:73], v[72:73], v[168:169]
	v_cvt_pk_bf16_f32 v223, v74, v75
	v_cvt_pk_bf16_f32 v222, v72, v73
	global_store_dwordx4 v[154:155], v[72:75], off offset:64
	s_nop 1
	v_mul_f32_e32 v73, v73, v73
	v_mul_f32_e32 v75, v75, v75
	v_fmac_f32_e32 v73, v72, v72
	v_fmac_f32_e32 v75, v74, v74
	v_add_f32_e32 v72, v73, v75
	v_add_f32_e32 v160, v160, v72
	v_permlane16_swap_b32_e32 v220, v222
	v_permlane16_swap_b32_e32 v221, v223
	global_store_dwordx4 v[156:157], v[220:223], off
	s_nop 0
	v_pk_add_f32 v[70:71], v[70:71], v[174:175]
	v_pk_add_f32 v[68:69], v[68:69], v[172:173]
	v_cvt_pk_bf16_f32 v221, v70, v71
	v_cvt_pk_bf16_f32 v220, v68, v69
	global_store_dwordx4 v[154:155], v[68:71], off offset:512
	s_nop 1
	v_mul_f32_e32 v69, v69, v69
	v_mul_f32_e32 v71, v71, v71
	v_fmac_f32_e32 v69, v68, v68
	v_fmac_f32_e32 v71, v70, v70
	v_add_f32_e32 v68, v69, v71
	v_add_f32_e32 v160, v160, v68
	v_pk_add_f32 v[66:67], v[66:67], v[178:179]
	v_pk_add_f32 v[64:65], v[64:65], v[176:177]
	v_cvt_pk_bf16_f32 v223, v66, v67
	v_cvt_pk_bf16_f32 v222, v64, v65
	global_store_dwordx4 v[154:155], v[64:67], off offset:576
	s_nop 1
	v_mul_f32_e32 v65, v65, v65
	v_mul_f32_e32 v67, v67, v67
	v_fmac_f32_e32 v65, v64, v64
	v_fmac_f32_e32 v67, v66, v66
	v_add_f32_e32 v64, v65, v67
	v_add_f32_e32 v160, v160, v64
	v_permlane16_swap_b32_e32 v220, v222
	v_permlane16_swap_b32_e32 v221, v223
	global_store_dwordx4 v[156:157], v[220:223], off offset:256
	s_nop 0
	v_mov_b32_e32 v161, v160
	s_nop 1
	v_permlane16_swap_b32_e32 v160, v161
	v_add_f32_e32 v160, v160, v161
	v_mov_b32_e32 v161, v160
	s_nop 1
	v_permlane32_swap_b32_e32 v160, v161
	s_and_saveexec_b64 s[24:25], s[8:9]
	v_lshl_add_u64 v[162:163], v[212:213], 2, s[64:65]
	v_add_f32_e32 v160, v160, v161
	global_atomic_add_f32 v[162:163], v160, off
	s_or_b64 exec, exec, s[24:25]
	v_add_u32_e32 v212, 0xa0, v146
	v_mov_b32_e32 v213, v147
	v_lshlrev_b64 v[214:215], 11, v[212:213]
	v_lshl_add_u64 v[214:215], v[214:215], 0, v[144:145]
	v_lshl_add_u64 v[152:153], v[214:215], 2, s[28:29]
	global_load_dwordx4 v[164:167], v[152:153], off
	global_load_dwordx4 v[168:171], v[152:153], off offset:64
	global_load_dwordx4 v[172:175], v[152:153], off offset:512
	global_load_dwordx4 v[176:179], v[152:153], off offset:576
	s_waitcnt vmcnt(22)
	v_add_u32_e32 v212, 0x80, v146
	v_mov_b32_e32 v213, v147
	v_lshlrev_b64 v[214:215], 11, v[212:213]
	v_lshl_add_u64 v[214:215], v[214:215], 0, v[144:145]
	v_lshl_add_u64 v[154:155], v[214:215], 2, s[28:29]
	v_lshl_add_u64 v[156:157], v[214:215], 1, s[40:41]
	v_lshl_add_u64 v[156:157], v[156:157], 0, v[224:225]
	v_pk_add_f32 v[62:63], v[62:63], v[182:183]
	v_pk_add_f32 v[60:61], v[60:61], v[180:181]
	v_cvt_pk_bf16_f32 v221, v62, v63
	v_cvt_pk_bf16_f32 v220, v60, v61
	global_store_dwordx4 v[154:155], v[60:63], off
	s_nop 1
	v_mul_f32_e32 v61, v61, v61
	v_mul_f32_e32 v63, v63, v63
	v_fmac_f32_e32 v61, v60, v60
	v_fmac_f32_e32 v63, v62, v62
	v_add_f32_e32 v160, v61, v63
	v_pk_add_f32 v[58:59], v[58:59], v[186:187]
	v_pk_add_f32 v[56:57], v[56:57], v[184:185]
	v_cvt_pk_bf16_f32 v223, v58, v59
	v_cvt_pk_bf16_f32 v222, v56, v57
	global_store_dwordx4 v[154:155], v[56:59], off offset:64
	s_nop 1
	v_mul_f32_e32 v57, v57, v57
	v_mul_f32_e32 v59, v59, v59
	v_fmac_f32_e32 v57, v56, v56
	v_fmac_f32_e32 v59, v58, v58
	v_add_f32_e32 v56, v57, v59
	v_add_f32_e32 v160, v160, v56
	v_permlane16_swap_b32_e32 v220, v222
	v_permlane16_swap_b32_e32 v221, v223
	global_store_dwordx4 v[156:157], v[220:223], off
	s_nop 0
	v_pk_add_f32 v[54:55], v[54:55], v[190:191]
	v_pk_add_f32 v[52:53], v[52:53], v[188:189]
	v_cvt_pk_bf16_f32 v221, v54, v55
	v_cvt_pk_bf16_f32 v220, v52, v53
	global_store_dwordx4 v[154:155], v[52:55], off offset:512
	s_nop 1
	v_mul_f32_e32 v53, v53, v53
	v_mul_f32_e32 v55, v55, v55
	v_fmac_f32_e32 v53, v52, v52
	v_fmac_f32_e32 v55, v54, v54
	v_add_f32_e32 v52, v53, v55
	v_add_f32_e32 v160, v160, v52
	v_pk_add_f32 v[50:51], v[50:51], v[194:195]
	v_pk_add_f32 v[48:49], v[48:49], v[192:193]
	v_cvt_pk_bf16_f32 v223, v50, v51
	v_cvt_pk_bf16_f32 v222, v48, v49
	global_store_dwordx4 v[154:155], v[48:51], off offset:576
	s_nop 1
	v_mul_f32_e32 v49, v49, v49
	v_mul_f32_e32 v51, v51, v51
	v_fmac_f32_e32 v49, v48, v48
	v_fmac_f32_e32 v51, v50, v50
	v_add_f32_e32 v48, v49, v51
	v_add_f32_e32 v160, v160, v48
	v_permlane16_swap_b32_e32 v220, v222
	v_permlane16_swap_b32_e32 v221, v223
	global_store_dwordx4 v[156:157], v[220:223], off offset:256
	s_nop 0
	v_mov_b32_e32 v161, v160
	s_nop 1
	v_permlane16_swap_b32_e32 v160, v161
	v_add_f32_e32 v160, v160, v161
	v_mov_b32_e32 v161, v160
	s_nop 1
	v_permlane32_swap_b32_e32 v160, v161
	s_and_saveexec_b64 s[24:25], s[8:9]
	v_lshl_add_u64 v[162:163], v[212:213], 2, s[64:65]
	v_add_f32_e32 v160, v160, v161
	global_atomic_add_f32 v[162:163], v160, off
	s_or_b64 exec, exec, s[24:25]
	v_add_u32_e32 v212, 0xb0, v146
	v_mov_b32_e32 v213, v147
	v_lshlrev_b64 v[214:215], 11, v[212:213]
	v_lshl_add_u64 v[214:215], v[214:215], 0, v[144:145]
	v_lshl_add_u64 v[152:153], v[214:215], 2, s[28:29]
	global_load_dwordx4 v[180:183], v[152:153], off
	global_load_dwordx4 v[184:187], v[152:153], off offset:64
	global_load_dwordx4 v[188:191], v[152:153], off offset:512
	global_load_dwordx4 v[192:195], v[152:153], off offset:576
	s_waitcnt vmcnt(22)
	v_add_u32_e32 v212, 0x90, v146
	v_mov_b32_e32 v213, v147
	v_lshlrev_b64 v[214:215], 11, v[212:213]
	v_lshl_add_u64 v[214:215], v[214:215], 0, v[144:145]
	v_lshl_add_u64 v[154:155], v[214:215], 2, s[28:29]
	v_lshl_add_u64 v[156:157], v[214:215], 1, s[40:41]
	v_lshl_add_u64 v[156:157], v[156:157], 0, v[224:225]
	v_pk_add_f32 v[46:47], v[46:47], v[198:199]
	v_pk_add_f32 v[44:45], v[44:45], v[196:197]
	v_cvt_pk_bf16_f32 v221, v46, v47
	v_cvt_pk_bf16_f32 v220, v44, v45
	global_store_dwordx4 v[154:155], v[44:47], off
	s_nop 1
	v_mul_f32_e32 v45, v45, v45
	v_mul_f32_e32 v47, v47, v47
	v_fmac_f32_e32 v45, v44, v44
	v_fmac_f32_e32 v47, v46, v46
	v_add_f32_e32 v160, v45, v47
	v_pk_add_f32 v[42:43], v[42:43], v[202:203]
	v_pk_add_f32 v[40:41], v[40:41], v[200:201]
	v_cvt_pk_bf16_f32 v223, v42, v43
	v_cvt_pk_bf16_f32 v222, v40, v41
	global_store_dwordx4 v[154:155], v[40:43], off offset:64
	s_nop 1
	v_mul_f32_e32 v41, v41, v41
	v_mul_f32_e32 v43, v43, v43
	v_fmac_f32_e32 v41, v40, v40
	v_fmac_f32_e32 v43, v42, v42
	v_add_f32_e32 v40, v41, v43
	v_add_f32_e32 v160, v160, v40
	v_permlane16_swap_b32_e32 v220, v222
	v_permlane16_swap_b32_e32 v221, v223
	global_store_dwordx4 v[156:157], v[220:223], off
	s_nop 0
	v_pk_add_f32 v[38:39], v[38:39], v[206:207]
	v_pk_add_f32 v[36:37], v[36:37], v[204:205]
	v_cvt_pk_bf16_f32 v221, v38, v39
	v_cvt_pk_bf16_f32 v220, v36, v37
	global_store_dwordx4 v[154:155], v[36:39], off offset:512
	s_nop 1
	v_mul_f32_e32 v37, v37, v37
	v_mul_f32_e32 v39, v39, v39
	v_fmac_f32_e32 v37, v36, v36
	v_fmac_f32_e32 v39, v38, v38
	v_add_f32_e32 v36, v37, v39
	v_add_f32_e32 v160, v160, v36
	v_pk_add_f32 v[34:35], v[34:35], v[210:211]
	v_pk_add_f32 v[32:33], v[32:33], v[208:209]
	v_cvt_pk_bf16_f32 v223, v34, v35
	v_cvt_pk_bf16_f32 v222, v32, v33
	global_store_dwordx4 v[154:155], v[32:35], off offset:576
	s_nop 1
	v_mul_f32_e32 v33, v33, v33
	v_mul_f32_e32 v35, v35, v35
	v_fmac_f32_e32 v33, v32, v32
	v_fmac_f32_e32 v35, v34, v34
	v_add_f32_e32 v32, v33, v35
	v_add_f32_e32 v160, v160, v32
	v_permlane16_swap_b32_e32 v220, v222
	v_permlane16_swap_b32_e32 v221, v223
	global_store_dwordx4 v[156:157], v[220:223], off offset:256
	s_nop 0
	v_mov_b32_e32 v161, v160
	s_nop 1
	v_permlane16_swap_b32_e32 v160, v161
	v_add_f32_e32 v160, v160, v161
	v_mov_b32_e32 v161, v160
	s_nop 1
	v_permlane32_swap_b32_e32 v160, v161
	s_and_saveexec_b64 s[24:25], s[8:9]
	v_lshl_add_u64 v[162:163], v[212:213], 2, s[64:65]
	v_add_f32_e32 v160, v160, v161
	global_atomic_add_f32 v[162:163], v160, off
	s_or_b64 exec, exec, s[24:25]
	s_waitcnt vmcnt(18)
	v_add_u32_e32 v212, 0xa0, v146
	v_mov_b32_e32 v213, v147
	v_lshlrev_b64 v[214:215], 11, v[212:213]
	v_lshl_add_u64 v[214:215], v[214:215], 0, v[144:145]
	v_lshl_add_u64 v[154:155], v[214:215], 2, s[28:29]
	v_lshl_add_u64 v[156:157], v[214:215], 1, s[40:41]
	v_lshl_add_u64 v[156:157], v[156:157], 0, v[224:225]
	v_pk_add_f32 v[30:31], v[30:31], v[166:167]
	v_pk_add_f32 v[28:29], v[28:29], v[164:165]
	v_cvt_pk_bf16_f32 v221, v30, v31
	v_cvt_pk_bf16_f32 v220, v28, v29
	global_store_dwordx4 v[154:155], v[28:31], off
	s_nop 1
	v_mul_f32_e32 v29, v29, v29
	v_mul_f32_e32 v31, v31, v31
	v_fmac_f32_e32 v29, v28, v28
	v_fmac_f32_e32 v31, v30, v30
	v_add_f32_e32 v160, v29, v31
	v_pk_add_f32 v[26:27], v[26:27], v[170:171]
	v_pk_add_f32 v[24:25], v[24:25], v[168:169]
	v_cvt_pk_bf16_f32 v223, v26, v27
	v_cvt_pk_bf16_f32 v222, v24, v25
	global_store_dwordx4 v[154:155], v[24:27], off offset:64
	s_nop 1
	v_mul_f32_e32 v25, v25, v25
	v_mul_f32_e32 v27, v27, v27
	v_fmac_f32_e32 v25, v24, v24
	v_fmac_f32_e32 v27, v26, v26
	v_add_f32_e32 v24, v25, v27
	v_add_f32_e32 v160, v160, v24
	v_permlane16_swap_b32_e32 v220, v222
	v_permlane16_swap_b32_e32 v221, v223
	global_store_dwordx4 v[156:157], v[220:223], off
	s_nop 0
	v_pk_add_f32 v[22:23], v[22:23], v[174:175]
	v_pk_add_f32 v[20:21], v[20:21], v[172:173]
	v_cvt_pk_bf16_f32 v221, v22, v23
	v_cvt_pk_bf16_f32 v220, v20, v21
	global_store_dwordx4 v[154:155], v[20:23], off offset:512
	s_nop 1
	v_mul_f32_e32 v21, v21, v21
	v_mul_f32_e32 v23, v23, v23
	v_fmac_f32_e32 v21, v20, v20
	v_fmac_f32_e32 v23, v22, v22
	v_add_f32_e32 v20, v21, v23
	v_add_f32_e32 v160, v160, v20
	v_pk_add_f32 v[18:19], v[18:19], v[178:179]
	v_pk_add_f32 v[16:17], v[16:17], v[176:177]
	v_cvt_pk_bf16_f32 v223, v18, v19
	v_cvt_pk_bf16_f32 v222, v16, v17
	global_store_dwordx4 v[154:155], v[16:19], off offset:576
	s_nop 1
	v_mul_f32_e32 v17, v17, v17
	v_mul_f32_e32 v19, v19, v19
	v_fmac_f32_e32 v17, v16, v16
	v_fmac_f32_e32 v19, v18, v18
	v_add_f32_e32 v16, v17, v19
	v_add_f32_e32 v160, v160, v16
	v_permlane16_swap_b32_e32 v220, v222
	v_permlane16_swap_b32_e32 v221, v223
	global_store_dwordx4 v[156:157], v[220:223], off offset:256
	s_nop 0
	v_mov_b32_e32 v161, v160
	s_nop 1
	v_permlane16_swap_b32_e32 v160, v161
	v_add_f32_e32 v160, v160, v161
	v_mov_b32_e32 v161, v160
	s_nop 1
	v_permlane32_swap_b32_e32 v160, v161
	s_and_saveexec_b64 s[24:25], s[8:9]
	v_lshl_add_u64 v[162:163], v[212:213], 2, s[64:65]
	v_add_f32_e32 v160, v160, v161
	global_atomic_add_f32 v[162:163], v160, off
	s_or_b64 exec, exec, s[24:25]
	s_waitcnt vmcnt(14)
	v_add_u32_e32 v212, 0xb0, v146
	v_mov_b32_e32 v213, v147
	v_lshlrev_b64 v[214:215], 11, v[212:213]
	v_lshl_add_u64 v[214:215], v[214:215], 0, v[144:145]
	v_lshl_add_u64 v[154:155], v[214:215], 2, s[28:29]
	v_lshl_add_u64 v[156:157], v[214:215], 1, s[40:41]
	v_lshl_add_u64 v[156:157], v[156:157], 0, v[224:225]
	v_pk_add_f32 v[14:15], v[14:15], v[182:183]
	v_pk_add_f32 v[12:13], v[12:13], v[180:181]
	v_cvt_pk_bf16_f32 v221, v14, v15
	v_cvt_pk_bf16_f32 v220, v12, v13
	global_store_dwordx4 v[154:155], v[12:15], off
	s_nop 1
	v_mul_f32_e32 v13, v13, v13
	v_mul_f32_e32 v15, v15, v15
	v_fmac_f32_e32 v13, v12, v12
	v_fmac_f32_e32 v15, v14, v14
	v_add_f32_e32 v160, v13, v15
	v_pk_add_f32 v[10:11], v[10:11], v[186:187]
	v_pk_add_f32 v[8:9], v[8:9], v[184:185]
	v_cvt_pk_bf16_f32 v223, v10, v11
	v_cvt_pk_bf16_f32 v222, v8, v9
	global_store_dwordx4 v[154:155], v[8:11], off offset:64
	s_nop 1
	v_mul_f32_e32 v9, v9, v9
	v_mul_f32_e32 v11, v11, v11
	v_fmac_f32_e32 v9, v8, v8
	v_fmac_f32_e32 v11, v10, v10
	v_add_f32_e32 v8, v9, v11
	v_add_f32_e32 v160, v160, v8
	v_permlane16_swap_b32_e32 v220, v222
	v_permlane16_swap_b32_e32 v221, v223
	global_store_dwordx4 v[156:157], v[220:223], off
	s_nop 0
	v_pk_add_f32 v[6:7], v[6:7], v[190:191]
	v_pk_add_f32 v[4:5], v[4:5], v[188:189]
	v_cvt_pk_bf16_f32 v221, v6, v7
	v_cvt_pk_bf16_f32 v220, v4, v5
	global_store_dwordx4 v[154:155], v[4:7], off offset:512
	s_nop 1
	v_mul_f32_e32 v5, v5, v5
	v_mul_f32_e32 v7, v7, v7
	v_fmac_f32_e32 v5, v4, v4
	v_fmac_f32_e32 v7, v6, v6
	v_add_f32_e32 v4, v5, v7
	v_add_f32_e32 v160, v160, v4
	v_pk_add_f32 v[2:3], v[2:3], v[194:195]
	v_pk_add_f32 v[0:1], v[0:1], v[192:193]
	v_cvt_pk_bf16_f32 v223, v2, v3
	v_cvt_pk_bf16_f32 v222, v0, v1
	global_store_dwordx4 v[154:155], v[0:3], off offset:576
	s_nop 1
	v_mul_f32_e32 v1, v1, v1
	v_mul_f32_e32 v3, v3, v3
	v_fmac_f32_e32 v1, v0, v0
	v_fmac_f32_e32 v3, v2, v2
	v_add_f32_e32 v0, v1, v3
	v_add_f32_e32 v160, v160, v0
	v_permlane16_swap_b32_e32 v220, v222
	v_permlane16_swap_b32_e32 v221, v223
	global_store_dwordx4 v[156:157], v[220:223], off offset:256
	s_nop 0
	v_mov_b32_e32 v161, v160
	s_nop 1
	v_permlane16_swap_b32_e32 v160, v161
	v_add_f32_e32 v160, v160, v161
	v_mov_b32_e32 v161, v160
	s_nop 1
	v_permlane32_swap_b32_e32 v160, v161
	s_and_saveexec_b64 s[24:25], s[8:9]
	v_lshl_add_u64 v[162:163], v[212:213], 2, s[64:65]
	v_add_f32_e32 v160, v160, v161
	global_atomic_add_f32 v[162:163], v160, off
	s_or_b64 exec, exec, s[24:25]
	s_branch .LBB0_522

.LBB0_1623:
	ds_read_b128 v[144:147], v148
	ds_read_b128 v[152:155], v148 offset:1024
	ds_read_b128 v[156:159], v148 offset:2048
	ds_read_b128 v[160:163], v148 offset:3072
	s_add_u32 s60, s58, 0x100
	s_addc_u32 s61, s59, 0
	s_cmp_eq_u32 s69, 28
	s_cselect_b32 s65, s17, s61
	s_cselect_b32 s64, s23, s60
	s_cselect_b32 s63, s15, s68
	s_cselect_b32 s62, s66, s67
	v_lshl_add_u64 v[196:197], s[58:59], 0, v[134:135]
	s_add_i32 m0, s26, 0xc000
	ds_read_b128 v[164:167], v149
	ds_read_b128 v[168:171], v149 offset:1024
	ds_read_b128 v[172:175], v149 offset:2048
	ds_read_b128 v[176:179], v149 offset:3072
	ds_read_b128 v[180:183], v149 offset:4096
	ds_read_b128 v[184:187], v149 offset:5120
	ds_read_b128 v[188:191], v149 offset:6144
	ds_read_b128 v[192:195], v149 offset:7168
	global_load_lds_dwordx4 v[196:197], off
	v_lshl_add_u64 v[196:197], s[58:59], 0, v[138:139]
	s_add_i32 m0, s26, 0xe000
	s_nop 0
	global_load_lds_dwordx4 v[196:197], off
	s_waitcnt lgkmcnt(8)
	s_barrier
	s_waitcnt lgkmcnt(0)
	s_setprio 1
	s_waitcnt lgkmcnt(0)
	v_mfma_f32_16x16x32_bf16 v[124:127], v[144:147], v[164:167], v[124:127]
	v_mfma_f32_16x16x32_bf16 v[120:123], v[156:159], v[164:167], v[120:123]
	v_mfma_f32_16x16x32_bf16 v[108:111], v[144:147], v[172:175], v[108:111]
	v_mfma_f32_16x16x32_bf16 v[104:107], v[156:159], v[172:175], v[104:107]
	v_mfma_f32_16x16x32_bf16 v[92:95], v[144:147], v[180:183], v[92:95]
	v_mfma_f32_16x16x32_bf16 v[88:91], v[156:159], v[180:183], v[88:91]
	v_mfma_f32_16x16x32_bf16 v[76:79], v[144:147], v[188:191], v[76:79]
	v_mfma_f32_16x16x32_bf16 v[72:75], v[156:159], v[188:191], v[72:75]
	v_mfma_f32_16x16x32_bf16 v[124:127], v[152:155], v[168:171], v[124:127]
	v_mfma_f32_16x16x32_bf16 v[120:123], v[160:163], v[168:171], v[120:123]
	v_mfma_f32_16x16x32_bf16 v[108:111], v[152:155], v[176:179], v[108:111]
	v_mfma_f32_16x16x32_bf16 v[104:107], v[160:163], v[176:179], v[104:107]
	v_mfma_f32_16x16x32_bf16 v[92:95], v[152:155], v[184:187], v[92:95]
	v_mfma_f32_16x16x32_bf16 v[88:91], v[160:163], v[184:187], v[88:91]
	v_mfma_f32_16x16x32_bf16 v[76:79], v[152:155], v[192:195], v[76:79]
	v_mfma_f32_16x16x32_bf16 v[72:75], v[160:163], v[192:195], v[72:75]
	s_setprio 0
	s_barrier
	s_add_i32 s58, s55, s7
	v_lshl_add_u64 v[212:213], s[62:63], 0, v[128:129]
	s_mov_b32 m0, s58
	ds_read_b128 v[196:199], v150
	ds_read_b128 v[200:203], v150 offset:1024
	ds_read_b128 v[204:207], v150 offset:2048
	ds_read_b128 v[208:211], v150 offset:3072
	global_load_lds_dwordx4 v[212:213], off
	v_lshl_add_u64 v[214:215], s[62:63], 0, v[130:131]
	s_add_i32 m0, s58, 0x2000
	s_nop 0
	global_load_lds_dwordx4 v[214:215], off
	s_barrier
	s_waitcnt lgkmcnt(0)
	s_setprio 1
	s_waitcnt lgkmcnt(0)
	v_mfma_f32_16x16x32_bf16 v[116:119], v[196:199], v[164:167], v[116:119]
	v_mfma_f32_16x16x32_bf16 v[112:115], v[204:207], v[164:167], v[112:115]
	v_mfma_f32_16x16x32_bf16 v[100:103], v[196:199], v[172:175], v[100:103]
	v_mfma_f32_16x16x32_bf16 v[96:99], v[204:207], v[172:175], v[96:99]
	v_mfma_f32_16x16x32_bf16 v[84:87], v[196:199], v[180:183], v[84:87]
	v_mfma_f32_16x16x32_bf16 v[80:83], v[204:207], v[180:183], v[80:83]
	v_mfma_f32_16x16x32_bf16 v[68:71], v[196:199], v[188:191], v[68:71]
	v_mfma_f32_16x16x32_bf16 v[64:67], v[204:207], v[188:191], v[64:67]
	v_mfma_f32_16x16x32_bf16 v[116:119], v[200:203], v[168:171], v[116:119]
	v_mfma_f32_16x16x32_bf16 v[112:115], v[208:211], v[168:171], v[112:115]
	v_mfma_f32_16x16x32_bf16 v[100:103], v[200:203], v[176:179], v[100:103]
	v_mfma_f32_16x16x32_bf16 v[96:99], v[208:211], v[176:179], v[96:99]
	v_mfma_f32_16x16x32_bf16 v[84:87], v[200:203], v[184:187], v[84:87]
	v_mfma_f32_16x16x32_bf16 v[80:83], v[208:211], v[184:187], v[80:83]
	v_mfma_f32_16x16x32_bf16 v[68:71], v[200:203], v[192:195], v[68:71]
	v_mfma_f32_16x16x32_bf16 v[64:67], v[208:211], v[192:195], v[64:67]
	s_setprio 0
	s_mov_b32 m0, s26
	v_lshl_add_u64 v[216:217], s[64:65], 0, v[128:129]
	s_barrier
	ds_read_b128 v[164:167], v149 offset:16384
	ds_read_b128 v[168:171], v149 offset:17408
	ds_read_b128 v[172:175], v149 offset:18432
	ds_read_b128 v[176:179], v149 offset:19456
	ds_read_b128 v[180:183], v149 offset:20480
	ds_read_b128 v[184:187], v149 offset:21504
	ds_read_b128 v[188:191], v149 offset:22528
	ds_read_b128 v[192:195], v149 offset:23552
	global_load_lds_dwordx4 v[216:217], off
	v_lshl_add_u64 v[218:219], s[64:65], 0, v[130:131]
	s_mov_b32 m0, s27
	s_nop 0
	global_load_lds_dwordx4 v[218:219], off
	s_barrier
	s_waitcnt lgkmcnt(0)
	s_setprio 1
	s_waitcnt lgkmcnt(0)
	v_mfma_f32_16x16x32_bf16 v[60:63], v[144:147], v[164:167], v[60:63]
	v_mfma_f32_16x16x32_bf16 v[56:59], v[156:159], v[164:167], v[56:59]
	v_mfma_f32_16x16x32_bf16 v[44:47], v[144:147], v[172:175], v[44:47]
	v_mfma_f32_16x16x32_bf16 v[40:43], v[156:159], v[172:175], v[40:43]
	v_mfma_f32_16x16x32_bf16 v[28:31], v[144:147], v[180:183], v[28:31]
	v_mfma_f32_16x16x32_bf16 v[24:27], v[156:159], v[180:183], v[24:27]
	v_mfma_f32_16x16x32_bf16 v[12:15], v[144:147], v[188:191], v[12:15]
	v_mfma_f32_16x16x32_bf16 v[8:11], v[156:159], v[188:191], v[8:11]
	v_mfma_f32_16x16x32_bf16 v[60:63], v[152:155], v[168:171], v[60:63]
	v_mfma_f32_16x16x32_bf16 v[56:59], v[160:163], v[168:171], v[56:59]
	v_mfma_f32_16x16x32_bf16 v[44:47], v[152:155], v[176:179], v[44:47]
	v_mfma_f32_16x16x32_bf16 v[40:43], v[160:163], v[176:179], v[40:43]
	v_mfma_f32_16x16x32_bf16 v[28:31], v[152:155], v[184:187], v[28:31]
	v_mfma_f32_16x16x32_bf16 v[24:27], v[160:163], v[184:187], v[24:27]
	v_mfma_f32_16x16x32_bf16 v[12:15], v[152:155], v[192:195], v[12:15]
	v_mfma_f32_16x16x32_bf16 v[8:11], v[160:163], v[192:195], v[8:11]
	s_setprio 0
	s_barrier
	s_add_u32 s58, s62, 0x80000
	s_addc_u32 s59, s63, 0
	s_add_i32 s70, s57, s7
	v_lshl_add_u64 v[144:145], s[58:59], 0, v[128:129]
	s_mov_b32 m0, s70
	s_nop 0
	global_load_lds_dwordx4 v[144:145], off
	v_lshl_add_u64 v[144:145], s[58:59], 0, v[130:131]
	s_add_i32 m0, s70, 0x2000
	s_nop 0
	global_load_lds_dwordx4 v[144:145], off
	s_waitcnt vmcnt(6)
	s_barrier
	s_setprio 1
	v_mfma_f32_16x16x32_bf16 v[52:55], v[196:199], v[164:167], v[52:55]
	v_mfma_f32_16x16x32_bf16 v[48:51], v[204:207], v[164:167], v[48:51]
	v_mfma_f32_16x16x32_bf16 v[36:39], v[196:199], v[172:175], v[36:39]
	v_mfma_f32_16x16x32_bf16 v[32:35], v[204:207], v[172:175], v[32:35]
	v_mfma_f32_16x16x32_bf16 v[20:23], v[196:199], v[180:183], v[20:23]
	v_mfma_f32_16x16x32_bf16 v[16:19], v[204:207], v[180:183], v[16:19]
	v_mfma_f32_16x16x32_bf16 v[4:7], v[196:199], v[188:191], v[4:7]
	v_mfma_f32_16x16x32_bf16 v[0:3], v[204:207], v[188:191], v[0:3]
	v_mfma_f32_16x16x32_bf16 v[52:55], v[200:203], v[168:171], v[52:55]
	v_mfma_f32_16x16x32_bf16 v[48:51], v[208:211], v[168:171], v[48:51]
	v_mfma_f32_16x16x32_bf16 v[36:39], v[200:203], v[176:179], v[36:39]
	v_mfma_f32_16x16x32_bf16 v[32:35], v[208:211], v[176:179], v[32:35]
	v_mfma_f32_16x16x32_bf16 v[20:23], v[200:203], v[184:187], v[20:23]
	v_mfma_f32_16x16x32_bf16 v[16:19], v[208:211], v[184:187], v[16:19]
	v_mfma_f32_16x16x32_bf16 v[4:7], v[200:203], v[192:195], v[4:7]
	v_mfma_f32_16x16x32_bf16 v[0:3], v[208:211], v[192:195], v[0:3]
	s_setprio 0
	s_add_i32 s70, 16, 0x18000
	v_add_u32_e32 v151, s70, v137
	s_barrier
	ds_read_b128 v[144:147], v151
	ds_read_b128 v[152:155], v151 offset:1024
	ds_read_b128 v[156:159], v151 offset:2048
	ds_read_b128 v[160:163], v151 offset:3072
	s_add_u32 s58, s64, 0x80000
	s_addc_u32 s59, s65, 0
	s_mov_b32 m0, s39
	v_lshl_add_u64 v[196:197], s[58:59], 0, v[128:129]
	ds_read_b128 v[164:167], v149 offset:32768
	ds_read_b128 v[168:171], v149 offset:33792
	ds_read_b128 v[172:175], v149 offset:34816
	ds_read_b128 v[176:179], v149 offset:35840
	ds_read_b128 v[180:183], v149 offset:36864
	ds_read_b128 v[184:187], v149 offset:37888
	ds_read_b128 v[188:191], v149 offset:38912
	ds_read_b128 v[192:195], v149 offset:39936
	global_load_lds_dwordx4 v[196:197], off
	v_lshl_add_u64 v[196:197], s[58:59], 0, v[130:131]
	s_mov_b32 m0, s44
	s_nop 0
	global_load_lds_dwordx4 v[196:197], off
	s_waitcnt lgkmcnt(8)
	s_barrier
	s_waitcnt lgkmcnt(0)
	s_setprio 1
	s_waitcnt lgkmcnt(0)
	v_mfma_f32_16x16x32_bf16 v[124:127], v[144:147], v[164:167], v[124:127]
	v_mfma_f32_16x16x32_bf16 v[120:123], v[156:159], v[164:167], v[120:123]
	v_mfma_f32_16x16x32_bf16 v[108:111], v[144:147], v[172:175], v[108:111]
	v_mfma_f32_16x16x32_bf16 v[104:107], v[156:159], v[172:175], v[104:107]
	v_mfma_f32_16x16x32_bf16 v[92:95], v[144:147], v[180:183], v[92:95]
	v_mfma_f32_16x16x32_bf16 v[88:91], v[156:159], v[180:183], v[88:91]
	v_mfma_f32_16x16x32_bf16 v[76:79], v[144:147], v[188:191], v[76:79]
	v_mfma_f32_16x16x32_bf16 v[72:75], v[156:159], v[188:191], v[72:75]
	v_mfma_f32_16x16x32_bf16 v[124:127], v[152:155], v[168:171], v[124:127]
	v_mfma_f32_16x16x32_bf16 v[120:123], v[160:163], v[168:171], v[120:123]
	v_mfma_f32_16x16x32_bf16 v[108:111], v[152:155], v[176:179], v[108:111]
	v_mfma_f32_16x16x32_bf16 v[104:107], v[160:163], v[176:179], v[104:107]
	v_mfma_f32_16x16x32_bf16 v[92:95], v[152:155], v[184:187], v[92:95]
	v_mfma_f32_16x16x32_bf16 v[88:91], v[160:163], v[184:187], v[88:91]
	v_mfma_f32_16x16x32_bf16 v[76:79], v[152:155], v[192:195], v[76:79]
	v_mfma_f32_16x16x32_bf16 v[72:75], v[160:163], v[192:195], v[72:75]
	s_setprio 0
	s_barrier
	s_add_i32 s64, 16, 0x1c000
	s_add_i32 s58, s70, s7
	v_add_u32_e32 v151, s64, v137
	v_lshl_add_u64 v[212:213], v[212:213], 0, s[12:13]
	s_mov_b32 m0, s58
	ds_read_b128 v[196:199], v151
	ds_read_b128 v[200:203], v151 offset:1024
	ds_read_b128 v[204:207], v151 offset:2048
	ds_read_b128 v[208:211], v151 offset:3072
	global_load_lds_dwordx4 v[212:213], off
	v_lshl_add_u64 v[212:213], v[214:215], 0, s[12:13]
	s_add_i32 m0, s58, 0x2000
	s_nop 0
	global_load_lds_dwordx4 v[212:213], off
	s_barrier
	s_waitcnt lgkmcnt(0)
	s_setprio 1
	s_waitcnt lgkmcnt(0)
	v_mfma_f32_16x16x32_bf16 v[116:119], v[196:199], v[164:167], v[116:119]
	v_mfma_f32_16x16x32_bf16 v[112:115], v[204:207], v[164:167], v[112:115]
	v_mfma_f32_16x16x32_bf16 v[100:103], v[196:199], v[172:175], v[100:103]
	v_mfma_f32_16x16x32_bf16 v[96:99], v[204:207], v[172:175], v[96:99]
	v_mfma_f32_16x16x32_bf16 v[84:87], v[196:199], v[180:183], v[84:87]
	v_mfma_f32_16x16x32_bf16 v[80:83], v[204:207], v[180:183], v[80:83]
	v_mfma_f32_16x16x32_bf16 v[68:71], v[196:199], v[188:191], v[68:71]
	v_mfma_f32_16x16x32_bf16 v[64:67], v[204:207], v[188:191], v[64:67]
	v_mfma_f32_16x16x32_bf16 v[116:119], v[200:203], v[168:171], v[116:119]
	v_mfma_f32_16x16x32_bf16 v[112:115], v[208:211], v[168:171], v[112:115]
	v_mfma_f32_16x16x32_bf16 v[100:103], v[200:203], v[176:179], v[100:103]
	v_mfma_f32_16x16x32_bf16 v[96:99], v[208:211], v[176:179], v[96:99]
	v_mfma_f32_16x16x32_bf16 v[84:87], v[200:203], v[184:187], v[84:87]
	v_mfma_f32_16x16x32_bf16 v[80:83], v[208:211], v[184:187], v[80:83]
	v_mfma_f32_16x16x32_bf16 v[68:71], v[200:203], v[192:195], v[68:71]
	v_mfma_f32_16x16x32_bf16 v[64:67], v[208:211], v[192:195], v[64:67]
	s_setprio 0
	s_mov_b32 m0, s45
	v_lshl_add_u64 v[212:213], v[216:217], 0, s[12:13]
	s_barrier
	ds_read_b128 v[164:167], v149 offset:49152
	ds_read_b128 v[168:171], v149 offset:50176
	ds_read_b128 v[172:175], v149 offset:51200
	ds_read_b128 v[176:179], v149 offset:52224
	ds_read_b128 v[180:183], v149 offset:53248
	ds_read_b128 v[184:187], v149 offset:54272
	ds_read_b128 v[188:191], v149 offset:55296
	ds_read_b128 v[192:195], v149 offset:56320
	global_load_lds_dwordx4 v[212:213], off
	v_lshl_add_u64 v[212:213], v[218:219], 0, s[12:13]
	s_mov_b32 m0, s46
	s_nop 0
	global_load_lds_dwordx4 v[212:213], off
	s_barrier
	s_waitcnt lgkmcnt(0)
	s_setprio 1
	s_waitcnt lgkmcnt(0)
	v_mfma_f32_16x16x32_bf16 v[60:63], v[144:147], v[164:167], v[60:63]
	v_mfma_f32_16x16x32_bf16 v[56:59], v[156:159], v[164:167], v[56:59]
	v_mfma_f32_16x16x32_bf16 v[44:47], v[144:147], v[172:175], v[44:47]
	v_mfma_f32_16x16x32_bf16 v[40:43], v[156:159], v[172:175], v[40:43]
	v_mfma_f32_16x16x32_bf16 v[28:31], v[144:147], v[180:183], v[28:31]
	v_mfma_f32_16x16x32_bf16 v[24:27], v[156:159], v[180:183], v[24:27]
	v_mfma_f32_16x16x32_bf16 v[12:15], v[144:147], v[188:191], v[12:15]
	v_mfma_f32_16x16x32_bf16 v[8:11], v[156:159], v[188:191], v[8:11]
	v_mfma_f32_16x16x32_bf16 v[60:63], v[152:155], v[168:171], v[60:63]
	v_mfma_f32_16x16x32_bf16 v[56:59], v[160:163], v[168:171], v[56:59]
	v_mfma_f32_16x16x32_bf16 v[44:47], v[152:155], v[176:179], v[44:47]
	v_mfma_f32_16x16x32_bf16 v[40:43], v[160:163], v[176:179], v[40:43]
	v_mfma_f32_16x16x32_bf16 v[28:31], v[152:155], v[184:187], v[28:31]
	v_mfma_f32_16x16x32_bf16 v[24:27], v[160:163], v[184:187], v[24:27]
	v_mfma_f32_16x16x32_bf16 v[12:15], v[152:155], v[192:195], v[12:15]
	v_mfma_f32_16x16x32_bf16 v[8:11], v[160:163], v[192:195], v[8:11]
	s_setprio 0
	s_barrier
	s_add_u32 s58, s62, 0x80080
	s_addc_u32 s59, s63, 0
	s_add_i32 s62, s64, s7
	v_lshl_add_u64 v[144:145], s[58:59], 0, v[128:129]
	s_mov_b32 m0, s62
	s_nop 0
	global_load_lds_dwordx4 v[144:145], off
	v_lshl_add_u64 v[144:145], s[58:59], 0, v[130:131]
	s_add_i32 m0, s62, 0x2000
	s_nop 0
	global_load_lds_dwordx4 v[144:145], off
	s_waitcnt vmcnt(6)
	s_barrier
	s_setprio 1
	v_mfma_f32_16x16x32_bf16 v[52:55], v[196:199], v[164:167], v[52:55]
	v_mfma_f32_16x16x32_bf16 v[48:51], v[204:207], v[164:167], v[48:51]
	v_mfma_f32_16x16x32_bf16 v[36:39], v[196:199], v[172:175], v[36:39]
	v_mfma_f32_16x16x32_bf16 v[32:35], v[204:207], v[172:175], v[32:35]
	v_mfma_f32_16x16x32_bf16 v[20:23], v[196:199], v[180:183], v[20:23]
	v_mfma_f32_16x16x32_bf16 v[16:19], v[204:207], v[180:183], v[16:19]
	v_mfma_f32_16x16x32_bf16 v[4:7], v[196:199], v[188:191], v[4:7]
	v_mfma_f32_16x16x32_bf16 v[0:3], v[204:207], v[188:191], v[0:3]
	v_mfma_f32_16x16x32_bf16 v[52:55], v[200:203], v[168:171], v[52:55]
	v_mfma_f32_16x16x32_bf16 v[48:51], v[208:211], v[168:171], v[48:51]
	v_mfma_f32_16x16x32_bf16 v[36:39], v[200:203], v[176:179], v[36:39]
	v_mfma_f32_16x16x32_bf16 v[32:35], v[208:211], v[176:179], v[32:35]
	v_mfma_f32_16x16x32_bf16 v[20:23], v[200:203], v[184:187], v[20:23]
	v_mfma_f32_16x16x32_bf16 v[16:19], v[208:211], v[184:187], v[16:19]
	v_mfma_f32_16x16x32_bf16 v[4:7], v[200:203], v[192:195], v[4:7]
	v_mfma_f32_16x16x32_bf16 v[0:3], v[208:211], v[192:195], v[0:3]
	s_setprio 0
	s_add_i32 s69, s69, 2
	s_add_u32 s67, s67, 0x100
	s_addc_u32 s68, s68, 0
	s_cmp_gt_u32 s69, 29
	s_mov_b64 s[58:59], s[60:61]
	s_barrier
	s_cbranch_scc0 .LBB0_1623
	v_lshl_add_u32 v146, s22, 8, v133
	s_lshl_b32 s15, s56, 8
	s_ashr_i32 s17, s15, 31
	v_ashrrev_i32_e32 v147, 31, v146
	v_mov_b32_e32 v145, s17
	v_or_b32_e32 v144, s15, v132
	v_bfe_u32 v224, v136, 4, 1
	v_mul_u32_u24_e32 v224, 24, v224
	v_mov_b32_e32 v225, 0
	v_mov_b32_e32 v212, v146
	v_mov_b32_e32 v213, v147
	v_lshlrev_b64 v[214:215], 11, v[212:213]
	v_lshl_add_u64 v[214:215], v[214:215], 0, v[144:145]
	v_lshl_add_u64 v[152:153], v[214:215], 2, s[28:29]
	global_load_dwordx4 v[164:167], v[152:153], off
	global_load_dwordx4 v[168:171], v[152:153], off offset:64
	global_load_dwordx4 v[172:175], v[152:153], off offset:512
	global_load_dwordx4 v[176:179], v[152:153], off offset:576
	v_add_u32_e32 v212, 0x10, v146
	v_mov_b32_e32 v213, v147
	v_lshlrev_b64 v[214:215], 11, v[212:213]
	v_lshl_add_u64 v[214:215], v[214:215], 0, v[144:145]
	v_lshl_add_u64 v[152:153], v[214:215], 2, s[28:29]
	global_load_dwordx4 v[180:183], v[152:153], off
	global_load_dwordx4 v[184:187], v[152:153], off offset:64
	global_load_dwordx4 v[188:191], v[152:153], off offset:512
	global_load_dwordx4 v[192:195], v[152:153], off offset:576
	v_add_u32_e32 v212, 0x20, v146
	v_mov_b32_e32 v213, v147
	v_lshlrev_b64 v[214:215], 11, v[212:213]
	v_lshl_add_u64 v[214:215], v[214:215], 0, v[144:145]
	v_lshl_add_u64 v[152:153], v[214:215], 2, s[28:29]
	global_load_dwordx4 v[196:199], v[152:153], off
	global_load_dwordx4 v[200:203], v[152:153], off offset:64
	global_load_dwordx4 v[204:207], v[152:153], off offset:512
	global_load_dwordx4 v[208:211], v[152:153], off offset:576
	s_waitcnt vmcnt(8)
	v_mov_b32_e32 v212, v146
	v_mov_b32_e32 v213, v147
	v_lshlrev_b64 v[214:215], 11, v[212:213]
	v_lshl_add_u64 v[214:215], v[214:215], 0, v[144:145]
	v_lshl_add_u64 v[154:155], v[214:215], 2, s[28:29]
	v_lshl_add_u64 v[156:157], v[214:215], 1, s[40:41]
	v_lshl_add_u64 v[156:157], v[156:157], 0, v[224:225]
	v_pk_add_f32 v[126:127], v[126:127], v[166:167]
	v_pk_add_f32 v[124:125], v[124:125], v[164:165]
	v_cvt_pk_bf16_f32 v221, v126, v127
	v_cvt_pk_bf16_f32 v220, v124, v125
	global_store_dwordx4 v[154:155], v[124:127], off
	s_nop 1
	v_mul_f32_e32 v125, v125, v125
	v_mul_f32_e32 v127, v127, v127
	v_fmac_f32_e32 v125, v124, v124
	v_fmac_f32_e32 v127, v126, v126
	v_add_f32_e32 v160, v125, v127
	v_pk_add_f32 v[122:123], v[122:123], v[170:171]
	v_pk_add_f32 v[120:121], v[120:121], v[168:169]
	v_cvt_pk_bf16_f32 v223, v122, v123
	v_cvt_pk_bf16_f32 v222, v120, v121
	global_store_dwordx4 v[154:155], v[120:123], off offset:64
	s_nop 1
	v_mul_f32_e32 v121, v121, v121
	v_mul_f32_e32 v123, v123, v123
	v_fmac_f32_e32 v121, v120, v120
	v_fmac_f32_e32 v123, v122, v122
	v_add_f32_e32 v120, v121, v123
	v_add_f32_e32 v160, v160, v120
	v_permlane16_swap_b32_e32 v220, v222
	v_permlane16_swap_b32_e32 v221, v223
	global_store_dwordx4 v[156:157], v[220:223], off
	s_nop 0
	v_pk_add_f32 v[118:119], v[118:119], v[174:175]
	v_pk_add_f32 v[116:117], v[116:117], v[172:173]
	v_cvt_pk_bf16_f32 v221, v118, v119
	v_cvt_pk_bf16_f32 v220, v116, v117
	global_store_dwordx4 v[154:155], v[116:119], off offset:512
	s_nop 1
	v_mul_f32_e32 v117, v117, v117
	v_mul_f32_e32 v119, v119, v119
	v_fmac_f32_e32 v117, v116, v116
	v_fmac_f32_e32 v119, v118, v118
	v_add_f32_e32 v116, v117, v119
	v_add_f32_e32 v160, v160, v116
	v_pk_add_f32 v[114:115], v[114:115], v[178:179]
	v_pk_add_f32 v[112:113], v[112:113], v[176:177]
	v_cvt_pk_bf16_f32 v223, v114, v115
	v_cvt_pk_bf16_f32 v222, v112, v113
	global_store_dwordx4 v[154:155], v[112:115], off offset:576
	s_nop 1
	v_mul_f32_e32 v113, v113, v113
	v_mul_f32_e32 v115, v115, v115
	v_fmac_f32_e32 v113, v112, v112
	v_fmac_f32_e32 v115, v114, v114
	v_add_f32_e32 v112, v113, v115
	v_add_f32_e32 v160, v160, v112
	v_permlane16_swap_b32_e32 v220, v222
	v_permlane16_swap_b32_e32 v221, v223
	global_store_dwordx4 v[156:157], v[220:223], off offset:256
	s_nop 0
	v_mov_b32_e32 v161, v160
	s_nop 1
	v_permlane16_swap_b32_e32 v160, v161
	v_add_f32_e32 v160, v160, v161
	v_mov_b32_e32 v161, v160
	s_nop 1
	v_permlane32_swap_b32_e32 v160, v161
	s_and_saveexec_b64 s[22:23], s[8:9]
	v_lshl_add_u64 v[162:163], v[212:213], 2, s[52:53]
	v_add_f32_e32 v160, v160, v161
	global_atomic_add_f32 v[162:163], v160, off
	s_or_b64 exec, exec, s[22:23]
	v_add_u32_e32 v212, 0x30, v146
	v_mov_b32_e32 v213, v147
	v_lshlrev_b64 v[214:215], 11, v[212:213]
	v_lshl_add_u64 v[214:215], v[214:215], 0, v[144:145]
	v_lshl_add_u64 v[152:153], v[214:215], 2, s[28:29]
	global_load_dwordx4 v[164:167], v[152:153], off
	global_load_dwordx4 v[168:171], v[152:153], off offset:64
	global_load_dwordx4 v[172:175], v[152:153], off offset:512
	global_load_dwordx4 v[176:179], v[152:153], off offset:576
	s_waitcnt vmcnt(15)
	v_add_u32_e32 v212, 0x10, v146
	v_mov_b32_e32 v213, v147
	v_lshlrev_b64 v[214:215], 11, v[212:213]
	v_lshl_add_u64 v[214:215], v[214:215], 0, v[144:145]
	v_lshl_add_u64 v[154:155], v[214:215], 2, s[28:29]
	v_lshl_add_u64 v[156:157], v[214:215], 1, s[40:41]
	v_lshl_add_u64 v[156:157], v[156:157], 0, v[224:225]
	v_pk_add_f32 v[110:111], v[110:111], v[182:183]
	v_pk_add_f32 v[108:109], v[108:109], v[180:181]
	v_cvt_pk_bf16_f32 v221, v110, v111
	v_cvt_pk_bf16_f32 v220, v108, v109
	global_store_dwordx4 v[154:155], v[108:111], off
	s_nop 1
	v_mul_f32_e32 v109, v109, v109
	v_mul_f32_e32 v111, v111, v111
	v_fmac_f32_e32 v109, v108, v108
	v_fmac_f32_e32 v111, v110, v110
	v_add_f32_e32 v160, v109, v111
	v_pk_add_f32 v[106:107], v[106:107], v[186:187]
	v_pk_add_f32 v[104:105], v[104:105], v[184:185]
	v_cvt_pk_bf16_f32 v223, v106, v107
	v_cvt_pk_bf16_f32 v222, v104, v105
	global_store_dwordx4 v[154:155], v[104:107], off offset:64
	s_nop 1
	v_mul_f32_e32 v105, v105, v105
	v_mul_f32_e32 v107, v107, v107
	v_fmac_f32_e32 v105, v104, v104
	v_fmac_f32_e32 v107, v106, v106
	v_add_f32_e32 v104, v105, v107
	v_add_f32_e32 v160, v160, v104
	v_permlane16_swap_b32_e32 v220, v222
	v_permlane16_swap_b32_e32 v221, v223
	global_store_dwordx4 v[156:157], v[220:223], off
	s_nop 0
	v_pk_add_f32 v[102:103], v[102:103], v[190:191]
	v_pk_add_f32 v[100:101], v[100:101], v[188:189]
	v_cvt_pk_bf16_f32 v221, v102, v103
	v_cvt_pk_bf16_f32 v220, v100, v101
	global_store_dwordx4 v[154:155], v[100:103], off offset:512
	s_nop 1
	v_mul_f32_e32 v101, v101, v101
	v_mul_f32_e32 v103, v103, v103
	v_fmac_f32_e32 v101, v100, v100
	v_fmac_f32_e32 v103, v102, v102
	v_add_f32_e32 v100, v101, v103
	v_add_f32_e32 v160, v160, v100
	v_pk_add_f32 v[98:99], v[98:99], v[194:195]
	v_pk_add_f32 v[96:97], v[96:97], v[192:193]
	v_cvt_pk_bf16_f32 v223, v98, v99
	v_cvt_pk_bf16_f32 v222, v96, v97
	global_store_dwordx4 v[154:155], v[96:99], off offset:576
	s_nop 1
	v_mul_f32_e32 v97, v97, v97
	v_mul_f32_e32 v99, v99, v99
	v_fmac_f32_e32 v97, v96, v96
	v_fmac_f32_e32 v99, v98, v98
	v_add_f32_e32 v96, v97, v99
	v_add_f32_e32 v160, v160, v96
	v_permlane16_swap_b32_e32 v220, v222
	v_permlane16_swap_b32_e32 v221, v223
	global_store_dwordx4 v[156:157], v[220:223], off offset:256
	s_nop 0
	v_mov_b32_e32 v161, v160
	s_nop 1
	v_permlane16_swap_b32_e32 v160, v161
	v_add_f32_e32 v160, v160, v161
	v_mov_b32_e32 v161, v160
	s_nop 1
	v_permlane32_swap_b32_e32 v160, v161
	s_and_saveexec_b64 s[22:23], s[8:9]
	v_lshl_add_u64 v[162:163], v[212:213], 2, s[52:53]
	v_add_f32_e32 v160, v160, v161
	global_atomic_add_f32 v[162:163], v160, off
	s_or_b64 exec, exec, s[22:23]
	v_add_u32_e32 v212, 0x80, v146
	v_mov_b32_e32 v213, v147
	v_lshlrev_b64 v[214:215], 11, v[212:213]
	v_lshl_add_u64 v[214:215], v[214:215], 0, v[144:145]
	v_lshl_add_u64 v[152:153], v[214:215], 2, s[28:29]
	global_load_dwordx4 v[180:183], v[152:153], off
	global_load_dwordx4 v[184:187], v[152:153], off offset:64
	global_load_dwordx4 v[188:191], v[152:153], off offset:512
	global_load_dwordx4 v[192:195], v[152:153], off offset:576
	s_waitcnt vmcnt(22)
	v_add_u32_e32 v212, 0x20, v146
	v_mov_b32_e32 v213, v147
	v_lshlrev_b64 v[214:215], 11, v[212:213]
	v_lshl_add_u64 v[214:215], v[214:215], 0, v[144:145]
	v_lshl_add_u64 v[154:155], v[214:215], 2, s[28:29]
	v_lshl_add_u64 v[156:157], v[214:215], 1, s[40:41]
	v_lshl_add_u64 v[156:157], v[156:157], 0, v[224:225]
	v_pk_add_f32 v[94:95], v[94:95], v[198:199]
	v_pk_add_f32 v[92:93], v[92:93], v[196:197]
	v_cvt_pk_bf16_f32 v221, v94, v95
	v_cvt_pk_bf16_f32 v220, v92, v93
	global_store_dwordx4 v[154:155], v[92:95], off
	s_nop 1
	v_mul_f32_e32 v93, v93, v93
	v_mul_f32_e32 v95, v95, v95
	v_fmac_f32_e32 v93, v92, v92
	v_fmac_f32_e32 v95, v94, v94
	v_add_f32_e32 v160, v93, v95
	v_pk_add_f32 v[90:91], v[90:91], v[202:203]
	v_pk_add_f32 v[88:89], v[88:89], v[200:201]
	v_cvt_pk_bf16_f32 v223, v90, v91
	v_cvt_pk_bf16_f32 v222, v88, v89
	global_store_dwordx4 v[154:155], v[88:91], off offset:64
	s_nop 1
	v_mul_f32_e32 v89, v89, v89
	v_mul_f32_e32 v91, v91, v91
	v_fmac_f32_e32 v89, v88, v88
	v_fmac_f32_e32 v91, v90, v90
	v_add_f32_e32 v88, v89, v91
	v_add_f32_e32 v160, v160, v88
	v_permlane16_swap_b32_e32 v220, v222
	v_permlane16_swap_b32_e32 v221, v223
	global_store_dwordx4 v[156:157], v[220:223], off
	s_nop 0
	v_pk_add_f32 v[86:87], v[86:87], v[206:207]
	v_pk_add_f32 v[84:85], v[84:85], v[204:205]
	v_cvt_pk_bf16_f32 v221, v86, v87
	v_cvt_pk_bf16_f32 v220, v84, v85
	global_store_dwordx4 v[154:155], v[84:87], off offset:512
	s_nop 1
	v_mul_f32_e32 v85, v85, v85
	v_mul_f32_e32 v87, v87, v87
	v_fmac_f32_e32 v85, v84, v84
	v_fmac_f32_e32 v87, v86, v86
	v_add_f32_e32 v84, v85, v87
	v_add_f32_e32 v160, v160, v84
	v_pk_add_f32 v[82:83], v[82:83], v[210:211]
	v_pk_add_f32 v[80:81], v[80:81], v[208:209]
	v_cvt_pk_bf16_f32 v223, v82, v83
	v_cvt_pk_bf16_f32 v222, v80, v81
	global_store_dwordx4 v[154:155], v[80:83], off offset:576
	s_nop 1
	v_mul_f32_e32 v81, v81, v81
	v_mul_f32_e32 v83, v83, v83
	v_fmac_f32_e32 v81, v80, v80
	v_fmac_f32_e32 v83, v82, v82
	v_add_f32_e32 v80, v81, v83
	v_add_f32_e32 v160, v160, v80
	v_permlane16_swap_b32_e32 v220, v222
	v_permlane16_swap_b32_e32 v221, v223
	global_store_dwordx4 v[156:157], v[220:223], off offset:256
	s_nop 0
	v_mov_b32_e32 v161, v160
	s_nop 1
	v_permlane16_swap_b32_e32 v160, v161
	v_add_f32_e32 v160, v160, v161
	v_mov_b32_e32 v161, v160
	s_nop 1
	v_permlane32_swap_b32_e32 v160, v161
	s_and_saveexec_b64 s[22:23], s[8:9]
	v_lshl_add_u64 v[162:163], v[212:213], 2, s[52:53]
	v_add_f32_e32 v160, v160, v161
	global_atomic_add_f32 v[162:163], v160, off
	s_or_b64 exec, exec, s[22:23]
	v_add_u32_e32 v212, 0x90, v146
	v_mov_b32_e32 v213, v147
	v_lshlrev_b64 v[214:215], 11, v[212:213]
	v_lshl_add_u64 v[214:215], v[214:215], 0, v[144:145]
	v_lshl_add_u64 v[152:153], v[214:215], 2, s[28:29]
	global_load_dwordx4 v[196:199], v[152:153], off
	global_load_dwordx4 v[200:203], v[152:153], off offset:64
	global_load_dwordx4 v[204:207], v[152:153], off offset:512
	global_load_dwordx4 v[208:211], v[152:153], off offset:576
	s_waitcnt vmcnt(22)
	v_add_u32_e32 v212, 0x30, v146
	v_mov_b32_e32 v213, v147
	v_lshlrev_b64 v[214:215], 11, v[212:213]
	v_lshl_add_u64 v[214:215], v[214:215], 0, v[144:145]
	v_lshl_add_u64 v[154:155], v[214:215], 2, s[28:29]
	v_lshl_add_u64 v[156:157], v[214:215], 1, s[40:41]
	v_lshl_add_u64 v[156:157], v[156:157], 0, v[224:225]
	v_pk_add_f32 v[78:79], v[78:79], v[166:167]
	v_pk_add_f32 v[76:77], v[76:77], v[164:165]
	v_cvt_pk_bf16_f32 v221, v78, v79
	v_cvt_pk_bf16_f32 v220, v76, v77
	global_store_dwordx4 v[154:155], v[76:79], off
	s_nop 1
	v_mul_f32_e32 v77, v77, v77
	v_mul_f32_e32 v79, v79, v79
	v_fmac_f32_e32 v77, v76, v76
	v_fmac_f32_e32 v79, v78, v78
	v_add_f32_e32 v160, v77, v79
	v_pk_add_f32 v[74:75], v[74:75], v[170:171]
	v_pk_add_f32 v[72:73], v[72:73], v[168:169]
	v_cvt_pk_bf16_f32 v223, v74, v75
	v_cvt_pk_bf16_f32 v222, v72, v73
	global_store_dwordx4 v[154:155], v[72:75], off offset:64
	s_nop 1
	v_mul_f32_e32 v73, v73, v73
	v_mul_f32_e32 v75, v75, v75
	v_fmac_f32_e32 v73, v72, v72
	v_fmac_f32_e32 v75, v74, v74
	v_add_f32_e32 v72, v73, v75
	v_add_f32_e32 v160, v160, v72
	v_permlane16_swap_b32_e32 v220, v222
	v_permlane16_swap_b32_e32 v221, v223
	global_store_dwordx4 v[156:157], v[220:223], off
	s_nop 0
	v_pk_add_f32 v[70:71], v[70:71], v[174:175]
	v_pk_add_f32 v[68:69], v[68:69], v[172:173]
	v_cvt_pk_bf16_f32 v221, v70, v71
	v_cvt_pk_bf16_f32 v220, v68, v69
	global_store_dwordx4 v[154:155], v[68:71], off offset:512
	s_nop 1
	v_mul_f32_e32 v69, v69, v69
	v_mul_f32_e32 v71, v71, v71
	v_fmac_f32_e32 v69, v68, v68
	v_fmac_f32_e32 v71, v70, v70
	v_add_f32_e32 v68, v69, v71
	v_add_f32_e32 v160, v160, v68
	v_pk_add_f32 v[66:67], v[66:67], v[178:179]
	v_pk_add_f32 v[64:65], v[64:65], v[176:177]
	v_cvt_pk_bf16_f32 v223, v66, v67
	v_cvt_pk_bf16_f32 v222, v64, v65
	global_store_dwordx4 v[154:155], v[64:67], off offset:576
	s_nop 1
	v_mul_f32_e32 v65, v65, v65
	v_mul_f32_e32 v67, v67, v67
	v_fmac_f32_e32 v65, v64, v64
	v_fmac_f32_e32 v67, v66, v66
	v_add_f32_e32 v64, v65, v67
	v_add_f32_e32 v160, v160, v64
	v_permlane16_swap_b32_e32 v220, v222
	v_permlane16_swap_b32_e32 v221, v223
	global_store_dwordx4 v[156:157], v[220:223], off offset:256
	s_nop 0
	v_mov_b32_e32 v161, v160
	s_nop 1
	v_permlane16_swap_b32_e32 v160, v161
	v_add_f32_e32 v160, v160, v161
	v_mov_b32_e32 v161, v160
	s_nop 1
	v_permlane32_swap_b32_e32 v160, v161
	s_and_saveexec_b64 s[22:23], s[8:9]
	v_lshl_add_u64 v[162:163], v[212:213], 2, s[52:53]
	v_add_f32_e32 v160, v160, v161
	global_atomic_add_f32 v[162:163], v160, off
	s_or_b64 exec, exec, s[22:23]
	v_add_u32_e32 v212, 0xa0, v146
	v_mov_b32_e32 v213, v147
	v_lshlrev_b64 v[214:215], 11, v[212:213]
	v_lshl_add_u64 v[214:215], v[214:215], 0, v[144:145]
	v_lshl_add_u64 v[152:153], v[214:215], 2, s[28:29]
	global_load_dwordx4 v[164:167], v[152:153], off
	global_load_dwordx4 v[168:171], v[152:153], off offset:64
	global_load_dwordx4 v[172:175], v[152:153], off offset:512
	global_load_dwordx4 v[176:179], v[152:153], off offset:576
	s_waitcnt vmcnt(22)
	v_add_u32_e32 v212, 0x80, v146
	v_mov_b32_e32 v213, v147
	v_lshlrev_b64 v[214:215], 11, v[212:213]
	v_lshl_add_u64 v[214:215], v[214:215], 0, v[144:145]
	v_lshl_add_u64 v[154:155], v[214:215], 2, s[28:29]
	v_lshl_add_u64 v[156:157], v[214:215], 1, s[40:41]
	v_lshl_add_u64 v[156:157], v[156:157], 0, v[224:225]
	v_pk_add_f32 v[62:63], v[62:63], v[182:183]
	v_pk_add_f32 v[60:61], v[60:61], v[180:181]
	v_cvt_pk_bf16_f32 v221, v62, v63
	v_cvt_pk_bf16_f32 v220, v60, v61
	global_store_dwordx4 v[154:155], v[60:63], off
	s_nop 1
	v_mul_f32_e32 v61, v61, v61
	v_mul_f32_e32 v63, v63, v63
	v_fmac_f32_e32 v61, v60, v60
	v_fmac_f32_e32 v63, v62, v62
	v_add_f32_e32 v160, v61, v63
	v_pk_add_f32 v[58:59], v[58:59], v[186:187]
	v_pk_add_f32 v[56:57], v[56:57], v[184:185]
	v_cvt_pk_bf16_f32 v223, v58, v59
	v_cvt_pk_bf16_f32 v222, v56, v57
	global_store_dwordx4 v[154:155], v[56:59], off offset:64
	s_nop 1
	v_mul_f32_e32 v57, v57, v57
	v_mul_f32_e32 v59, v59, v59
	v_fmac_f32_e32 v57, v56, v56
	v_fmac_f32_e32 v59, v58, v58
	v_add_f32_e32 v56, v57, v59
	v_add_f32_e32 v160, v160, v56
	v_permlane16_swap_b32_e32 v220, v222
	v_permlane16_swap_b32_e32 v221, v223
	global_store_dwordx4 v[156:157], v[220:223], off
	s_nop 0
	v_pk_add_f32 v[54:55], v[54:55], v[190:191]
	v_pk_add_f32 v[52:53], v[52:53], v[188:189]
	v_cvt_pk_bf16_f32 v221, v54, v55
	v_cvt_pk_bf16_f32 v220, v52, v53
	global_store_dwordx4 v[154:155], v[52:55], off offset:512
	s_nop 1
	v_mul_f32_e32 v53, v53, v53
	v_mul_f32_e32 v55, v55, v55
	v_fmac_f32_e32 v53, v52, v52
	v_fmac_f32_e32 v55, v54, v54
	v_add_f32_e32 v52, v53, v55
	v_add_f32_e32 v160, v160, v52
	v_pk_add_f32 v[50:51], v[50:51], v[194:195]
	v_pk_add_f32 v[48:49], v[48:49], v[192:193]
	v_cvt_pk_bf16_f32 v223, v50, v51
	v_cvt_pk_bf16_f32 v222, v48, v49
	global_store_dwordx4 v[154:155], v[48:51], off offset:576
	s_nop 1
	v_mul_f32_e32 v49, v49, v49
	v_mul_f32_e32 v51, v51, v51
	v_fmac_f32_e32 v49, v48, v48
	v_fmac_f32_e32 v51, v50, v50
	v_add_f32_e32 v48, v49, v51
	v_add_f32_e32 v160, v160, v48
	v_permlane16_swap_b32_e32 v220, v222
	v_permlane16_swap_b32_e32 v221, v223
	global_store_dwordx4 v[156:157], v[220:223], off offset:256
	s_nop 0
	v_mov_b32_e32 v161, v160
	s_nop 1
	v_permlane16_swap_b32_e32 v160, v161
	v_add_f32_e32 v160, v160, v161
	v_mov_b32_e32 v161, v160
	s_nop 1
	v_permlane32_swap_b32_e32 v160, v161
	s_and_saveexec_b64 s[22:23], s[8:9]
	v_lshl_add_u64 v[162:163], v[212:213], 2, s[52:53]
	v_add_f32_e32 v160, v160, v161
	global_atomic_add_f32 v[162:163], v160, off
	s_or_b64 exec, exec, s[22:23]
	v_add_u32_e32 v212, 0xb0, v146
	v_mov_b32_e32 v213, v147
	v_lshlrev_b64 v[214:215], 11, v[212:213]
	v_lshl_add_u64 v[214:215], v[214:215], 0, v[144:145]
	v_lshl_add_u64 v[152:153], v[214:215], 2, s[28:29]
	global_load_dwordx4 v[180:183], v[152:153], off
	global_load_dwordx4 v[184:187], v[152:153], off offset:64
	global_load_dwordx4 v[188:191], v[152:153], off offset:512
	global_load_dwordx4 v[192:195], v[152:153], off offset:576
	s_waitcnt vmcnt(22)
	v_add_u32_e32 v212, 0x90, v146
	v_mov_b32_e32 v213, v147
	v_lshlrev_b64 v[214:215], 11, v[212:213]
	v_lshl_add_u64 v[214:215], v[214:215], 0, v[144:145]
	v_lshl_add_u64 v[154:155], v[214:215], 2, s[28:29]
	v_lshl_add_u64 v[156:157], v[214:215], 1, s[40:41]
	v_lshl_add_u64 v[156:157], v[156:157], 0, v[224:225]
	v_pk_add_f32 v[46:47], v[46:47], v[198:199]
	v_pk_add_f32 v[44:45], v[44:45], v[196:197]
	v_cvt_pk_bf16_f32 v221, v46, v47
	v_cvt_pk_bf16_f32 v220, v44, v45
	global_store_dwordx4 v[154:155], v[44:47], off
	s_nop 1
	v_mul_f32_e32 v45, v45, v45
	v_mul_f32_e32 v47, v47, v47
	v_fmac_f32_e32 v45, v44, v44
	v_fmac_f32_e32 v47, v46, v46
	v_add_f32_e32 v160, v45, v47
	v_pk_add_f32 v[42:43], v[42:43], v[202:203]
	v_pk_add_f32 v[40:41], v[40:41], v[200:201]
	v_cvt_pk_bf16_f32 v223, v42, v43
	v_cvt_pk_bf16_f32 v222, v40, v41
	global_store_dwordx4 v[154:155], v[40:43], off offset:64
	s_nop 1
	v_mul_f32_e32 v41, v41, v41
	v_mul_f32_e32 v43, v43, v43
	v_fmac_f32_e32 v41, v40, v40
	v_fmac_f32_e32 v43, v42, v42
	v_add_f32_e32 v40, v41, v43
	v_add_f32_e32 v160, v160, v40
	v_permlane16_swap_b32_e32 v220, v222
	v_permlane16_swap_b32_e32 v221, v223
	global_store_dwordx4 v[156:157], v[220:223], off
	s_nop 0
	v_pk_add_f32 v[38:39], v[38:39], v[206:207]
	v_pk_add_f32 v[36:37], v[36:37], v[204:205]
	v_cvt_pk_bf16_f32 v221, v38, v39
	v_cvt_pk_bf16_f32 v220, v36, v37
	global_store_dwordx4 v[154:155], v[36:39], off offset:512
	s_nop 1
	v_mul_f32_e32 v37, v37, v37
	v_mul_f32_e32 v39, v39, v39
	v_fmac_f32_e32 v37, v36, v36
	v_fmac_f32_e32 v39, v38, v38
	v_add_f32_e32 v36, v37, v39
	v_add_f32_e32 v160, v160, v36
	v_pk_add_f32 v[34:35], v[34:35], v[210:211]
	v_pk_add_f32 v[32:33], v[32:33], v[208:209]
	v_cvt_pk_bf16_f32 v223, v34, v35
	v_cvt_pk_bf16_f32 v222, v32, v33
	global_store_dwordx4 v[154:155], v[32:35], off offset:576
	s_nop 1
	v_mul_f32_e32 v33, v33, v33
	v_mul_f32_e32 v35, v35, v35
	v_fmac_f32_e32 v33, v32, v32
	v_fmac_f32_e32 v35, v34, v34
	v_add_f32_e32 v32, v33, v35
	v_add_f32_e32 v160, v160, v32
	v_permlane16_swap_b32_e32 v220, v222
	v_permlane16_swap_b32_e32 v221, v223
	global_store_dwordx4 v[156:157], v[220:223], off offset:256
	s_nop 0
	v_mov_b32_e32 v161, v160
	s_nop 1
	v_permlane16_swap_b32_e32 v160, v161
	v_add_f32_e32 v160, v160, v161
	v_mov_b32_e32 v161, v160
	s_nop 1
	v_permlane32_swap_b32_e32 v160, v161
	s_and_saveexec_b64 s[22:23], s[8:9]
	v_lshl_add_u64 v[162:163], v[212:213], 2, s[52:53]
	v_add_f32_e32 v160, v160, v161
	global_atomic_add_f32 v[162:163], v160, off
	s_or_b64 exec, exec, s[22:23]
	s_waitcnt vmcnt(18)
	v_add_u32_e32 v212, 0xa0, v146
	v_mov_b32_e32 v213, v147
	v_lshlrev_b64 v[214:215], 11, v[212:213]
	v_lshl_add_u64 v[214:215], v[214:215], 0, v[144:145]
	v_lshl_add_u64 v[154:155], v[214:215], 2, s[28:29]
	v_lshl_add_u64 v[156:157], v[214:215], 1, s[40:41]
	v_lshl_add_u64 v[156:157], v[156:157], 0, v[224:225]
	v_pk_add_f32 v[30:31], v[30:31], v[166:167]
	v_pk_add_f32 v[28:29], v[28:29], v[164:165]
	v_cvt_pk_bf16_f32 v221, v30, v31
	v_cvt_pk_bf16_f32 v220, v28, v29
	global_store_dwordx4 v[154:155], v[28:31], off
	s_nop 1
	v_mul_f32_e32 v29, v29, v29
	v_mul_f32_e32 v31, v31, v31
	v_fmac_f32_e32 v29, v28, v28
	v_fmac_f32_e32 v31, v30, v30
	v_add_f32_e32 v160, v29, v31
	v_pk_add_f32 v[26:27], v[26:27], v[170:171]
	v_pk_add_f32 v[24:25], v[24:25], v[168:169]
	v_cvt_pk_bf16_f32 v223, v26, v27
	v_cvt_pk_bf16_f32 v222, v24, v25
	global_store_dwordx4 v[154:155], v[24:27], off offset:64
	s_nop 1
	v_mul_f32_e32 v25, v25, v25
	v_mul_f32_e32 v27, v27, v27
	v_fmac_f32_e32 v25, v24, v24
	v_fmac_f32_e32 v27, v26, v26
	v_add_f32_e32 v24, v25, v27
	v_add_f32_e32 v160, v160, v24
	v_permlane16_swap_b32_e32 v220, v222
	v_permlane16_swap_b32_e32 v221, v223
	global_store_dwordx4 v[156:157], v[220:223], off
	s_nop 0
	v_pk_add_f32 v[22:23], v[22:23], v[174:175]
	v_pk_add_f32 v[20:21], v[20:21], v[172:173]
	v_cvt_pk_bf16_f32 v221, v22, v23
	v_cvt_pk_bf16_f32 v220, v20, v21
	global_store_dwordx4 v[154:155], v[20:23], off offset:512
	s_nop 1
	v_mul_f32_e32 v21, v21, v21
	v_mul_f32_e32 v23, v23, v23
	v_fmac_f32_e32 v21, v20, v20
	v_fmac_f32_e32 v23, v22, v22
	v_add_f32_e32 v20, v21, v23
	v_add_f32_e32 v160, v160, v20
	v_pk_add_f32 v[18:19], v[18:19], v[178:179]
	v_pk_add_f32 v[16:17], v[16:17], v[176:177]
	v_cvt_pk_bf16_f32 v223, v18, v19
	v_cvt_pk_bf16_f32 v222, v16, v17
	global_store_dwordx4 v[154:155], v[16:19], off offset:576
	s_nop 1
	v_mul_f32_e32 v17, v17, v17
	v_mul_f32_e32 v19, v19, v19
	v_fmac_f32_e32 v17, v16, v16
	v_fmac_f32_e32 v19, v18, v18
	v_add_f32_e32 v16, v17, v19
	v_add_f32_e32 v160, v160, v16
	v_permlane16_swap_b32_e32 v220, v222
	v_permlane16_swap_b32_e32 v221, v223
	global_store_dwordx4 v[156:157], v[220:223], off offset:256
	s_nop 0
	v_mov_b32_e32 v161, v160
	s_nop 1
	v_permlane16_swap_b32_e32 v160, v161
	v_add_f32_e32 v160, v160, v161
	v_mov_b32_e32 v161, v160
	s_nop 1
	v_permlane32_swap_b32_e32 v160, v161
	s_and_saveexec_b64 s[22:23], s[8:9]
	v_lshl_add_u64 v[162:163], v[212:213], 2, s[52:53]
	v_add_f32_e32 v160, v160, v161
	global_atomic_add_f32 v[162:163], v160, off
	s_or_b64 exec, exec, s[22:23]
	s_waitcnt vmcnt(14)
	v_add_u32_e32 v212, 0xb0, v146
	v_mov_b32_e32 v213, v147
	v_lshlrev_b64 v[214:215], 11, v[212:213]
	v_lshl_add_u64 v[214:215], v[214:215], 0, v[144:145]
	v_lshl_add_u64 v[154:155], v[214:215], 2, s[28:29]
	v_lshl_add_u64 v[156:157], v[214:215], 1, s[40:41]
	v_lshl_add_u64 v[156:157], v[156:157], 0, v[224:225]
	v_pk_add_f32 v[14:15], v[14:15], v[182:183]
	v_pk_add_f32 v[12:13], v[12:13], v[180:181]
	v_cvt_pk_bf16_f32 v221, v14, v15
	v_cvt_pk_bf16_f32 v220, v12, v13
	global_store_dwordx4 v[154:155], v[12:15], off
	s_nop 1
	v_mul_f32_e32 v13, v13, v13
	v_mul_f32_e32 v15, v15, v15
	v_fmac_f32_e32 v13, v12, v12
	v_fmac_f32_e32 v15, v14, v14
	v_add_f32_e32 v160, v13, v15
	v_pk_add_f32 v[10:11], v[10:11], v[186:187]
	v_pk_add_f32 v[8:9], v[8:9], v[184:185]
	v_cvt_pk_bf16_f32 v223, v10, v11
	v_cvt_pk_bf16_f32 v222, v8, v9
	global_store_dwordx4 v[154:155], v[8:11], off offset:64
	s_nop 1
	v_mul_f32_e32 v9, v9, v9
	v_mul_f32_e32 v11, v11, v11
	v_fmac_f32_e32 v9, v8, v8
	v_fmac_f32_e32 v11, v10, v10
	v_add_f32_e32 v8, v9, v11
	v_add_f32_e32 v160, v160, v8
	v_permlane16_swap_b32_e32 v220, v222
	v_permlane16_swap_b32_e32 v221, v223
	global_store_dwordx4 v[156:157], v[220:223], off
	s_nop 0
	v_pk_add_f32 v[6:7], v[6:7], v[190:191]
	v_pk_add_f32 v[4:5], v[4:5], v[188:189]
	v_cvt_pk_bf16_f32 v221, v6, v7
	v_cvt_pk_bf16_f32 v220, v4, v5
	global_store_dwordx4 v[154:155], v[4:7], off offset:512
	s_nop 1
	v_mul_f32_e32 v5, v5, v5
	v_mul_f32_e32 v7, v7, v7
	v_fmac_f32_e32 v5, v4, v4
	v_fmac_f32_e32 v7, v6, v6
	v_add_f32_e32 v4, v5, v7
	v_add_f32_e32 v160, v160, v4
	v_pk_add_f32 v[2:3], v[2:3], v[194:195]
	v_pk_add_f32 v[0:1], v[0:1], v[192:193]
	v_cvt_pk_bf16_f32 v223, v2, v3
	v_cvt_pk_bf16_f32 v222, v0, v1
	global_store_dwordx4 v[154:155], v[0:3], off offset:576
	s_nop 1
	v_mul_f32_e32 v1, v1, v1
	v_mul_f32_e32 v3, v3, v3
	v_fmac_f32_e32 v1, v0, v0
	v_fmac_f32_e32 v3, v2, v2
	v_add_f32_e32 v0, v1, v3
	v_add_f32_e32 v160, v160, v0
	v_permlane16_swap_b32_e32 v220, v222
	v_permlane16_swap_b32_e32 v221, v223
	global_store_dwordx4 v[156:157], v[220:223], off offset:256
	s_nop 0
	v_mov_b32_e32 v161, v160
	s_nop 1
	v_permlane16_swap_b32_e32 v160, v161
	v_add_f32_e32 v160, v160, v161
	v_mov_b32_e32 v161, v160
	s_nop 1
	v_permlane32_swap_b32_e32 v160, v161
	s_and_saveexec_b64 s[22:23], s[8:9]
	v_lshl_add_u64 v[162:163], v[212:213], 2, s[52:53]
	v_add_f32_e32 v160, v160, v161
	global_atomic_add_f32 v[162:163], v160, off
	s_or_b64 exec, exec, s[22:23]
	s_branch .LBB0_1615

.LBB0_1785:
	ds_read_b128 v[144:147], v148
	ds_read_b128 v[152:155], v148 offset:1024
	ds_read_b128 v[156:159], v148 offset:2048
	ds_read_b128 v[160:163], v148 offset:3072
	s_add_u32 s58, s56, 0x100
	s_addc_u32 s59, s57, 0
	s_cmpk_eq_i32 s67, 0x7c
	s_cselect_b32 s63, s19, s59
	s_cselect_b32 s62, s53, s58
	s_cselect_b32 s61, s15, s66
	s_cselect_b32 s60, s64, s65
	v_lshl_add_u64 v[196:197], s[56:57], 0, v[134:135]
	s_add_i32 m0, s6, 0xc000
	ds_read_b128 v[164:167], v149
	ds_read_b128 v[168:171], v149 offset:1024
	ds_read_b128 v[172:175], v149 offset:2048
	ds_read_b128 v[176:179], v149 offset:3072
	ds_read_b128 v[180:183], v149 offset:4096
	ds_read_b128 v[184:187], v149 offset:5120
	ds_read_b128 v[188:191], v149 offset:6144
	ds_read_b128 v[192:195], v149 offset:7168
	global_load_lds_dwordx4 v[196:197], off
	v_lshl_add_u64 v[196:197], s[56:57], 0, v[138:139]
	s_add_i32 m0, s6, 0xe000
	s_nop 0
	global_load_lds_dwordx4 v[196:197], off
	s_waitcnt lgkmcnt(8)
	s_barrier
	s_waitcnt lgkmcnt(0)
	s_setprio 1
	s_waitcnt lgkmcnt(0)
	v_mfma_f32_16x16x32_bf16 v[124:127], v[144:147], v[164:167], v[124:127]
	v_mfma_f32_16x16x32_bf16 v[120:123], v[156:159], v[164:167], v[120:123]
	v_mfma_f32_16x16x32_bf16 v[108:111], v[144:147], v[172:175], v[108:111]
	v_mfma_f32_16x16x32_bf16 v[104:107], v[156:159], v[172:175], v[104:107]
	v_mfma_f32_16x16x32_bf16 v[92:95], v[144:147], v[180:183], v[92:95]
	v_mfma_f32_16x16x32_bf16 v[88:91], v[156:159], v[180:183], v[88:91]
	v_mfma_f32_16x16x32_bf16 v[76:79], v[144:147], v[188:191], v[76:79]
	v_mfma_f32_16x16x32_bf16 v[72:75], v[156:159], v[188:191], v[72:75]
	v_mfma_f32_16x16x32_bf16 v[124:127], v[152:155], v[168:171], v[124:127]
	v_mfma_f32_16x16x32_bf16 v[120:123], v[160:163], v[168:171], v[120:123]
	v_mfma_f32_16x16x32_bf16 v[108:111], v[152:155], v[176:179], v[108:111]
	v_mfma_f32_16x16x32_bf16 v[104:107], v[160:163], v[176:179], v[104:107]
	v_mfma_f32_16x16x32_bf16 v[92:95], v[152:155], v[184:187], v[92:95]
	v_mfma_f32_16x16x32_bf16 v[88:91], v[160:163], v[184:187], v[88:91]
	v_mfma_f32_16x16x32_bf16 v[76:79], v[152:155], v[192:195], v[76:79]
	v_mfma_f32_16x16x32_bf16 v[72:75], v[160:163], v[192:195], v[72:75]
	s_setprio 0
	s_barrier
	s_add_i32 s56, s47, s5
	v_lshl_add_u64 v[212:213], s[60:61], 0, v[128:129]
	s_mov_b32 m0, s56
	ds_read_b128 v[196:199], v150
	ds_read_b128 v[200:203], v150 offset:1024
	ds_read_b128 v[204:207], v150 offset:2048
	ds_read_b128 v[208:211], v150 offset:3072
	global_load_lds_dwordx4 v[212:213], off
	v_lshl_add_u64 v[214:215], s[60:61], 0, v[130:131]
	s_add_i32 m0, s56, 0x2000
	s_nop 0
	global_load_lds_dwordx4 v[214:215], off
	s_barrier
	s_waitcnt lgkmcnt(0)
	s_setprio 1
	s_waitcnt lgkmcnt(0)
	v_mfma_f32_16x16x32_bf16 v[116:119], v[196:199], v[164:167], v[116:119]
	v_mfma_f32_16x16x32_bf16 v[112:115], v[204:207], v[164:167], v[112:115]
	v_mfma_f32_16x16x32_bf16 v[100:103], v[196:199], v[172:175], v[100:103]
	v_mfma_f32_16x16x32_bf16 v[96:99], v[204:207], v[172:175], v[96:99]
	v_mfma_f32_16x16x32_bf16 v[84:87], v[196:199], v[180:183], v[84:87]
	v_mfma_f32_16x16x32_bf16 v[80:83], v[204:207], v[180:183], v[80:83]
	v_mfma_f32_16x16x32_bf16 v[68:71], v[196:199], v[188:191], v[68:71]
	v_mfma_f32_16x16x32_bf16 v[64:67], v[204:207], v[188:191], v[64:67]
	v_mfma_f32_16x16x32_bf16 v[116:119], v[200:203], v[168:171], v[116:119]
	v_mfma_f32_16x16x32_bf16 v[112:115], v[208:211], v[168:171], v[112:115]
	v_mfma_f32_16x16x32_bf16 v[100:103], v[200:203], v[176:179], v[100:103]
	v_mfma_f32_16x16x32_bf16 v[96:99], v[208:211], v[176:179], v[96:99]
	v_mfma_f32_16x16x32_bf16 v[84:87], v[200:203], v[184:187], v[84:87]
	v_mfma_f32_16x16x32_bf16 v[80:83], v[208:211], v[184:187], v[80:83]
	v_mfma_f32_16x16x32_bf16 v[68:71], v[200:203], v[192:195], v[68:71]
	v_mfma_f32_16x16x32_bf16 v[64:67], v[208:211], v[192:195], v[64:67]
	s_setprio 0
	s_mov_b32 m0, s6
	v_lshl_add_u64 v[216:217], s[62:63], 0, v[128:129]
	s_barrier
	ds_read_b128 v[164:167], v149 offset:16384
	ds_read_b128 v[168:171], v149 offset:17408
	ds_read_b128 v[172:175], v149 offset:18432
	ds_read_b128 v[176:179], v149 offset:19456
	ds_read_b128 v[180:183], v149 offset:20480
	ds_read_b128 v[184:187], v149 offset:21504
	ds_read_b128 v[188:191], v149 offset:22528
	ds_read_b128 v[192:195], v149 offset:23552
	global_load_lds_dwordx4 v[216:217], off
	v_lshl_add_u64 v[218:219], s[62:63], 0, v[130:131]
	s_mov_b32 m0, s7
	s_nop 0
	global_load_lds_dwordx4 v[218:219], off
	s_barrier
	s_waitcnt lgkmcnt(0)
	s_setprio 1
	s_waitcnt lgkmcnt(0)
	v_mfma_f32_16x16x32_bf16 v[60:63], v[144:147], v[164:167], v[60:63]
	v_mfma_f32_16x16x32_bf16 v[56:59], v[156:159], v[164:167], v[56:59]
	v_mfma_f32_16x16x32_bf16 v[44:47], v[144:147], v[172:175], v[44:47]
	v_mfma_f32_16x16x32_bf16 v[40:43], v[156:159], v[172:175], v[40:43]
	v_mfma_f32_16x16x32_bf16 v[28:31], v[144:147], v[180:183], v[28:31]
	v_mfma_f32_16x16x32_bf16 v[24:27], v[156:159], v[180:183], v[24:27]
	v_mfma_f32_16x16x32_bf16 v[12:15], v[144:147], v[188:191], v[12:15]
	v_mfma_f32_16x16x32_bf16 v[8:11], v[156:159], v[188:191], v[8:11]
	v_mfma_f32_16x16x32_bf16 v[60:63], v[152:155], v[168:171], v[60:63]
	v_mfma_f32_16x16x32_bf16 v[56:59], v[160:163], v[168:171], v[56:59]
	v_mfma_f32_16x16x32_bf16 v[44:47], v[152:155], v[176:179], v[44:47]
	v_mfma_f32_16x16x32_bf16 v[40:43], v[160:163], v[176:179], v[40:43]
	v_mfma_f32_16x16x32_bf16 v[28:31], v[152:155], v[184:187], v[28:31]
	v_mfma_f32_16x16x32_bf16 v[24:27], v[160:163], v[184:187], v[24:27]
	v_mfma_f32_16x16x32_bf16 v[12:15], v[152:155], v[192:195], v[12:15]
	v_mfma_f32_16x16x32_bf16 v[8:11], v[160:163], v[192:195], v[8:11]
	s_setprio 0
	s_barrier
	s_add_u32 s56, s60, 0x200000
	s_addc_u32 s57, s61, 0
	s_add_i32 s68, s55, s5
	v_lshl_add_u64 v[144:145], s[56:57], 0, v[128:129]
	s_mov_b32 m0, s68
	s_nop 0
	global_load_lds_dwordx4 v[144:145], off
	v_lshl_add_u64 v[144:145], s[56:57], 0, v[130:131]
	s_add_i32 m0, s68, 0x2000
	s_nop 0
	global_load_lds_dwordx4 v[144:145], off
	s_waitcnt vmcnt(6)
	s_barrier
	s_setprio 1
	v_mfma_f32_16x16x32_bf16 v[52:55], v[196:199], v[164:167], v[52:55]
	v_mfma_f32_16x16x32_bf16 v[48:51], v[204:207], v[164:167], v[48:51]
	v_mfma_f32_16x16x32_bf16 v[36:39], v[196:199], v[172:175], v[36:39]
	v_mfma_f32_16x16x32_bf16 v[32:35], v[204:207], v[172:175], v[32:35]
	v_mfma_f32_16x16x32_bf16 v[20:23], v[196:199], v[180:183], v[20:23]
	v_mfma_f32_16x16x32_bf16 v[16:19], v[204:207], v[180:183], v[16:19]
	v_mfma_f32_16x16x32_bf16 v[4:7], v[196:199], v[188:191], v[4:7]
	v_mfma_f32_16x16x32_bf16 v[0:3], v[204:207], v[188:191], v[0:3]
	v_mfma_f32_16x16x32_bf16 v[52:55], v[200:203], v[168:171], v[52:55]
	v_mfma_f32_16x16x32_bf16 v[48:51], v[208:211], v[168:171], v[48:51]
	v_mfma_f32_16x16x32_bf16 v[36:39], v[200:203], v[176:179], v[36:39]
	v_mfma_f32_16x16x32_bf16 v[32:35], v[208:211], v[176:179], v[32:35]
	v_mfma_f32_16x16x32_bf16 v[20:23], v[200:203], v[184:187], v[20:23]
	v_mfma_f32_16x16x32_bf16 v[16:19], v[208:211], v[184:187], v[16:19]
	v_mfma_f32_16x16x32_bf16 v[4:7], v[200:203], v[192:195], v[4:7]
	v_mfma_f32_16x16x32_bf16 v[0:3], v[208:211], v[192:195], v[0:3]
	s_setprio 0
	s_add_i32 s68, 16, 0x18000
	v_add_u32_e32 v151, s68, v137
	s_barrier
	ds_read_b128 v[144:147], v151
	ds_read_b128 v[152:155], v151 offset:1024
	ds_read_b128 v[156:159], v151 offset:2048
	ds_read_b128 v[160:163], v151 offset:3072
	s_add_u32 s56, s62, 0x200000
	s_addc_u32 s57, s63, 0
	s_mov_b32 m0, s26
	v_lshl_add_u64 v[196:197], s[56:57], 0, v[128:129]
	ds_read_b128 v[164:167], v149 offset:32768
	ds_read_b128 v[168:171], v149 offset:33792
	ds_read_b128 v[172:175], v149 offset:34816
	ds_read_b128 v[176:179], v149 offset:35840
	ds_read_b128 v[180:183], v149 offset:36864
	ds_read_b128 v[184:187], v149 offset:37888
	ds_read_b128 v[188:191], v149 offset:38912
	ds_read_b128 v[192:195], v149 offset:39936
	global_load_lds_dwordx4 v[196:197], off
	v_lshl_add_u64 v[196:197], s[56:57], 0, v[130:131]
	s_mov_b32 m0, s27
	s_nop 0
	global_load_lds_dwordx4 v[196:197], off
	s_waitcnt lgkmcnt(8)
	s_barrier
	s_waitcnt lgkmcnt(0)
	s_setprio 1
	s_waitcnt lgkmcnt(0)
	v_mfma_f32_16x16x32_bf16 v[124:127], v[144:147], v[164:167], v[124:127]
	v_mfma_f32_16x16x32_bf16 v[120:123], v[156:159], v[164:167], v[120:123]
	v_mfma_f32_16x16x32_bf16 v[108:111], v[144:147], v[172:175], v[108:111]
	v_mfma_f32_16x16x32_bf16 v[104:107], v[156:159], v[172:175], v[104:107]
	v_mfma_f32_16x16x32_bf16 v[92:95], v[144:147], v[180:183], v[92:95]
	v_mfma_f32_16x16x32_bf16 v[88:91], v[156:159], v[180:183], v[88:91]
	v_mfma_f32_16x16x32_bf16 v[76:79], v[144:147], v[188:191], v[76:79]
	v_mfma_f32_16x16x32_bf16 v[72:75], v[156:159], v[188:191], v[72:75]
	v_mfma_f32_16x16x32_bf16 v[124:127], v[152:155], v[168:171], v[124:127]
	v_mfma_f32_16x16x32_bf16 v[120:123], v[160:163], v[168:171], v[120:123]
	v_mfma_f32_16x16x32_bf16 v[108:111], v[152:155], v[176:179], v[108:111]
	v_mfma_f32_16x16x32_bf16 v[104:107], v[160:163], v[176:179], v[104:107]
	v_mfma_f32_16x16x32_bf16 v[92:95], v[152:155], v[184:187], v[92:95]
	v_mfma_f32_16x16x32_bf16 v[88:91], v[160:163], v[184:187], v[88:91]
	v_mfma_f32_16x16x32_bf16 v[76:79], v[152:155], v[192:195], v[76:79]
	v_mfma_f32_16x16x32_bf16 v[72:75], v[160:163], v[192:195], v[72:75]
	s_setprio 0
	s_barrier
	s_add_i32 s62, 16, 0x1c000
	s_add_i32 s56, s68, s5
	v_add_u32_e32 v151, s62, v137
	v_lshl_add_u64 v[212:213], v[212:213], 0, s[12:13]
	s_mov_b32 m0, s56
	ds_read_b128 v[196:199], v151
	ds_read_b128 v[200:203], v151 offset:1024
	ds_read_b128 v[204:207], v151 offset:2048
	ds_read_b128 v[208:211], v151 offset:3072
	global_load_lds_dwordx4 v[212:213], off
	v_lshl_add_u64 v[212:213], v[214:215], 0, s[12:13]
	s_add_i32 m0, s56, 0x2000
	s_nop 0
	global_load_lds_dwordx4 v[212:213], off
	s_barrier
	s_waitcnt lgkmcnt(0)
	s_setprio 1
	s_waitcnt lgkmcnt(0)
	v_mfma_f32_16x16x32_bf16 v[116:119], v[196:199], v[164:167], v[116:119]
	v_mfma_f32_16x16x32_bf16 v[112:115], v[204:207], v[164:167], v[112:115]
	v_mfma_f32_16x16x32_bf16 v[100:103], v[196:199], v[172:175], v[100:103]
	v_mfma_f32_16x16x32_bf16 v[96:99], v[204:207], v[172:175], v[96:99]
	v_mfma_f32_16x16x32_bf16 v[84:87], v[196:199], v[180:183], v[84:87]
	v_mfma_f32_16x16x32_bf16 v[80:83], v[204:207], v[180:183], v[80:83]
	v_mfma_f32_16x16x32_bf16 v[68:71], v[196:199], v[188:191], v[68:71]
	v_mfma_f32_16x16x32_bf16 v[64:67], v[204:207], v[188:191], v[64:67]
	v_mfma_f32_16x16x32_bf16 v[116:119], v[200:203], v[168:171], v[116:119]
	v_mfma_f32_16x16x32_bf16 v[112:115], v[208:211], v[168:171], v[112:115]
	v_mfma_f32_16x16x32_bf16 v[100:103], v[200:203], v[176:179], v[100:103]
	v_mfma_f32_16x16x32_bf16 v[96:99], v[208:211], v[176:179], v[96:99]
	v_mfma_f32_16x16x32_bf16 v[84:87], v[200:203], v[184:187], v[84:87]
	v_mfma_f32_16x16x32_bf16 v[80:83], v[208:211], v[184:187], v[80:83]
	v_mfma_f32_16x16x32_bf16 v[68:71], v[200:203], v[192:195], v[68:71]
	v_mfma_f32_16x16x32_bf16 v[64:67], v[208:211], v[192:195], v[64:67]
	s_setprio 0
	s_mov_b32 m0, s39
	v_lshl_add_u64 v[212:213], v[216:217], 0, s[12:13]
	s_barrier
	ds_read_b128 v[164:167], v149 offset:49152
	ds_read_b128 v[168:171], v149 offset:50176
	ds_read_b128 v[172:175], v149 offset:51200
	ds_read_b128 v[176:179], v149 offset:52224
	ds_read_b128 v[180:183], v149 offset:53248
	ds_read_b128 v[184:187], v149 offset:54272
	ds_read_b128 v[188:191], v149 offset:55296
	ds_read_b128 v[192:195], v149 offset:56320
	global_load_lds_dwordx4 v[212:213], off
	v_lshl_add_u64 v[212:213], v[218:219], 0, s[12:13]
	s_mov_b32 m0, s44
	s_nop 0
	global_load_lds_dwordx4 v[212:213], off
	s_barrier
	s_waitcnt lgkmcnt(0)
	s_setprio 1
	s_waitcnt lgkmcnt(0)
	v_mfma_f32_16x16x32_bf16 v[60:63], v[144:147], v[164:167], v[60:63]
	v_mfma_f32_16x16x32_bf16 v[56:59], v[156:159], v[164:167], v[56:59]
	v_mfma_f32_16x16x32_bf16 v[44:47], v[144:147], v[172:175], v[44:47]
	v_mfma_f32_16x16x32_bf16 v[40:43], v[156:159], v[172:175], v[40:43]
	v_mfma_f32_16x16x32_bf16 v[28:31], v[144:147], v[180:183], v[28:31]
	v_mfma_f32_16x16x32_bf16 v[24:27], v[156:159], v[180:183], v[24:27]
	v_mfma_f32_16x16x32_bf16 v[12:15], v[144:147], v[188:191], v[12:15]
	v_mfma_f32_16x16x32_bf16 v[8:11], v[156:159], v[188:191], v[8:11]
	v_mfma_f32_16x16x32_bf16 v[60:63], v[152:155], v[168:171], v[60:63]
	v_mfma_f32_16x16x32_bf16 v[56:59], v[160:163], v[168:171], v[56:59]
	v_mfma_f32_16x16x32_bf16 v[44:47], v[152:155], v[176:179], v[44:47]
	v_mfma_f32_16x16x32_bf16 v[40:43], v[160:163], v[176:179], v[40:43]
	v_mfma_f32_16x16x32_bf16 v[28:31], v[152:155], v[184:187], v[28:31]
	v_mfma_f32_16x16x32_bf16 v[24:27], v[160:163], v[184:187], v[24:27]
	v_mfma_f32_16x16x32_bf16 v[12:15], v[152:155], v[192:195], v[12:15]
	v_mfma_f32_16x16x32_bf16 v[8:11], v[160:163], v[192:195], v[8:11]
	s_setprio 0
	s_barrier
	s_add_u32 s56, s60, 0x200080
	s_addc_u32 s57, s61, 0
	s_add_i32 s60, s62, s5
	v_lshl_add_u64 v[144:145], s[56:57], 0, v[128:129]
	s_mov_b32 m0, s60
	s_nop 0
	global_load_lds_dwordx4 v[144:145], off
	v_lshl_add_u64 v[144:145], s[56:57], 0, v[130:131]
	s_add_i32 m0, s60, 0x2000
	s_nop 0
	global_load_lds_dwordx4 v[144:145], off
	s_waitcnt vmcnt(6)
	s_barrier
	s_setprio 1
	v_mfma_f32_16x16x32_bf16 v[52:55], v[196:199], v[164:167], v[52:55]
	v_mfma_f32_16x16x32_bf16 v[48:51], v[204:207], v[164:167], v[48:51]
	v_mfma_f32_16x16x32_bf16 v[36:39], v[196:199], v[172:175], v[36:39]
	v_mfma_f32_16x16x32_bf16 v[32:35], v[204:207], v[172:175], v[32:35]
	v_mfma_f32_16x16x32_bf16 v[20:23], v[196:199], v[180:183], v[20:23]
	v_mfma_f32_16x16x32_bf16 v[16:19], v[204:207], v[180:183], v[16:19]
	v_mfma_f32_16x16x32_bf16 v[4:7], v[196:199], v[188:191], v[4:7]
	v_mfma_f32_16x16x32_bf16 v[0:3], v[204:207], v[188:191], v[0:3]
	v_mfma_f32_16x16x32_bf16 v[52:55], v[200:203], v[168:171], v[52:55]
	v_mfma_f32_16x16x32_bf16 v[48:51], v[208:211], v[168:171], v[48:51]
	v_mfma_f32_16x16x32_bf16 v[36:39], v[200:203], v[176:179], v[36:39]
	v_mfma_f32_16x16x32_bf16 v[32:35], v[208:211], v[176:179], v[32:35]
	v_mfma_f32_16x16x32_bf16 v[20:23], v[200:203], v[184:187], v[20:23]
	v_mfma_f32_16x16x32_bf16 v[16:19], v[208:211], v[184:187], v[16:19]
	v_mfma_f32_16x16x32_bf16 v[4:7], v[200:203], v[192:195], v[4:7]
	v_mfma_f32_16x16x32_bf16 v[0:3], v[208:211], v[192:195], v[0:3]
	s_setprio 0
	s_add_i32 s67, s67, 2
	s_add_u32 s65, s65, 0x100
	s_addc_u32 s66, s66, 0
	s_cmpk_gt_u32 s67, 0x7d
	s_mov_b64 s[56:57], s[58:59]
	s_barrier
	s_cbranch_scc0 .LBB0_1785
	v_lshl_add_u32 v146, s52, 8, v133
	s_lshl_b32 s15, s54, 8
	s_ashr_i32 s19, s15, 31
	v_ashrrev_i32_e32 v147, 31, v146
	v_mov_b32_e32 v145, s19
	v_or_b32_e32 v144, s15, v132
	v_bfe_u32 v224, v136, 4, 1
	v_mul_u32_u24_e32 v224, 24, v224
	v_mov_b32_e32 v225, 0
	v_mov_b32_e32 v212, v146
	v_mov_b32_e32 v213, v147
	v_lshlrev_b64 v[214:215], 11, v[212:213]
	v_lshl_add_u64 v[214:215], v[214:215], 0, v[144:145]
	v_lshl_add_u64 v[152:153], v[214:215], 2, s[28:29]
	global_load_dwordx4 v[164:167], v[152:153], off
	global_load_dwordx4 v[168:171], v[152:153], off offset:64
	global_load_dwordx4 v[172:175], v[152:153], off offset:512
	global_load_dwordx4 v[176:179], v[152:153], off offset:576
	v_add_u32_e32 v212, 0x10, v146
	v_mov_b32_e32 v213, v147
	v_lshlrev_b64 v[214:215], 11, v[212:213]
	v_lshl_add_u64 v[214:215], v[214:215], 0, v[144:145]
	v_lshl_add_u64 v[152:153], v[214:215], 2, s[28:29]
	global_load_dwordx4 v[180:183], v[152:153], off
	global_load_dwordx4 v[184:187], v[152:153], off offset:64
	global_load_dwordx4 v[188:191], v[152:153], off offset:512
	global_load_dwordx4 v[192:195], v[152:153], off offset:576
	v_add_u32_e32 v212, 0x20, v146
	v_mov_b32_e32 v213, v147
	v_lshlrev_b64 v[214:215], 11, v[212:213]
	v_lshl_add_u64 v[214:215], v[214:215], 0, v[144:145]
	v_lshl_add_u64 v[152:153], v[214:215], 2, s[28:29]
	global_load_dwordx4 v[196:199], v[152:153], off
	global_load_dwordx4 v[200:203], v[152:153], off offset:64
	global_load_dwordx4 v[204:207], v[152:153], off offset:512
	global_load_dwordx4 v[208:211], v[152:153], off offset:576
	s_waitcnt vmcnt(8)
	v_mov_b32_e32 v212, v146
	v_mov_b32_e32 v213, v147
	v_lshlrev_b64 v[214:215], 11, v[212:213]
	v_lshl_add_u64 v[214:215], v[214:215], 0, v[144:145]
	v_lshl_add_u64 v[154:155], v[214:215], 2, s[28:29]
	v_lshl_add_u64 v[156:157], v[214:215], 1, s[40:41]
	v_lshl_add_u64 v[156:157], v[156:157], 0, v[224:225]
	v_pk_add_f32 v[126:127], v[126:127], v[166:167]
	v_pk_add_f32 v[124:125], v[124:125], v[164:165]
	v_cvt_pk_bf16_f32 v221, v126, v127
	v_cvt_pk_bf16_f32 v220, v124, v125
	global_store_dwordx4 v[154:155], v[124:127], off
	s_nop 1
	v_mul_f32_e32 v125, v125, v125
	v_mul_f32_e32 v127, v127, v127
	v_fmac_f32_e32 v125, v124, v124
	v_fmac_f32_e32 v127, v126, v126
	v_add_f32_e32 v160, v125, v127
	v_pk_add_f32 v[122:123], v[122:123], v[170:171]
	v_pk_add_f32 v[120:121], v[120:121], v[168:169]
	v_cvt_pk_bf16_f32 v223, v122, v123
	v_cvt_pk_bf16_f32 v222, v120, v121
	global_store_dwordx4 v[154:155], v[120:123], off offset:64
	s_nop 1
	v_mul_f32_e32 v121, v121, v121
	v_mul_f32_e32 v123, v123, v123
	v_fmac_f32_e32 v121, v120, v120
	v_fmac_f32_e32 v123, v122, v122
	v_add_f32_e32 v120, v121, v123
	v_add_f32_e32 v160, v160, v120
	v_permlane16_swap_b32_e32 v220, v222
	v_permlane16_swap_b32_e32 v221, v223
	global_store_dwordx4 v[156:157], v[220:223], off
	s_nop 0
	v_pk_add_f32 v[118:119], v[118:119], v[174:175]
	v_pk_add_f32 v[116:117], v[116:117], v[172:173]
	v_cvt_pk_bf16_f32 v221, v118, v119
	v_cvt_pk_bf16_f32 v220, v116, v117
	global_store_dwordx4 v[154:155], v[116:119], off offset:512
	s_nop 1
	v_mul_f32_e32 v117, v117, v117
	v_mul_f32_e32 v119, v119, v119
	v_fmac_f32_e32 v117, v116, v116
	v_fmac_f32_e32 v119, v118, v118
	v_add_f32_e32 v116, v117, v119
	v_add_f32_e32 v160, v160, v116
	v_pk_add_f32 v[114:115], v[114:115], v[178:179]
	v_pk_add_f32 v[112:113], v[112:113], v[176:177]
	v_cvt_pk_bf16_f32 v223, v114, v115
	v_cvt_pk_bf16_f32 v222, v112, v113
	global_store_dwordx4 v[154:155], v[112:115], off offset:576
	s_nop 1
	v_mul_f32_e32 v113, v113, v113
	v_mul_f32_e32 v115, v115, v115
	v_fmac_f32_e32 v113, v112, v112
	v_fmac_f32_e32 v115, v114, v114
	v_add_f32_e32 v112, v113, v115
	v_add_f32_e32 v160, v160, v112
	v_permlane16_swap_b32_e32 v220, v222
	v_permlane16_swap_b32_e32 v221, v223
	global_store_dwordx4 v[156:157], v[220:223], off offset:256
	s_nop 0
	v_mov_b32_e32 v161, v160
	s_nop 1
	v_permlane16_swap_b32_e32 v160, v161
	v_add_f32_e32 v160, v160, v161
	v_mov_b32_e32 v161, v160
	s_nop 1
	v_permlane32_swap_b32_e32 v160, v161
	s_and_saveexec_b64 s[52:53], s[8:9]
	v_lshl_add_u64 v[162:163], v[212:213], 2, s[16:17]
	v_add_f32_e32 v160, v160, v161
	global_atomic_add_f32 v[162:163], v160, off
	s_or_b64 exec, exec, s[52:53]
	v_add_u32_e32 v212, 0x30, v146
	v_mov_b32_e32 v213, v147
	v_lshlrev_b64 v[214:215], 11, v[212:213]
	v_lshl_add_u64 v[214:215], v[214:215], 0, v[144:145]
	v_lshl_add_u64 v[152:153], v[214:215], 2, s[28:29]
	global_load_dwordx4 v[164:167], v[152:153], off
	global_load_dwordx4 v[168:171], v[152:153], off offset:64
	global_load_dwordx4 v[172:175], v[152:153], off offset:512
	global_load_dwordx4 v[176:179], v[152:153], off offset:576
	s_waitcnt vmcnt(15)
	v_add_u32_e32 v212, 0x10, v146
	v_mov_b32_e32 v213, v147
	v_lshlrev_b64 v[214:215], 11, v[212:213]
	v_lshl_add_u64 v[214:215], v[214:215], 0, v[144:145]
	v_lshl_add_u64 v[154:155], v[214:215], 2, s[28:29]
	v_lshl_add_u64 v[156:157], v[214:215], 1, s[40:41]
	v_lshl_add_u64 v[156:157], v[156:157], 0, v[224:225]
	v_pk_add_f32 v[110:111], v[110:111], v[182:183]
	v_pk_add_f32 v[108:109], v[108:109], v[180:181]
	v_cvt_pk_bf16_f32 v221, v110, v111
	v_cvt_pk_bf16_f32 v220, v108, v109
	global_store_dwordx4 v[154:155], v[108:111], off
	s_nop 1
	v_mul_f32_e32 v109, v109, v109
	v_mul_f32_e32 v111, v111, v111
	v_fmac_f32_e32 v109, v108, v108
	v_fmac_f32_e32 v111, v110, v110
	v_add_f32_e32 v160, v109, v111
	v_pk_add_f32 v[106:107], v[106:107], v[186:187]
	v_pk_add_f32 v[104:105], v[104:105], v[184:185]
	v_cvt_pk_bf16_f32 v223, v106, v107
	v_cvt_pk_bf16_f32 v222, v104, v105
	global_store_dwordx4 v[154:155], v[104:107], off offset:64
	s_nop 1
	v_mul_f32_e32 v105, v105, v105
	v_mul_f32_e32 v107, v107, v107
	v_fmac_f32_e32 v105, v104, v104
	v_fmac_f32_e32 v107, v106, v106
	v_add_f32_e32 v104, v105, v107
	v_add_f32_e32 v160, v160, v104
	v_permlane16_swap_b32_e32 v220, v222
	v_permlane16_swap_b32_e32 v221, v223
	global_store_dwordx4 v[156:157], v[220:223], off
	s_nop 0
	v_pk_add_f32 v[102:103], v[102:103], v[190:191]
	v_pk_add_f32 v[100:101], v[100:101], v[188:189]
	v_cvt_pk_bf16_f32 v221, v102, v103
	v_cvt_pk_bf16_f32 v220, v100, v101
	global_store_dwordx4 v[154:155], v[100:103], off offset:512
	s_nop 1
	v_mul_f32_e32 v101, v101, v101
	v_mul_f32_e32 v103, v103, v103
	v_fmac_f32_e32 v101, v100, v100
	v_fmac_f32_e32 v103, v102, v102
	v_add_f32_e32 v100, v101, v103
	v_add_f32_e32 v160, v160, v100
	v_pk_add_f32 v[98:99], v[98:99], v[194:195]
	v_pk_add_f32 v[96:97], v[96:97], v[192:193]
	v_cvt_pk_bf16_f32 v223, v98, v99
	v_cvt_pk_bf16_f32 v222, v96, v97
	global_store_dwordx4 v[154:155], v[96:99], off offset:576
	s_nop 1
	v_mul_f32_e32 v97, v97, v97
	v_mul_f32_e32 v99, v99, v99
	v_fmac_f32_e32 v97, v96, v96
	v_fmac_f32_e32 v99, v98, v98
	v_add_f32_e32 v96, v97, v99
	v_add_f32_e32 v160, v160, v96
	v_permlane16_swap_b32_e32 v220, v222
	v_permlane16_swap_b32_e32 v221, v223
	global_store_dwordx4 v[156:157], v[220:223], off offset:256
	s_nop 0
	v_mov_b32_e32 v161, v160
	s_nop 1
	v_permlane16_swap_b32_e32 v160, v161
	v_add_f32_e32 v160, v160, v161
	v_mov_b32_e32 v161, v160
	s_nop 1
	v_permlane32_swap_b32_e32 v160, v161
	s_and_saveexec_b64 s[52:53], s[8:9]
	v_lshl_add_u64 v[162:163], v[212:213], 2, s[16:17]
	v_add_f32_e32 v160, v160, v161
	global_atomic_add_f32 v[162:163], v160, off
	s_or_b64 exec, exec, s[52:53]
	v_add_u32_e32 v212, 0x80, v146
	v_mov_b32_e32 v213, v147
	v_lshlrev_b64 v[214:215], 11, v[212:213]
	v_lshl_add_u64 v[214:215], v[214:215], 0, v[144:145]
	v_lshl_add_u64 v[152:153], v[214:215], 2, s[28:29]
	global_load_dwordx4 v[180:183], v[152:153], off
	global_load_dwordx4 v[184:187], v[152:153], off offset:64
	global_load_dwordx4 v[188:191], v[152:153], off offset:512
	global_load_dwordx4 v[192:195], v[152:153], off offset:576
	s_waitcnt vmcnt(22)
	v_add_u32_e32 v212, 0x20, v146
	v_mov_b32_e32 v213, v147
	v_lshlrev_b64 v[214:215], 11, v[212:213]
	v_lshl_add_u64 v[214:215], v[214:215], 0, v[144:145]
	v_lshl_add_u64 v[154:155], v[214:215], 2, s[28:29]
	v_lshl_add_u64 v[156:157], v[214:215], 1, s[40:41]
	v_lshl_add_u64 v[156:157], v[156:157], 0, v[224:225]
	v_pk_add_f32 v[94:95], v[94:95], v[198:199]
	v_pk_add_f32 v[92:93], v[92:93], v[196:197]
	v_cvt_pk_bf16_f32 v221, v94, v95
	v_cvt_pk_bf16_f32 v220, v92, v93
	global_store_dwordx4 v[154:155], v[92:95], off
	s_nop 1
	v_mul_f32_e32 v93, v93, v93
	v_mul_f32_e32 v95, v95, v95
	v_fmac_f32_e32 v93, v92, v92
	v_fmac_f32_e32 v95, v94, v94
	v_add_f32_e32 v160, v93, v95
	v_pk_add_f32 v[90:91], v[90:91], v[202:203]
	v_pk_add_f32 v[88:89], v[88:89], v[200:201]
	v_cvt_pk_bf16_f32 v223, v90, v91
	v_cvt_pk_bf16_f32 v222, v88, v89
	global_store_dwordx4 v[154:155], v[88:91], off offset:64
	s_nop 1
	v_mul_f32_e32 v89, v89, v89
	v_mul_f32_e32 v91, v91, v91
	v_fmac_f32_e32 v89, v88, v88
	v_fmac_f32_e32 v91, v90, v90
	v_add_f32_e32 v88, v89, v91
	v_add_f32_e32 v160, v160, v88
	v_permlane16_swap_b32_e32 v220, v222
	v_permlane16_swap_b32_e32 v221, v223
	global_store_dwordx4 v[156:157], v[220:223], off
	s_nop 0
	v_pk_add_f32 v[86:87], v[86:87], v[206:207]
	v_pk_add_f32 v[84:85], v[84:85], v[204:205]
	v_cvt_pk_bf16_f32 v221, v86, v87
	v_cvt_pk_bf16_f32 v220, v84, v85
	global_store_dwordx4 v[154:155], v[84:87], off offset:512
	s_nop 1
	v_mul_f32_e32 v85, v85, v85
	v_mul_f32_e32 v87, v87, v87
	v_fmac_f32_e32 v85, v84, v84
	v_fmac_f32_e32 v87, v86, v86
	v_add_f32_e32 v84, v85, v87
	v_add_f32_e32 v160, v160, v84
	v_pk_add_f32 v[82:83], v[82:83], v[210:211]
	v_pk_add_f32 v[80:81], v[80:81], v[208:209]
	v_cvt_pk_bf16_f32 v223, v82, v83
	v_cvt_pk_bf16_f32 v222, v80, v81
	global_store_dwordx4 v[154:155], v[80:83], off offset:576
	s_nop 1
	v_mul_f32_e32 v81, v81, v81
	v_mul_f32_e32 v83, v83, v83
	v_fmac_f32_e32 v81, v80, v80
	v_fmac_f32_e32 v83, v82, v82
	v_add_f32_e32 v80, v81, v83
	v_add_f32_e32 v160, v160, v80
	v_permlane16_swap_b32_e32 v220, v222
	v_permlane16_swap_b32_e32 v221, v223
	global_store_dwordx4 v[156:157], v[220:223], off offset:256
	s_nop 0
	v_mov_b32_e32 v161, v160
	s_nop 1
	v_permlane16_swap_b32_e32 v160, v161
	v_add_f32_e32 v160, v160, v161
	v_mov_b32_e32 v161, v160
	s_nop 1
	v_permlane32_swap_b32_e32 v160, v161
	s_and_saveexec_b64 s[52:53], s[8:9]
	v_lshl_add_u64 v[162:163], v[212:213], 2, s[16:17]
	v_add_f32_e32 v160, v160, v161
	global_atomic_add_f32 v[162:163], v160, off
	s_or_b64 exec, exec, s[52:53]
	v_add_u32_e32 v212, 0x90, v146
	v_mov_b32_e32 v213, v147
	v_lshlrev_b64 v[214:215], 11, v[212:213]
	v_lshl_add_u64 v[214:215], v[214:215], 0, v[144:145]
	v_lshl_add_u64 v[152:153], v[214:215], 2, s[28:29]
	global_load_dwordx4 v[196:199], v[152:153], off
	global_load_dwordx4 v[200:203], v[152:153], off offset:64
	global_load_dwordx4 v[204:207], v[152:153], off offset:512
	global_load_dwordx4 v[208:211], v[152:153], off offset:576
	s_waitcnt vmcnt(22)
	v_add_u32_e32 v212, 0x30, v146
	v_mov_b32_e32 v213, v147
	v_lshlrev_b64 v[214:215], 11, v[212:213]
	v_lshl_add_u64 v[214:215], v[214:215], 0, v[144:145]
	v_lshl_add_u64 v[154:155], v[214:215], 2, s[28:29]
	v_lshl_add_u64 v[156:157], v[214:215], 1, s[40:41]
	v_lshl_add_u64 v[156:157], v[156:157], 0, v[224:225]
	v_pk_add_f32 v[78:79], v[78:79], v[166:167]
	v_pk_add_f32 v[76:77], v[76:77], v[164:165]
	v_cvt_pk_bf16_f32 v221, v78, v79
	v_cvt_pk_bf16_f32 v220, v76, v77
	global_store_dwordx4 v[154:155], v[76:79], off
	s_nop 1
	v_mul_f32_e32 v77, v77, v77
	v_mul_f32_e32 v79, v79, v79
	v_fmac_f32_e32 v77, v76, v76
	v_fmac_f32_e32 v79, v78, v78
	v_add_f32_e32 v160, v77, v79
	v_pk_add_f32 v[74:75], v[74:75], v[170:171]
	v_pk_add_f32 v[72:73], v[72:73], v[168:169]
	v_cvt_pk_bf16_f32 v223, v74, v75
	v_cvt_pk_bf16_f32 v222, v72, v73
	global_store_dwordx4 v[154:155], v[72:75], off offset:64
	s_nop 1
	v_mul_f32_e32 v73, v73, v73
	v_mul_f32_e32 v75, v75, v75
	v_fmac_f32_e32 v73, v72, v72
	v_fmac_f32_e32 v75, v74, v74
	v_add_f32_e32 v72, v73, v75
	v_add_f32_e32 v160, v160, v72
	v_permlane16_swap_b32_e32 v220, v222
	v_permlane16_swap_b32_e32 v221, v223
	global_store_dwordx4 v[156:157], v[220:223], off
	s_nop 0
	v_pk_add_f32 v[70:71], v[70:71], v[174:175]
	v_pk_add_f32 v[68:69], v[68:69], v[172:173]
	v_cvt_pk_bf16_f32 v221, v70, v71
	v_cvt_pk_bf16_f32 v220, v68, v69
	global_store_dwordx4 v[154:155], v[68:71], off offset:512
	s_nop 1
	v_mul_f32_e32 v69, v69, v69
	v_mul_f32_e32 v71, v71, v71
	v_fmac_f32_e32 v69, v68, v68
	v_fmac_f32_e32 v71, v70, v70
	v_add_f32_e32 v68, v69, v71
	v_add_f32_e32 v160, v160, v68
	v_pk_add_f32 v[66:67], v[66:67], v[178:179]
	v_pk_add_f32 v[64:65], v[64:65], v[176:177]
	v_cvt_pk_bf16_f32 v223, v66, v67
	v_cvt_pk_bf16_f32 v222, v64, v65
	global_store_dwordx4 v[154:155], v[64:67], off offset:576
	s_nop 1
	v_mul_f32_e32 v65, v65, v65
	v_mul_f32_e32 v67, v67, v67
	v_fmac_f32_e32 v65, v64, v64
	v_fmac_f32_e32 v67, v66, v66
	v_add_f32_e32 v64, v65, v67
	v_add_f32_e32 v160, v160, v64
	v_permlane16_swap_b32_e32 v220, v222
	v_permlane16_swap_b32_e32 v221, v223
	global_store_dwordx4 v[156:157], v[220:223], off offset:256
	s_nop 0
	v_mov_b32_e32 v161, v160
	s_nop 1
	v_permlane16_swap_b32_e32 v160, v161
	v_add_f32_e32 v160, v160, v161
	v_mov_b32_e32 v161, v160
	s_nop 1
	v_permlane32_swap_b32_e32 v160, v161
	s_and_saveexec_b64 s[52:53], s[8:9]
	v_lshl_add_u64 v[162:163], v[212:213], 2, s[16:17]
	v_add_f32_e32 v160, v160, v161
	global_atomic_add_f32 v[162:163], v160, off
	s_or_b64 exec, exec, s[52:53]
	v_add_u32_e32 v212, 0xa0, v146
	v_mov_b32_e32 v213, v147
	v_lshlrev_b64 v[214:215], 11, v[212:213]
	v_lshl_add_u64 v[214:215], v[214:215], 0, v[144:145]
	v_lshl_add_u64 v[152:153], v[214:215], 2, s[28:29]
	global_load_dwordx4 v[164:167], v[152:153], off
	global_load_dwordx4 v[168:171], v[152:153], off offset:64
	global_load_dwordx4 v[172:175], v[152:153], off offset:512
	global_load_dwordx4 v[176:179], v[152:153], off offset:576
	s_waitcnt vmcnt(22)
	v_add_u32_e32 v212, 0x80, v146
	v_mov_b32_e32 v213, v147
	v_lshlrev_b64 v[214:215], 11, v[212:213]
	v_lshl_add_u64 v[214:215], v[214:215], 0, v[144:145]
	v_lshl_add_u64 v[154:155], v[214:215], 2, s[28:29]
	v_lshl_add_u64 v[156:157], v[214:215], 1, s[40:41]
	v_lshl_add_u64 v[156:157], v[156:157], 0, v[224:225]
	v_pk_add_f32 v[62:63], v[62:63], v[182:183]
	v_pk_add_f32 v[60:61], v[60:61], v[180:181]
	v_cvt_pk_bf16_f32 v221, v62, v63
	v_cvt_pk_bf16_f32 v220, v60, v61
	global_store_dwordx4 v[154:155], v[60:63], off
	s_nop 1
	v_mul_f32_e32 v61, v61, v61
	v_mul_f32_e32 v63, v63, v63
	v_fmac_f32_e32 v61, v60, v60
	v_fmac_f32_e32 v63, v62, v62
	v_add_f32_e32 v160, v61, v63
	v_pk_add_f32 v[58:59], v[58:59], v[186:187]
	v_pk_add_f32 v[56:57], v[56:57], v[184:185]
	v_cvt_pk_bf16_f32 v223, v58, v59
	v_cvt_pk_bf16_f32 v222, v56, v57
	global_store_dwordx4 v[154:155], v[56:59], off offset:64
	s_nop 1
	v_mul_f32_e32 v57, v57, v57
	v_mul_f32_e32 v59, v59, v59
	v_fmac_f32_e32 v57, v56, v56
	v_fmac_f32_e32 v59, v58, v58
	v_add_f32_e32 v56, v57, v59
	v_add_f32_e32 v160, v160, v56
	v_permlane16_swap_b32_e32 v220, v222
	v_permlane16_swap_b32_e32 v221, v223
	global_store_dwordx4 v[156:157], v[220:223], off
	s_nop 0
	v_pk_add_f32 v[54:55], v[54:55], v[190:191]
	v_pk_add_f32 v[52:53], v[52:53], v[188:189]
	v_cvt_pk_bf16_f32 v221, v54, v55
	v_cvt_pk_bf16_f32 v220, v52, v53
	global_store_dwordx4 v[154:155], v[52:55], off offset:512
	s_nop 1
	v_mul_f32_e32 v53, v53, v53
	v_mul_f32_e32 v55, v55, v55
	v_fmac_f32_e32 v53, v52, v52
	v_fmac_f32_e32 v55, v54, v54
	v_add_f32_e32 v52, v53, v55
	v_add_f32_e32 v160, v160, v52
	v_pk_add_f32 v[50:51], v[50:51], v[194:195]
	v_pk_add_f32 v[48:49], v[48:49], v[192:193]
	v_cvt_pk_bf16_f32 v223, v50, v51
	v_cvt_pk_bf16_f32 v222, v48, v49
	global_store_dwordx4 v[154:155], v[48:51], off offset:576
	s_nop 1
	v_mul_f32_e32 v49, v49, v49
	v_mul_f32_e32 v51, v51, v51
	v_fmac_f32_e32 v49, v48, v48
	v_fmac_f32_e32 v51, v50, v50
	v_add_f32_e32 v48, v49, v51
	v_add_f32_e32 v160, v160, v48
	v_permlane16_swap_b32_e32 v220, v222
	v_permlane16_swap_b32_e32 v221, v223
	global_store_dwordx4 v[156:157], v[220:223], off offset:256
	s_nop 0
	v_mov_b32_e32 v161, v160
	s_nop 1
	v_permlane16_swap_b32_e32 v160, v161
	v_add_f32_e32 v160, v160, v161
	v_mov_b32_e32 v161, v160
	s_nop 1
	v_permlane32_swap_b32_e32 v160, v161
	s_and_saveexec_b64 s[52:53], s[8:9]
	v_lshl_add_u64 v[162:163], v[212:213], 2, s[16:17]
	v_add_f32_e32 v160, v160, v161
	global_atomic_add_f32 v[162:163], v160, off
	s_or_b64 exec, exec, s[52:53]
	v_add_u32_e32 v212, 0xb0, v146
	v_mov_b32_e32 v213, v147
	v_lshlrev_b64 v[214:215], 11, v[212:213]
	v_lshl_add_u64 v[214:215], v[214:215], 0, v[144:145]
	v_lshl_add_u64 v[152:153], v[214:215], 2, s[28:29]
	global_load_dwordx4 v[180:183], v[152:153], off
	global_load_dwordx4 v[184:187], v[152:153], off offset:64
	global_load_dwordx4 v[188:191], v[152:153], off offset:512
	global_load_dwordx4 v[192:195], v[152:153], off offset:576
	s_waitcnt vmcnt(22)
	v_add_u32_e32 v212, 0x90, v146
	v_mov_b32_e32 v213, v147
	v_lshlrev_b64 v[214:215], 11, v[212:213]
	v_lshl_add_u64 v[214:215], v[214:215], 0, v[144:145]
	v_lshl_add_u64 v[154:155], v[214:215], 2, s[28:29]
	v_lshl_add_u64 v[156:157], v[214:215], 1, s[40:41]
	v_lshl_add_u64 v[156:157], v[156:157], 0, v[224:225]
	v_pk_add_f32 v[46:47], v[46:47], v[198:199]
	v_pk_add_f32 v[44:45], v[44:45], v[196:197]
	v_cvt_pk_bf16_f32 v221, v46, v47
	v_cvt_pk_bf16_f32 v220, v44, v45
	global_store_dwordx4 v[154:155], v[44:47], off
	s_nop 1
	v_mul_f32_e32 v45, v45, v45
	v_mul_f32_e32 v47, v47, v47
	v_fmac_f32_e32 v45, v44, v44
	v_fmac_f32_e32 v47, v46, v46
	v_add_f32_e32 v160, v45, v47
	v_pk_add_f32 v[42:43], v[42:43], v[202:203]
	v_pk_add_f32 v[40:41], v[40:41], v[200:201]
	v_cvt_pk_bf16_f32 v223, v42, v43
	v_cvt_pk_bf16_f32 v222, v40, v41
	global_store_dwordx4 v[154:155], v[40:43], off offset:64
	s_nop 1
	v_mul_f32_e32 v41, v41, v41
	v_mul_f32_e32 v43, v43, v43
	v_fmac_f32_e32 v41, v40, v40
	v_fmac_f32_e32 v43, v42, v42
	v_add_f32_e32 v40, v41, v43
	v_add_f32_e32 v160, v160, v40
	v_permlane16_swap_b32_e32 v220, v222
	v_permlane16_swap_b32_e32 v221, v223
	global_store_dwordx4 v[156:157], v[220:223], off
	s_nop 0
	v_pk_add_f32 v[38:39], v[38:39], v[206:207]
	v_pk_add_f32 v[36:37], v[36:37], v[204:205]
	v_cvt_pk_bf16_f32 v221, v38, v39
	v_cvt_pk_bf16_f32 v220, v36, v37
	global_store_dwordx4 v[154:155], v[36:39], off offset:512
	s_nop 1
	v_mul_f32_e32 v37, v37, v37
	v_mul_f32_e32 v39, v39, v39
	v_fmac_f32_e32 v37, v36, v36
	v_fmac_f32_e32 v39, v38, v38
	v_add_f32_e32 v36, v37, v39
	v_add_f32_e32 v160, v160, v36
	v_pk_add_f32 v[34:35], v[34:35], v[210:211]
	v_pk_add_f32 v[32:33], v[32:33], v[208:209]
	v_cvt_pk_bf16_f32 v223, v34, v35
	v_cvt_pk_bf16_f32 v222, v32, v33
	global_store_dwordx4 v[154:155], v[32:35], off offset:576
	s_nop 1
	v_mul_f32_e32 v33, v33, v33
	v_mul_f32_e32 v35, v35, v35
	v_fmac_f32_e32 v33, v32, v32
	v_fmac_f32_e32 v35, v34, v34
	v_add_f32_e32 v32, v33, v35
	v_add_f32_e32 v160, v160, v32
	v_permlane16_swap_b32_e32 v220, v222
	v_permlane16_swap_b32_e32 v221, v223
	global_store_dwordx4 v[156:157], v[220:223], off offset:256
	s_nop 0
	v_mov_b32_e32 v161, v160
	s_nop 1
	v_permlane16_swap_b32_e32 v160, v161
	v_add_f32_e32 v160, v160, v161
	v_mov_b32_e32 v161, v160
	s_nop 1
	v_permlane32_swap_b32_e32 v160, v161
	s_and_saveexec_b64 s[52:53], s[8:9]
	v_lshl_add_u64 v[162:163], v[212:213], 2, s[16:17]
	v_add_f32_e32 v160, v160, v161
	global_atomic_add_f32 v[162:163], v160, off
	s_or_b64 exec, exec, s[52:53]
	s_waitcnt vmcnt(18)
	v_add_u32_e32 v212, 0xa0, v146
	v_mov_b32_e32 v213, v147
	v_lshlrev_b64 v[214:215], 11, v[212:213]
	v_lshl_add_u64 v[214:215], v[214:215], 0, v[144:145]
	v_lshl_add_u64 v[154:155], v[214:215], 2, s[28:29]
	v_lshl_add_u64 v[156:157], v[214:215], 1, s[40:41]
	v_lshl_add_u64 v[156:157], v[156:157], 0, v[224:225]
	v_pk_add_f32 v[30:31], v[30:31], v[166:167]
	v_pk_add_f32 v[28:29], v[28:29], v[164:165]
	v_cvt_pk_bf16_f32 v221, v30, v31
	v_cvt_pk_bf16_f32 v220, v28, v29
	global_store_dwordx4 v[154:155], v[28:31], off
	s_nop 1
	v_mul_f32_e32 v29, v29, v29
	v_mul_f32_e32 v31, v31, v31
	v_fmac_f32_e32 v29, v28, v28
	v_fmac_f32_e32 v31, v30, v30
	v_add_f32_e32 v160, v29, v31
	v_pk_add_f32 v[26:27], v[26:27], v[170:171]
	v_pk_add_f32 v[24:25], v[24:25], v[168:169]
	v_cvt_pk_bf16_f32 v223, v26, v27
	v_cvt_pk_bf16_f32 v222, v24, v25
	global_store_dwordx4 v[154:155], v[24:27], off offset:64
	s_nop 1
	v_mul_f32_e32 v25, v25, v25
	v_mul_f32_e32 v27, v27, v27
	v_fmac_f32_e32 v25, v24, v24
	v_fmac_f32_e32 v27, v26, v26
	v_add_f32_e32 v24, v25, v27
	v_add_f32_e32 v160, v160, v24
	v_permlane16_swap_b32_e32 v220, v222
	v_permlane16_swap_b32_e32 v221, v223
	global_store_dwordx4 v[156:157], v[220:223], off
	s_nop 0
	v_pk_add_f32 v[22:23], v[22:23], v[174:175]
	v_pk_add_f32 v[20:21], v[20:21], v[172:173]
	v_cvt_pk_bf16_f32 v221, v22, v23
	v_cvt_pk_bf16_f32 v220, v20, v21
	global_store_dwordx4 v[154:155], v[20:23], off offset:512
	s_nop 1
	v_mul_f32_e32 v21, v21, v21
	v_mul_f32_e32 v23, v23, v23
	v_fmac_f32_e32 v21, v20, v20
	v_fmac_f32_e32 v23, v22, v22
	v_add_f32_e32 v20, v21, v23
	v_add_f32_e32 v160, v160, v20
	v_pk_add_f32 v[18:19], v[18:19], v[178:179]
	v_pk_add_f32 v[16:17], v[16:17], v[176:177]
	v_cvt_pk_bf16_f32 v223, v18, v19
	v_cvt_pk_bf16_f32 v222, v16, v17
	global_store_dwordx4 v[154:155], v[16:19], off offset:576
	s_nop 1
	v_mul_f32_e32 v17, v17, v17
	v_mul_f32_e32 v19, v19, v19
	v_fmac_f32_e32 v17, v16, v16
	v_fmac_f32_e32 v19, v18, v18
	v_add_f32_e32 v16, v17, v19
	v_add_f32_e32 v160, v160, v16
	v_permlane16_swap_b32_e32 v220, v222
	v_permlane16_swap_b32_e32 v221, v223
	global_store_dwordx4 v[156:157], v[220:223], off offset:256
	s_nop 0
	v_mov_b32_e32 v161, v160
	s_nop 1
	v_permlane16_swap_b32_e32 v160, v161
	v_add_f32_e32 v160, v160, v161
	v_mov_b32_e32 v161, v160
	s_nop 1
	v_permlane32_swap_b32_e32 v160, v161
	s_and_saveexec_b64 s[52:53], s[8:9]
	v_lshl_add_u64 v[162:163], v[212:213], 2, s[16:17]
	v_add_f32_e32 v160, v160, v161
	global_atomic_add_f32 v[162:163], v160, off
	s_or_b64 exec, exec, s[52:53]
	s_waitcnt vmcnt(14)
	v_add_u32_e32 v212, 0xb0, v146
	v_mov_b32_e32 v213, v147
	v_lshlrev_b64 v[214:215], 11, v[212:213]
	v_lshl_add_u64 v[214:215], v[214:215], 0, v[144:145]
	v_lshl_add_u64 v[154:155], v[214:215], 2, s[28:29]
	v_lshl_add_u64 v[156:157], v[214:215], 1, s[40:41]
	v_lshl_add_u64 v[156:157], v[156:157], 0, v[224:225]
	v_pk_add_f32 v[14:15], v[14:15], v[182:183]
	v_pk_add_f32 v[12:13], v[12:13], v[180:181]
	v_cvt_pk_bf16_f32 v221, v14, v15
	v_cvt_pk_bf16_f32 v220, v12, v13
	global_store_dwordx4 v[154:155], v[12:15], off
	s_nop 1
	v_mul_f32_e32 v13, v13, v13
	v_mul_f32_e32 v15, v15, v15
	v_fmac_f32_e32 v13, v12, v12
	v_fmac_f32_e32 v15, v14, v14
	v_add_f32_e32 v160, v13, v15
	v_pk_add_f32 v[10:11], v[10:11], v[186:187]
	v_pk_add_f32 v[8:9], v[8:9], v[184:185]
	v_cvt_pk_bf16_f32 v223, v10, v11
	v_cvt_pk_bf16_f32 v222, v8, v9
	global_store_dwordx4 v[154:155], v[8:11], off offset:64
	s_nop 1
	v_mul_f32_e32 v9, v9, v9
	v_mul_f32_e32 v11, v11, v11
	v_fmac_f32_e32 v9, v8, v8
	v_fmac_f32_e32 v11, v10, v10
	v_add_f32_e32 v8, v9, v11
	v_add_f32_e32 v160, v160, v8
	v_permlane16_swap_b32_e32 v220, v222
	v_permlane16_swap_b32_e32 v221, v223
	global_store_dwordx4 v[156:157], v[220:223], off
	s_nop 0
	v_pk_add_f32 v[6:7], v[6:7], v[190:191]
	v_pk_add_f32 v[4:5], v[4:5], v[188:189]
	v_cvt_pk_bf16_f32 v221, v6, v7
	v_cvt_pk_bf16_f32 v220, v4, v5
	global_store_dwordx4 v[154:155], v[4:7], off offset:512
	s_nop 1
	v_mul_f32_e32 v5, v5, v5
	v_mul_f32_e32 v7, v7, v7
	v_fmac_f32_e32 v5, v4, v4
	v_fmac_f32_e32 v7, v6, v6
	v_add_f32_e32 v4, v5, v7
	v_add_f32_e32 v160, v160, v4
	v_pk_add_f32 v[2:3], v[2:3], v[194:195]
	v_pk_add_f32 v[0:1], v[0:1], v[192:193]
	v_cvt_pk_bf16_f32 v223, v2, v3
	v_cvt_pk_bf16_f32 v222, v0, v1
	global_store_dwordx4 v[154:155], v[0:3], off offset:576
	s_nop 1
	v_mul_f32_e32 v1, v1, v1
	v_mul_f32_e32 v3, v3, v3
	v_fmac_f32_e32 v1, v0, v0
	v_fmac_f32_e32 v3, v2, v2
	v_add_f32_e32 v0, v1, v3
	v_add_f32_e32 v160, v160, v0
	v_permlane16_swap_b32_e32 v220, v222
	v_permlane16_swap_b32_e32 v221, v223
	global_store_dwordx4 v[156:157], v[220:223], off offset:256
	s_nop 0
	v_mov_b32_e32 v161, v160
	s_nop 1
	v_permlane16_swap_b32_e32 v160, v161
	v_add_f32_e32 v160, v160, v161
	v_mov_b32_e32 v161, v160
	s_nop 1
	v_permlane32_swap_b32_e32 v160, v161
	s_and_saveexec_b64 s[52:53], s[8:9]
	v_lshl_add_u64 v[162:163], v[212:213], 2, s[16:17]
	v_add_f32_e32 v160, v160, v161
	global_atomic_add_f32 v[162:163], v160, off
	s_or_b64 exec, exec, s[52:53]
	s_branch .LBB0_1777
